# GEMM k-loop: all 6 LDS-DMA issues right after the barrier (SALU m0), raised priority during DMA+ds_read issue and normal priority during MFMA block
# speedup vs baseline: 1.0738x; 1.0127x over previous
.LBB0_123:
	s_add_i32 s45, s44, 2
	s_mul_hi_i32 s50, s45, 0x55555556
	s_lshr_b32 s51, s50, 31
	s_add_i32 s50, s50, s51
	s_mul_i32 s50, s50, 3
	s_sub_i32 s45, s45, s50
	s_mulk_i32 s45, 0x6000
	s_mul_i32 s54, s44, 0x6000
	v_readfirstlane_b32 s55, v140
	v_lshl_add_u64 v[232:233], v[132:133], 0, s[2:3]
	v_lshl_add_u64 v[234:235], v[130:131], 0, s[2:3]
	s_add_u32 s55, s55, s45
	s_waitcnt vmcnt(6) lgkmcnt(0)
	s_barrier
	s_setprio 1
	s_mov_b32 m0, s55
	v_lshl_add_u64 v[236:237], v[232:233], 0, s[20:21]
	global_load_lds_dwordx4 v[236:237], off
	s_add_u32 m0, s55, 0x1000
	v_lshl_add_u64 v[236:237], v[232:233], 0, s[22:23]
	global_load_lds_dwordx4 v[236:237], off
	s_add_u32 m0, s55, 0x2000
	v_lshl_add_u64 v[236:237], v[232:233], 0, s[24:25]
	global_load_lds_dwordx4 v[236:237], off
	s_add_u32 m0, s55, 0x3000
	v_lshl_add_u64 v[236:237], v[232:233], 0, s[26:27]
	global_load_lds_dwordx4 v[236:237], off
	s_add_u32 m0, s55, 0x4000
	v_lshl_add_u64 v[236:237], v[234:235], 0, s[28:29]
	global_load_lds_dwordx4 v[236:237], off
	s_add_u32 m0, s55, 0x5000
	v_lshl_add_u64 v[236:237], v[234:235], 0, s[30:31]
	global_load_lds_dwordx4 v[236:237], off
	v_or_b32_e32 v128, s54, v139
	v_add3_u32 v128, v128, v137, v138
	ds_read_b128 v[176:179], v128 offset:16384
	ds_read_b128 v[180:183], v128 offset:17408
	ds_read_b128 v[184:187], v128 offset:18432
	ds_read_b128 v[192:195], v128 offset:19456
	v_add_u32_e32 v128, s54, v141
	v_add3_u32 v128, v128, v137, v138
	ds_read_b128 v[144:147], v128
	ds_read_b128 v[148:151], v128 offset:1024
	ds_read_b128 v[152:155], v128 offset:2048
	ds_read_b128 v[156:159], v128 offset:3072
	ds_read_b128 v[160:163], v128 offset:4096
	ds_read_b128 v[164:167], v128 offset:5120
	ds_read_b128 v[168:171], v128 offset:6144
	ds_read_b128 v[172:175], v128 offset:7168
	s_setprio 0
	s_waitcnt lgkmcnt(7)
	v_mfma_f32_16x16x32_bf16 v[124:127], v[144:147], v[176:179], v[124:127]
	v_mfma_f32_16x16x32_bf16 v[120:123], v[144:147], v[180:183], v[120:123]
	v_mfma_f32_16x16x32_bf16 v[116:119], v[144:147], v[184:187], v[116:119]
	v_mfma_f32_16x16x32_bf16 v[112:115], v[144:147], v[192:195], v[112:115]
	s_waitcnt lgkmcnt(6)
	v_mfma_f32_16x16x32_bf16 v[108:111], v[148:151], v[176:179], v[108:111]
	v_mfma_f32_16x16x32_bf16 v[104:107], v[148:151], v[180:183], v[104:107]
	v_mfma_f32_16x16x32_bf16 v[100:103], v[148:151], v[184:187], v[100:103]
	v_mfma_f32_16x16x32_bf16 v[96:99], v[148:151], v[192:195], v[96:99]
	s_waitcnt lgkmcnt(5)
	v_mfma_f32_16x16x32_bf16 v[92:95], v[152:155], v[176:179], v[92:95]
	v_mfma_f32_16x16x32_bf16 v[88:91], v[152:155], v[180:183], v[88:91]
	v_mfma_f32_16x16x32_bf16 v[84:87], v[152:155], v[184:187], v[84:87]
	v_mfma_f32_16x16x32_bf16 v[80:83], v[152:155], v[192:195], v[80:83]
	s_waitcnt lgkmcnt(4)
	v_mfma_f32_16x16x32_bf16 v[76:79], v[156:159], v[176:179], v[76:79]
	v_mfma_f32_16x16x32_bf16 v[72:75], v[156:159], v[180:183], v[72:75]
	v_mfma_f32_16x16x32_bf16 v[68:71], v[156:159], v[184:187], v[68:71]
	v_mfma_f32_16x16x32_bf16 v[64:67], v[156:159], v[192:195], v[64:67]
	s_waitcnt lgkmcnt(3)
	v_mfma_f32_16x16x32_bf16 v[60:63], v[160:163], v[176:179], v[60:63]
	v_mfma_f32_16x16x32_bf16 v[56:59], v[160:163], v[180:183], v[56:59]
	v_mfma_f32_16x16x32_bf16 v[52:55], v[160:163], v[184:187], v[52:55]
	v_mfma_f32_16x16x32_bf16 v[48:51], v[160:163], v[192:195], v[48:51]
	s_waitcnt lgkmcnt(2)
	v_mfma_f32_16x16x32_bf16 v[44:47], v[164:167], v[176:179], v[44:47]
	v_mfma_f32_16x16x32_bf16 v[40:43], v[164:167], v[180:183], v[40:43]
	v_mfma_f32_16x16x32_bf16 v[36:39], v[164:167], v[184:187], v[36:39]
	v_mfma_f32_16x16x32_bf16 v[32:35], v[164:167], v[192:195], v[32:35]
	s_waitcnt lgkmcnt(1)
	v_mfma_f32_16x16x32_bf16 v[28:31], v[168:171], v[176:179], v[28:31]
	v_mfma_f32_16x16x32_bf16 v[24:27], v[168:171], v[180:183], v[24:27]
	v_mfma_f32_16x16x32_bf16 v[20:23], v[168:171], v[184:187], v[20:23]
	v_mfma_f32_16x16x32_bf16 v[16:19], v[168:171], v[192:195], v[16:19]
	s_waitcnt lgkmcnt(0)
	v_mfma_f32_16x16x32_bf16 v[12:15], v[172:175], v[176:179], v[12:15]
	v_mfma_f32_16x16x32_bf16 v[8:11], v[172:175], v[180:183], v[8:11]
	v_mfma_f32_16x16x32_bf16 v[4:7], v[172:175], v[184:187], v[4:7]
	v_mfma_f32_16x16x32_bf16 v[0:3], v[172:175], v[192:195], v[0:3]
	s_add_i32 s45, s44, 1
	s_cmp_lg_u32 s44, 2
	s_cselect_b32 s44, s45, 0
	s_add_u32 s2, s2, 0x80
	s_addc_u32 s3, s3, 0
	s_cmpk_lg_i32 s2, 0xf00
	s_cbranch_scc1 .LBB0_123
	s_waitcnt vmcnt(6) lgkmcnt(0)
	s_barrier
	v_add3_u32 v128, v141, v137, v138
	ds_read_b128 v[130:133], v128
	ds_read_b128 v[144:147], v128 offset:1024
	ds_read_b128 v[148:151], v128 offset:2048
	ds_read_b128 v[152:155], v128 offset:3072
	ds_read_b128 v[156:159], v128 offset:4096
	ds_read_b128 v[160:163], v128 offset:5120
	ds_read_b128 v[164:167], v128 offset:6144
	ds_read_b128 v[168:171], v128 offset:7168
	v_add3_u32 v137, v139, v137, v138
	ds_read_b128 v[138:141], v137 offset:16384
	ds_read_b128 v[172:175], v137 offset:17408
	ds_read_b128 v[176:179], v137 offset:18432
	ds_read_b128 v[180:183], v137 offset:19456
	s_setprio 1
	s_waitcnt lgkmcnt(0)
	v_mfma_f32_16x16x32_bf16 v[124:127], v[130:133], v[138:141], v[124:127]
	v_mfma_f32_16x16x32_bf16 v[120:123], v[130:133], v[172:175], v[120:123]
	v_mfma_f32_16x16x32_bf16 v[116:119], v[130:133], v[176:179], v[116:119]
	v_mfma_f32_16x16x32_bf16 v[112:115], v[130:133], v[180:183], v[112:115]
	v_mfma_f32_16x16x32_bf16 v[108:111], v[144:147], v[138:141], v[108:111]
	v_mfma_f32_16x16x32_bf16 v[104:107], v[144:147], v[172:175], v[104:107]
	v_mfma_f32_16x16x32_bf16 v[100:103], v[144:147], v[176:179], v[100:103]
	v_mfma_f32_16x16x32_bf16 v[96:99], v[144:147], v[180:183], v[96:99]
	v_mfma_f32_16x16x32_bf16 v[92:95], v[148:151], v[138:141], v[92:95]
	v_mfma_f32_16x16x32_bf16 v[88:91], v[148:151], v[172:175], v[88:91]
	v_mfma_f32_16x16x32_bf16 v[84:87], v[148:151], v[176:179], v[84:87]
	v_mfma_f32_16x16x32_bf16 v[80:83], v[148:151], v[180:183], v[80:83]
	v_mfma_f32_16x16x32_bf16 v[76:79], v[152:155], v[138:141], v[76:79]
	v_mfma_f32_16x16x32_bf16 v[72:75], v[152:155], v[172:175], v[72:75]
	v_mfma_f32_16x16x32_bf16 v[68:71], v[152:155], v[176:179], v[68:71]
	v_mfma_f32_16x16x32_bf16 v[64:67], v[152:155], v[180:183], v[64:67]
	v_mfma_f32_16x16x32_bf16 v[60:63], v[156:159], v[138:141], v[60:63]
	v_mfma_f32_16x16x32_bf16 v[56:59], v[156:159], v[172:175], v[56:59]
	v_mfma_f32_16x16x32_bf16 v[52:55], v[156:159], v[176:179], v[52:55]
	v_mfma_f32_16x16x32_bf16 v[48:51], v[156:159], v[180:183], v[48:51]
	v_mfma_f32_16x16x32_bf16 v[44:47], v[160:163], v[138:141], v[44:47]
	v_mfma_f32_16x16x32_bf16 v[40:43], v[160:163], v[172:175], v[40:43]
	v_mfma_f32_16x16x32_bf16 v[36:39], v[160:163], v[176:179], v[36:39]
	v_mfma_f32_16x16x32_bf16 v[32:35], v[160:163], v[180:183], v[32:35]
	v_mfma_f32_16x16x32_bf16 v[28:31], v[164:167], v[138:141], v[28:31]
	v_mfma_f32_16x16x32_bf16 v[24:27], v[164:167], v[172:175], v[24:27]
	v_mfma_f32_16x16x32_bf16 v[20:23], v[164:167], v[176:179], v[20:23]
	v_mfma_f32_16x16x32_bf16 v[16:19], v[164:167], v[180:183], v[16:19]
	v_mfma_f32_16x16x32_bf16 v[12:15], v[168:171], v[138:141], v[12:15]
	v_mfma_f32_16x16x32_bf16 v[8:11], v[168:171], v[172:175], v[8:11]
	v_mfma_f32_16x16x32_bf16 v[4:7], v[168:171], v[176:179], v[4:7]
	v_mfma_f32_16x16x32_bf16 v[0:3], v[168:171], v[180:183], v[0:3]
	s_setprio 0
	s_waitcnt vmcnt(0) lgkmcnt(0)
	s_barrier
	ds_read_b128 v[130:133], v128 offset:24576
	ds_read_b128 v[138:141], v128 offset:25600
	ds_read_b128 v[144:147], v128 offset:26624
	ds_read_b128 v[148:151], v128 offset:27648
	ds_read_b128 v[152:155], v128 offset:28672
	ds_read_b128 v[156:159], v128 offset:29696
	ds_read_b128 v[160:163], v128 offset:30720
	ds_read_b128 v[164:167], v128 offset:31744
	ds_read_b128 v[168:171], v137 offset:40960
	ds_read_b128 v[172:175], v137 offset:41984
	ds_read_b128 v[176:179], v137 offset:43008
	ds_read_b128 v[180:183], v137 offset:44032
	s_setprio 1
	s_waitcnt lgkmcnt(0)
	v_mfma_f32_16x16x32_bf16 v[124:127], v[130:133], v[168:171], v[124:127]
	v_mfma_f32_16x16x32_bf16 v[120:123], v[130:133], v[172:175], v[120:123]
	v_mfma_f32_16x16x32_bf16 v[116:119], v[130:133], v[176:179], v[116:119]
	v_mfma_f32_16x16x32_bf16 v[112:115], v[130:133], v[180:183], v[112:115]
	v_mfma_f32_16x16x32_bf16 v[108:111], v[138:141], v[168:171], v[108:111]
	v_mfma_f32_16x16x32_bf16 v[104:107], v[138:141], v[172:175], v[104:107]
	v_mfma_f32_16x16x32_bf16 v[100:103], v[138:141], v[176:179], v[100:103]
	v_mfma_f32_16x16x32_bf16 v[96:99], v[138:141], v[180:183], v[96:99]
	v_mfma_f32_16x16x32_bf16 v[92:95], v[144:147], v[168:171], v[92:95]
	v_mfma_f32_16x16x32_bf16 v[88:91], v[144:147], v[172:175], v[88:91]
	v_mfma_f32_16x16x32_bf16 v[84:87], v[144:147], v[176:179], v[84:87]
	v_mfma_f32_16x16x32_bf16 v[130:133], v[144:147], v[180:183], v[80:83]
	v_mfma_f32_16x16x32_bf16 v[138:141], v[148:151], v[168:171], v[76:79]
	v_mfma_f32_16x16x32_bf16 v[72:75], v[148:151], v[172:175], v[72:75]
	v_mfma_f32_16x16x32_bf16 v[68:71], v[148:151], v[176:179], v[68:71]
	v_mfma_f32_16x16x32_bf16 v[64:67], v[148:151], v[180:183], v[64:67]
	v_mfma_f32_16x16x32_bf16 v[60:63], v[152:155], v[168:171], v[60:63]
	v_mfma_f32_16x16x32_bf16 v[56:59], v[152:155], v[172:175], v[56:59]
	v_mfma_f32_16x16x32_bf16 v[52:55], v[152:155], v[176:179], v[52:55]
	v_mfma_f32_16x16x32_bf16 v[48:51], v[152:155], v[180:183], v[48:51]
	v_mfma_f32_16x16x32_bf16 v[44:47], v[156:159], v[168:171], v[44:47]
	v_mfma_f32_16x16x32_bf16 v[40:43], v[156:159], v[172:175], v[40:43]
	v_mfma_f32_16x16x32_bf16 v[36:39], v[156:159], v[176:179], v[36:39]
	v_mfma_f32_16x16x32_bf16 v[32:35], v[156:159], v[180:183], v[32:35]
	v_mfma_f32_16x16x32_bf16 v[28:31], v[160:163], v[168:171], v[28:31]
	v_mfma_f32_16x16x32_bf16 v[24:27], v[160:163], v[172:175], v[24:27]
	v_mfma_f32_16x16x32_bf16 v[20:23], v[160:163], v[176:179], v[20:23]
	v_mfma_f32_16x16x32_bf16 v[16:19], v[160:163], v[180:183], v[16:19]
	v_mfma_f32_16x16x32_bf16 v[12:15], v[164:167], v[168:171], v[12:15]
	v_mfma_f32_16x16x32_bf16 v[8:11], v[164:167], v[172:175], v[8:11]
	v_mfma_f32_16x16x32_bf16 v[4:7], v[164:167], v[176:179], v[4:7]
	v_mfma_f32_16x16x32_bf16 v[0:3], v[164:167], v[180:183], v[0:3]
	s_setprio 0
	v_and_b32_e32 v76, 0xffffff80, v134
	v_add_u32_e32 v76, s43, v76
	v_lshlrev_b32_e32 v77, 6, v136
	s_add_i32 s2, s4, 0xfffffc00
	v_ashrrev_i32_e32 v76, 6, v76
	v_or3_b32 v136, v77, s2, v135
	v_ashrrev_i32_e32 v77, 31, v76
	v_lshlrev_b64 v[78:79], 17, v[76:77]
	v_readlane_b32 s2, v254, 60
	v_lshrrev_b32_e32 v77, 1, v134
	v_and_b32_sdwa v81, v127, v142 dst_sel:DWORD dst_unused:UNUSED_PAD src0_sel:WORD_1 src1_sel:DWORD
	v_and_b32_sdwa v82, v125, v142 dst_sel:DWORD dst_unused:UNUSED_PAD src0_sel:WORD_1 src1_sel:DWORD
	v_readlane_b32 s3, v254, 61
	v_and_b32_e32 v128, 24, v77
	v_and_b32_sdwa v77, v126, v142 dst_sel:DWORD dst_unused:UNUSED_PAD src0_sel:WORD_1 src1_sel:DWORD
	v_and_b32_sdwa v80, v124, v142 dst_sel:DWORD dst_unused:UNUSED_PAD src0_sel:WORD_1 src1_sel:DWORD
	v_add3_u32 v81, v127, v81, s46
	v_add3_u32 v82, v125, v82, s46
	v_lshl_add_u64 v[78:79], s[2:3], 0, v[78:79]
	v_mov_b32_e32 v137, v129
	v_add3_u32 v80, v124, v80, s46
	v_add3_u32 v77, v126, v77, s46
	v_and_b32_e32 v81, 0xffff0000, v81
	v_and_b32_e32 v82, 0xffff0000, v82
	v_and_b32_sdwa v83, v123, v142 dst_sel:DWORD dst_unused:UNUSED_PAD src0_sel:WORD_1 src1_sel:DWORD
	v_lshl_add_u64 v[134:135], v[78:79], 0, v[128:129]
	v_lshlrev_b64 v[78:79], 7, v[136:137]
	v_or_b32_sdwa v81, v81, v77 dst_sel:DWORD dst_unused:UNUSED_PAD src0_sel:DWORD src1_sel:WORD_1
	v_or_b32_sdwa v80, v82, v80 dst_sel:DWORD dst_unused:UNUSED_PAD src0_sel:DWORD src1_sel:WORD_1
	v_and_b32_sdwa v77, v122, v142 dst_sel:DWORD dst_unused:UNUSED_PAD src0_sel:WORD_1 src1_sel:DWORD
	v_and_b32_sdwa v82, v120, v142 dst_sel:DWORD dst_unused:UNUSED_PAD src0_sel:WORD_1 src1_sel:DWORD
	v_add3_u32 v83, v123, v83, s46
	v_lshl_add_u64 v[144:145], v[134:135], 0, v[78:79]
	v_add3_u32 v82, v120, v82, s46
	v_add3_u32 v77, v122, v77, s46
	v_and_b32_sdwa v120, v121, v142 dst_sel:DWORD dst_unused:UNUSED_PAD src0_sel:WORD_1 src1_sel:DWORD
	v_and_b32_e32 v83, 0xffff0000, v83
	global_store_dwordx2 v[144:145], v[80:81], off
	v_or_b32_e32 v80, 16, v136
	v_mov_b32_e32 v81, v129
	v_add3_u32 v120, v121, v120, s46
	v_or_b32_sdwa v83, v83, v77 dst_sel:DWORD dst_unused:UNUSED_PAD src0_sel:DWORD src1_sel:WORD_1
	v_and_b32_sdwa v77, v118, v142 dst_sel:DWORD dst_unused:UNUSED_PAD src0_sel:WORD_1 src1_sel:DWORD
	v_lshlrev_b64 v[80:81], 7, v[80:81]
	v_and_b32_e32 v120, 0xffff0000, v120
	v_and_b32_sdwa v122, v116, v142 dst_sel:DWORD dst_unused:UNUSED_PAD src0_sel:WORD_1 src1_sel:DWORD
	v_add3_u32 v77, v118, v77, s46
	v_and_b32_sdwa v118, v119, v142 dst_sel:DWORD dst_unused:UNUSED_PAD src0_sel:WORD_1 src1_sel:DWORD
	v_lshl_add_u64 v[124:125], v[134:135], 0, v[80:81]
	v_or_b32_sdwa v82, v120, v82 dst_sel:DWORD dst_unused:UNUSED_PAD src0_sel:DWORD src1_sel:WORD_1
	v_add3_u32 v116, v116, v122, s46
	v_and_b32_sdwa v122, v117, v142 dst_sel:DWORD dst_unused:UNUSED_PAD src0_sel:WORD_1 src1_sel:DWORD
	v_add3_u32 v118, v119, v118, s46
	global_store_dwordx2 v[124:125], v[82:83], off
	v_or_b32_e32 v82, 32, v136
	v_mov_b32_e32 v83, v129
	v_add3_u32 v117, v117, v122, s46
	v_and_b32_e32 v118, 0xffff0000, v118
	v_lshlrev_b64 v[82:83], 7, v[82:83]
	v_and_b32_e32 v119, 0xffff0000, v117
	v_or_b32_sdwa v117, v118, v77 dst_sel:DWORD dst_unused:UNUSED_PAD src0_sel:DWORD src1_sel:WORD_1
	v_and_b32_sdwa v77, v114, v142 dst_sel:DWORD dst_unused:UNUSED_PAD src0_sel:WORD_1 src1_sel:DWORD
	v_and_b32_sdwa v122, v112, v142 dst_sel:DWORD dst_unused:UNUSED_PAD src0_sel:WORD_1 src1_sel:DWORD
	v_lshl_add_u64 v[120:121], v[134:135], 0, v[82:83]
	v_or_b32_sdwa v116, v119, v116 dst_sel:DWORD dst_unused:UNUSED_PAD src0_sel:DWORD src1_sel:WORD_1
	v_add3_u32 v112, v112, v122, s46
	v_add3_u32 v77, v114, v77, s46
	v_and_b32_sdwa v114, v115, v142 dst_sel:DWORD dst_unused:UNUSED_PAD src0_sel:WORD_1 src1_sel:DWORD
	v_and_b32_sdwa v122, v113, v142 dst_sel:DWORD dst_unused:UNUSED_PAD src0_sel:WORD_1 src1_sel:DWORD
	global_store_dwordx2 v[120:121], v[116:117], off
	v_or_b32_e32 v116, 48, v136
	v_mov_b32_e32 v117, v129
	v_add3_u32 v114, v115, v114, s46
	v_add3_u32 v113, v113, v122, s46
	v_lshlrev_b64 v[116:117], 7, v[116:117]
	v_and_b32_e32 v114, 0xffff0000, v114
	v_and_b32_e32 v115, 0xffff0000, v113
	v_lshl_add_u64 v[118:119], v[134:135], 0, v[116:117]
	v_or_b32_sdwa v113, v114, v77 dst_sel:DWORD dst_unused:UNUSED_PAD src0_sel:DWORD src1_sel:WORD_1
	v_or_b32_sdwa v112, v115, v112 dst_sel:DWORD dst_unused:UNUSED_PAD src0_sel:DWORD src1_sel:WORD_1
	global_store_dwordx2 v[118:119], v[112:113], off
	v_and_b32_sdwa v77, v110, v142 dst_sel:DWORD dst_unused:UNUSED_PAD src0_sel:WORD_1 src1_sel:DWORD
	v_and_b32_sdwa v112, v108, v142 dst_sel:DWORD dst_unused:UNUSED_PAD src0_sel:WORD_1 src1_sel:DWORD
	v_add3_u32 v108, v108, v112, s46
	v_add3_u32 v77, v110, v77, s46
	v_and_b32_sdwa v110, v111, v142 dst_sel:DWORD dst_unused:UNUSED_PAD src0_sel:WORD_1 src1_sel:DWORD
	v_and_b32_sdwa v112, v109, v142 dst_sel:DWORD dst_unused:UNUSED_PAD src0_sel:WORD_1 src1_sel:DWORD
	v_add3_u32 v110, v111, v110, s46
	v_add3_u32 v109, v109, v112, s46
	v_and_b32_e32 v110, 0xffff0000, v110
	v_and_b32_e32 v111, 0xffff0000, v109
	v_or_b32_sdwa v109, v110, v77 dst_sel:DWORD dst_unused:UNUSED_PAD src0_sel:DWORD src1_sel:WORD_1
	v_or_b32_sdwa v108, v111, v108 dst_sel:DWORD dst_unused:UNUSED_PAD src0_sel:DWORD src1_sel:WORD_1
	global_store_dwordx2 v[144:145], v[108:109], off offset:32
	v_and_b32_sdwa v77, v106, v142 dst_sel:DWORD dst_unused:UNUSED_PAD src0_sel:WORD_1 src1_sel:DWORD
	v_and_b32_sdwa v108, v104, v142 dst_sel:DWORD dst_unused:UNUSED_PAD src0_sel:WORD_1 src1_sel:DWORD
	v_add3_u32 v104, v104, v108, s46
	v_add3_u32 v77, v106, v77, s46
	v_and_b32_sdwa v106, v107, v142 dst_sel:DWORD dst_unused:UNUSED_PAD src0_sel:WORD_1 src1_sel:DWORD
	v_and_b32_sdwa v108, v105, v142 dst_sel:DWORD dst_unused:UNUSED_PAD src0_sel:WORD_1 src1_sel:DWORD
	v_add3_u32 v106, v107, v106, s46
	v_add3_u32 v105, v105, v108, s46
	v_and_b32_e32 v106, 0xffff0000, v106
	v_and_b32_e32 v107, 0xffff0000, v105
	v_or_b32_sdwa v105, v106, v77 dst_sel:DWORD dst_unused:UNUSED_PAD src0_sel:DWORD src1_sel:WORD_1
	v_or_b32_sdwa v104, v107, v104 dst_sel:DWORD dst_unused:UNUSED_PAD src0_sel:DWORD src1_sel:WORD_1
	global_store_dwordx2 v[124:125], v[104:105], off offset:32
	v_and_b32_sdwa v77, v102, v142 dst_sel:DWORD dst_unused:UNUSED_PAD src0_sel:WORD_1 src1_sel:DWORD
	v_and_b32_sdwa v104, v100, v142 dst_sel:DWORD dst_unused:UNUSED_PAD src0_sel:WORD_1 src1_sel:DWORD
	v_add3_u32 v100, v100, v104, s46
	v_add3_u32 v77, v102, v77, s46
	v_and_b32_sdwa v102, v103, v142 dst_sel:DWORD dst_unused:UNUSED_PAD src0_sel:WORD_1 src1_sel:DWORD
	v_and_b32_sdwa v104, v101, v142 dst_sel:DWORD dst_unused:UNUSED_PAD src0_sel:WORD_1 src1_sel:DWORD
	v_add3_u32 v102, v103, v102, s46
	v_add3_u32 v101, v101, v104, s46
	v_and_b32_e32 v102, 0xffff0000, v102
	v_and_b32_e32 v103, 0xffff0000, v101
	v_or_b32_sdwa v101, v102, v77 dst_sel:DWORD dst_unused:UNUSED_PAD src0_sel:DWORD src1_sel:WORD_1
	v_or_b32_sdwa v100, v103, v100 dst_sel:DWORD dst_unused:UNUSED_PAD src0_sel:DWORD src1_sel:WORD_1
	global_store_dwordx2 v[120:121], v[100:101], off offset:32
	v_and_b32_sdwa v77, v98, v142 dst_sel:DWORD dst_unused:UNUSED_PAD src0_sel:WORD_1 src1_sel:DWORD
	v_and_b32_sdwa v100, v96, v142 dst_sel:DWORD dst_unused:UNUSED_PAD src0_sel:WORD_1 src1_sel:DWORD
	v_add3_u32 v96, v96, v100, s46
	v_add3_u32 v77, v98, v77, s46
	v_and_b32_sdwa v98, v99, v142 dst_sel:DWORD dst_unused:UNUSED_PAD src0_sel:WORD_1 src1_sel:DWORD
	v_and_b32_sdwa v100, v97, v142 dst_sel:DWORD dst_unused:UNUSED_PAD src0_sel:WORD_1 src1_sel:DWORD
	v_add3_u32 v98, v99, v98, s46
	v_add3_u32 v97, v97, v100, s46
	v_and_b32_e32 v98, 0xffff0000, v98
	v_and_b32_e32 v99, 0xffff0000, v97
	v_or_b32_sdwa v97, v98, v77 dst_sel:DWORD dst_unused:UNUSED_PAD src0_sel:DWORD src1_sel:WORD_1
	v_or_b32_sdwa v96, v99, v96 dst_sel:DWORD dst_unused:UNUSED_PAD src0_sel:DWORD src1_sel:WORD_1
	global_store_dwordx2 v[118:119], v[96:97], off offset:32
	v_and_b32_sdwa v77, v94, v142 dst_sel:DWORD dst_unused:UNUSED_PAD src0_sel:WORD_1 src1_sel:DWORD
	v_and_b32_sdwa v96, v92, v142 dst_sel:DWORD dst_unused:UNUSED_PAD src0_sel:WORD_1 src1_sel:DWORD
	v_add3_u32 v92, v92, v96, s46
	v_add3_u32 v77, v94, v77, s46
	v_and_b32_sdwa v94, v95, v142 dst_sel:DWORD dst_unused:UNUSED_PAD src0_sel:WORD_1 src1_sel:DWORD
	v_and_b32_sdwa v96, v93, v142 dst_sel:DWORD dst_unused:UNUSED_PAD src0_sel:WORD_1 src1_sel:DWORD
	v_add3_u32 v94, v95, v94, s46
	v_add3_u32 v93, v93, v96, s46
	v_and_b32_e32 v94, 0xffff0000, v94
	v_and_b32_e32 v95, 0xffff0000, v93
	v_or_b32_sdwa v93, v94, v77 dst_sel:DWORD dst_unused:UNUSED_PAD src0_sel:DWORD src1_sel:WORD_1
	v_or_b32_sdwa v92, v95, v92 dst_sel:DWORD dst_unused:UNUSED_PAD src0_sel:DWORD src1_sel:WORD_1
	global_store_dwordx2 v[144:145], v[92:93], off offset:64
	v_and_b32_sdwa v77, v90, v142 dst_sel:DWORD dst_unused:UNUSED_PAD src0_sel:WORD_1 src1_sel:DWORD
	v_and_b32_sdwa v92, v88, v142 dst_sel:DWORD dst_unused:UNUSED_PAD src0_sel:WORD_1 src1_sel:DWORD
	v_add3_u32 v88, v88, v92, s46
	v_add3_u32 v77, v90, v77, s46
	v_and_b32_sdwa v90, v91, v142 dst_sel:DWORD dst_unused:UNUSED_PAD src0_sel:WORD_1 src1_sel:DWORD
	v_and_b32_sdwa v92, v89, v142 dst_sel:DWORD dst_unused:UNUSED_PAD src0_sel:WORD_1 src1_sel:DWORD
	v_add3_u32 v90, v91, v90, s46
	v_add3_u32 v89, v89, v92, s46
	v_and_b32_e32 v90, 0xffff0000, v90
	v_and_b32_e32 v91, 0xffff0000, v89
	v_or_b32_sdwa v89, v90, v77 dst_sel:DWORD dst_unused:UNUSED_PAD src0_sel:DWORD src1_sel:WORD_1
	v_or_b32_sdwa v88, v91, v88 dst_sel:DWORD dst_unused:UNUSED_PAD src0_sel:DWORD src1_sel:WORD_1
	global_store_dwordx2 v[124:125], v[88:89], off offset:64
	v_and_b32_sdwa v77, v86, v142 dst_sel:DWORD dst_unused:UNUSED_PAD src0_sel:WORD_1 src1_sel:DWORD
	v_and_b32_sdwa v88, v84, v142 dst_sel:DWORD dst_unused:UNUSED_PAD src0_sel:WORD_1 src1_sel:DWORD
	v_add3_u32 v84, v84, v88, s46
	v_add3_u32 v77, v86, v77, s46
	v_and_b32_sdwa v86, v87, v142 dst_sel:DWORD dst_unused:UNUSED_PAD src0_sel:WORD_1 src1_sel:DWORD
	v_and_b32_sdwa v88, v85, v142 dst_sel:DWORD dst_unused:UNUSED_PAD src0_sel:WORD_1 src1_sel:DWORD
	v_add3_u32 v86, v87, v86, s46
	v_add3_u32 v85, v85, v88, s46
	v_and_b32_e32 v86, 0xffff0000, v86
	v_and_b32_e32 v87, 0xffff0000, v85
	v_or_b32_sdwa v85, v86, v77 dst_sel:DWORD dst_unused:UNUSED_PAD src0_sel:DWORD src1_sel:WORD_1
	v_or_b32_sdwa v84, v87, v84 dst_sel:DWORD dst_unused:UNUSED_PAD src0_sel:DWORD src1_sel:WORD_1
	global_store_dwordx2 v[120:121], v[84:85], off offset:64
	v_and_b32_sdwa v85, v133, v142 dst_sel:DWORD dst_unused:UNUSED_PAD src0_sel:WORD_1 src1_sel:DWORD
	v_and_b32_sdwa v86, v131, v142 dst_sel:DWORD dst_unused:UNUSED_PAD src0_sel:WORD_1 src1_sel:DWORD
	v_and_b32_sdwa v77, v132, v142 dst_sel:DWORD dst_unused:UNUSED_PAD src0_sel:WORD_1 src1_sel:DWORD
	v_and_b32_sdwa v84, v130, v142 dst_sel:DWORD dst_unused:UNUSED_PAD src0_sel:WORD_1 src1_sel:DWORD
	v_add3_u32 v85, v133, v85, s46
	v_add3_u32 v86, v131, v86, s46
	v_add3_u32 v84, v130, v84, s46
	v_add3_u32 v77, v132, v77, s46
	v_and_b32_e32 v85, 0xffff0000, v85
	v_and_b32_e32 v86, 0xffff0000, v86
	v_or_b32_sdwa v85, v85, v77 dst_sel:DWORD dst_unused:UNUSED_PAD src0_sel:DWORD src1_sel:WORD_1
	v_or_b32_sdwa v84, v86, v84 dst_sel:DWORD dst_unused:UNUSED_PAD src0_sel:DWORD src1_sel:WORD_1
	global_store_dwordx2 v[118:119], v[84:85], off offset:64
	v_and_b32_sdwa v85, v141, v142 dst_sel:DWORD dst_unused:UNUSED_PAD src0_sel:WORD_1 src1_sel:DWORD
	v_and_b32_sdwa v86, v139, v142 dst_sel:DWORD dst_unused:UNUSED_PAD src0_sel:WORD_1 src1_sel:DWORD
	v_and_b32_sdwa v77, v140, v142 dst_sel:DWORD dst_unused:UNUSED_PAD src0_sel:WORD_1 src1_sel:DWORD
	v_and_b32_sdwa v84, v138, v142 dst_sel:DWORD dst_unused:UNUSED_PAD src0_sel:WORD_1 src1_sel:DWORD
	v_add3_u32 v85, v141, v85, s46
	v_add3_u32 v86, v139, v86, s46
	v_add3_u32 v84, v138, v84, s46
	v_add3_u32 v77, v140, v77, s46
	v_and_b32_e32 v85, 0xffff0000, v85
	v_and_b32_e32 v86, 0xffff0000, v86
	v_or_b32_sdwa v85, v85, v77 dst_sel:DWORD dst_unused:UNUSED_PAD src0_sel:DWORD src1_sel:WORD_1
	v_or_b32_sdwa v84, v86, v84 dst_sel:DWORD dst_unused:UNUSED_PAD src0_sel:DWORD src1_sel:WORD_1
	global_store_dwordx2 v[144:145], v[84:85], off offset:96
	v_and_b32_sdwa v77, v74, v142 dst_sel:DWORD dst_unused:UNUSED_PAD src0_sel:WORD_1 src1_sel:DWORD
	v_and_b32_sdwa v84, v72, v142 dst_sel:DWORD dst_unused:UNUSED_PAD src0_sel:WORD_1 src1_sel:DWORD
	v_add3_u32 v72, v72, v84, s46
	v_add3_u32 v74, v74, v77, s46
	v_and_b32_sdwa v77, v75, v142 dst_sel:DWORD dst_unused:UNUSED_PAD src0_sel:WORD_1 src1_sel:DWORD
	v_and_b32_sdwa v84, v73, v142 dst_sel:DWORD dst_unused:UNUSED_PAD src0_sel:WORD_1 src1_sel:DWORD
	v_add3_u32 v75, v75, v77, s46
	v_add3_u32 v73, v73, v84, s46
	v_and_b32_e32 v75, 0xffff0000, v75
	v_and_b32_e32 v77, 0xffff0000, v73
	v_or_b32_sdwa v73, v75, v74 dst_sel:DWORD dst_unused:UNUSED_PAD src0_sel:DWORD src1_sel:WORD_1
	v_or_b32_sdwa v72, v77, v72 dst_sel:DWORD dst_unused:UNUSED_PAD src0_sel:DWORD src1_sel:WORD_1
	global_store_dwordx2 v[124:125], v[72:73], off offset:96
	v_and_b32_sdwa v72, v70, v142 dst_sel:DWORD dst_unused:UNUSED_PAD src0_sel:WORD_1 src1_sel:DWORD
	v_and_b32_sdwa v73, v68, v142 dst_sel:DWORD dst_unused:UNUSED_PAD src0_sel:WORD_1 src1_sel:DWORD
	v_add3_u32 v68, v68, v73, s46
	v_add3_u32 v70, v70, v72, s46
	v_and_b32_sdwa v72, v71, v142 dst_sel:DWORD dst_unused:UNUSED_PAD src0_sel:WORD_1 src1_sel:DWORD
	v_and_b32_sdwa v73, v69, v142 dst_sel:DWORD dst_unused:UNUSED_PAD src0_sel:WORD_1 src1_sel:DWORD
	v_add3_u32 v71, v71, v72, s46
	v_add3_u32 v69, v69, v73, s46
	v_and_b32_e32 v71, 0xffff0000, v71
	v_and_b32_e32 v72, 0xffff0000, v69
	v_or_b32_sdwa v69, v71, v70 dst_sel:DWORD dst_unused:UNUSED_PAD src0_sel:DWORD src1_sel:WORD_1
	v_or_b32_sdwa v68, v72, v68 dst_sel:DWORD dst_unused:UNUSED_PAD src0_sel:DWORD src1_sel:WORD_1
	global_store_dwordx2 v[120:121], v[68:69], off offset:96
	v_and_b32_sdwa v69, v64, v142 dst_sel:DWORD dst_unused:UNUSED_PAD src0_sel:WORD_1 src1_sel:DWORD
	v_and_b32_sdwa v68, v66, v142 dst_sel:DWORD dst_unused:UNUSED_PAD src0_sel:WORD_1 src1_sel:DWORD
	v_add3_u32 v64, v64, v69, s46
	v_and_b32_sdwa v69, v65, v142 dst_sel:DWORD dst_unused:UNUSED_PAD src0_sel:WORD_1 src1_sel:DWORD
	v_add3_u32 v66, v66, v68, s46
	v_and_b32_sdwa v68, v67, v142 dst_sel:DWORD dst_unused:UNUSED_PAD src0_sel:WORD_1 src1_sel:DWORD
	v_add3_u32 v65, v65, v69, s46
	v_add3_u32 v67, v67, v68, s46
	v_and_b32_e32 v68, 0xffff0000, v65
	v_or_b32_sdwa v64, v68, v64 dst_sel:DWORD dst_unused:UNUSED_PAD src0_sel:DWORD src1_sel:WORD_1
	v_and_b32_sdwa v68, v62, v142 dst_sel:DWORD dst_unused:UNUSED_PAD src0_sel:WORD_1 src1_sel:DWORD
	v_and_b32_sdwa v69, v60, v142 dst_sel:DWORD dst_unused:UNUSED_PAD src0_sel:WORD_1 src1_sel:DWORD
	v_add3_u32 v62, v62, v68, s46
	v_and_b32_sdwa v68, v63, v142 dst_sel:DWORD dst_unused:UNUSED_PAD src0_sel:WORD_1 src1_sel:DWORD
	v_add3_u32 v60, v60, v69, s46
	v_and_b32_sdwa v69, v61, v142 dst_sel:DWORD dst_unused:UNUSED_PAD src0_sel:WORD_1 src1_sel:DWORD
	v_add3_u32 v63, v63, v68, s46
	v_add3_u32 v61, v61, v69, s46
	v_and_b32_e32 v63, 0xffff0000, v63
	v_and_b32_e32 v68, 0xffff0000, v61
	v_or_b32_sdwa v61, v63, v62 dst_sel:DWORD dst_unused:UNUSED_PAD src0_sel:DWORD src1_sel:WORD_1
	v_and_b32_sdwa v62, v58, v142 dst_sel:DWORD dst_unused:UNUSED_PAD src0_sel:WORD_1 src1_sel:DWORD
	v_and_b32_sdwa v63, v56, v142 dst_sel:DWORD dst_unused:UNUSED_PAD src0_sel:WORD_1 src1_sel:DWORD
	v_add3_u32 v58, v58, v62, s46
	v_and_b32_sdwa v62, v59, v142 dst_sel:DWORD dst_unused:UNUSED_PAD src0_sel:WORD_1 src1_sel:DWORD
	v_and_b32_e32 v67, 0xffff0000, v67
	v_add3_u32 v56, v56, v63, s46
	v_and_b32_sdwa v63, v57, v142 dst_sel:DWORD dst_unused:UNUSED_PAD src0_sel:WORD_1 src1_sel:DWORD
	v_add3_u32 v59, v59, v62, s46
	v_or_b32_sdwa v65, v67, v66 dst_sel:DWORD dst_unused:UNUSED_PAD src0_sel:DWORD src1_sel:WORD_1
	v_add3_u32 v57, v57, v63, s46
	v_and_b32_e32 v59, 0xffff0000, v59
	global_store_dwordx2 v[118:119], v[64:65], off offset:96
	v_or_b32_e32 v64, 1, v76
	v_and_b32_e32 v62, 0xffff0000, v57
	v_or_b32_sdwa v57, v59, v58 dst_sel:DWORD dst_unused:UNUSED_PAD src0_sel:DWORD src1_sel:WORD_1
	v_and_b32_sdwa v58, v54, v142 dst_sel:DWORD dst_unused:UNUSED_PAD src0_sel:WORD_1 src1_sel:DWORD
	v_ashrrev_i32_e32 v65, 31, v64
	v_and_b32_sdwa v59, v52, v142 dst_sel:DWORD dst_unused:UNUSED_PAD src0_sel:WORD_1 src1_sel:DWORD
	v_add3_u32 v54, v54, v58, s46
	v_and_b32_sdwa v58, v55, v142 dst_sel:DWORD dst_unused:UNUSED_PAD src0_sel:WORD_1 src1_sel:DWORD
	v_lshlrev_b64 v[64:65], 17, v[64:65]
	v_add3_u32 v52, v52, v59, s46
	v_and_b32_sdwa v59, v53, v142 dst_sel:DWORD dst_unused:UNUSED_PAD src0_sel:WORD_1 src1_sel:DWORD
	v_add3_u32 v55, v55, v58, s46
	v_lshl_add_u64 v[64:65], s[2:3], 0, v[64:65]
	v_add3_u32 v53, v53, v59, s46
	v_and_b32_e32 v55, 0xffff0000, v55
	v_lshl_add_u64 v[64:65], v[64:65], 0, v[128:129]
	v_and_b32_e32 v58, 0xffff0000, v53
	v_or_b32_sdwa v53, v55, v54 dst_sel:DWORD dst_unused:UNUSED_PAD src0_sel:DWORD src1_sel:WORD_1
	v_and_b32_sdwa v54, v50, v142 dst_sel:DWORD dst_unused:UNUSED_PAD src0_sel:WORD_1 src1_sel:DWORD
	v_and_b32_sdwa v55, v48, v142 dst_sel:DWORD dst_unused:UNUSED_PAD src0_sel:WORD_1 src1_sel:DWORD
	v_lshl_add_u64 v[66:67], v[64:65], 0, v[78:79]
	v_or_b32_sdwa v60, v68, v60 dst_sel:DWORD dst_unused:UNUSED_PAD src0_sel:DWORD src1_sel:WORD_1
	v_add3_u32 v48, v48, v55, s46
	v_add3_u32 v50, v50, v54, s46
	v_and_b32_sdwa v54, v51, v142 dst_sel:DWORD dst_unused:UNUSED_PAD src0_sel:WORD_1 src1_sel:DWORD
	v_and_b32_sdwa v55, v49, v142 dst_sel:DWORD dst_unused:UNUSED_PAD src0_sel:WORD_1 src1_sel:DWORD
	global_store_dwordx2 v[66:67], v[60:61], off
	v_lshl_add_u64 v[60:61], v[64:65], 0, v[80:81]
	v_or_b32_sdwa v56, v62, v56 dst_sel:DWORD dst_unused:UNUSED_PAD src0_sel:DWORD src1_sel:WORD_1
	v_add3_u32 v51, v51, v54, s46
	v_add3_u32 v49, v49, v55, s46
	global_store_dwordx2 v[60:61], v[56:57], off
	v_lshl_add_u64 v[56:57], v[64:65], 0, v[82:83]
	v_or_b32_sdwa v52, v58, v52 dst_sel:DWORD dst_unused:UNUSED_PAD src0_sel:DWORD src1_sel:WORD_1
	v_and_b32_e32 v51, 0xffff0000, v51
	v_and_b32_e32 v54, 0xffff0000, v49
	global_store_dwordx2 v[56:57], v[52:53], off
	v_lshl_add_u64 v[52:53], v[64:65], 0, v[116:117]
	v_or_b32_sdwa v49, v51, v50 dst_sel:DWORD dst_unused:UNUSED_PAD src0_sel:DWORD src1_sel:WORD_1
	v_or_b32_sdwa v48, v54, v48 dst_sel:DWORD dst_unused:UNUSED_PAD src0_sel:DWORD src1_sel:WORD_1
	global_store_dwordx2 v[52:53], v[48:49], off
	v_and_b32_sdwa v48, v46, v142 dst_sel:DWORD dst_unused:UNUSED_PAD src0_sel:WORD_1 src1_sel:DWORD
	v_and_b32_sdwa v49, v44, v142 dst_sel:DWORD dst_unused:UNUSED_PAD src0_sel:WORD_1 src1_sel:DWORD
	v_add3_u32 v44, v44, v49, s46
	v_add3_u32 v46, v46, v48, s46
	v_and_b32_sdwa v48, v47, v142 dst_sel:DWORD dst_unused:UNUSED_PAD src0_sel:WORD_1 src1_sel:DWORD
	v_and_b32_sdwa v49, v45, v142 dst_sel:DWORD dst_unused:UNUSED_PAD src0_sel:WORD_1 src1_sel:DWORD
	v_add3_u32 v47, v47, v48, s46
	v_add3_u32 v45, v45, v49, s46
	v_and_b32_e32 v47, 0xffff0000, v47
	v_and_b32_e32 v48, 0xffff0000, v45
	v_or_b32_sdwa v45, v47, v46 dst_sel:DWORD dst_unused:UNUSED_PAD src0_sel:DWORD src1_sel:WORD_1
	v_or_b32_sdwa v44, v48, v44 dst_sel:DWORD dst_unused:UNUSED_PAD src0_sel:DWORD src1_sel:WORD_1
	global_store_dwordx2 v[66:67], v[44:45], off offset:32
	v_and_b32_sdwa v44, v42, v142 dst_sel:DWORD dst_unused:UNUSED_PAD src0_sel:WORD_1 src1_sel:DWORD
	v_and_b32_sdwa v45, v40, v142 dst_sel:DWORD dst_unused:UNUSED_PAD src0_sel:WORD_1 src1_sel:DWORD
	v_add3_u32 v40, v40, v45, s46
	v_add3_u32 v42, v42, v44, s46
	v_and_b32_sdwa v44, v43, v142 dst_sel:DWORD dst_unused:UNUSED_PAD src0_sel:WORD_1 src1_sel:DWORD
	v_and_b32_sdwa v45, v41, v142 dst_sel:DWORD dst_unused:UNUSED_PAD src0_sel:WORD_1 src1_sel:DWORD
	v_add3_u32 v43, v43, v44, s46
	v_add3_u32 v41, v41, v45, s46
	v_and_b32_e32 v43, 0xffff0000, v43
	v_and_b32_e32 v44, 0xffff0000, v41
	v_or_b32_sdwa v41, v43, v42 dst_sel:DWORD dst_unused:UNUSED_PAD src0_sel:DWORD src1_sel:WORD_1
	v_or_b32_sdwa v40, v44, v40 dst_sel:DWORD dst_unused:UNUSED_PAD src0_sel:DWORD src1_sel:WORD_1
	global_store_dwordx2 v[60:61], v[40:41], off offset:32
	v_and_b32_sdwa v40, v38, v142 dst_sel:DWORD dst_unused:UNUSED_PAD src0_sel:WORD_1 src1_sel:DWORD
	v_and_b32_sdwa v41, v36, v142 dst_sel:DWORD dst_unused:UNUSED_PAD src0_sel:WORD_1 src1_sel:DWORD
	v_add3_u32 v36, v36, v41, s46
	v_add3_u32 v38, v38, v40, s46
	v_and_b32_sdwa v40, v39, v142 dst_sel:DWORD dst_unused:UNUSED_PAD src0_sel:WORD_1 src1_sel:DWORD
	v_and_b32_sdwa v41, v37, v142 dst_sel:DWORD dst_unused:UNUSED_PAD src0_sel:WORD_1 src1_sel:DWORD
	v_add3_u32 v39, v39, v40, s46
	v_add3_u32 v37, v37, v41, s46
	v_and_b32_e32 v39, 0xffff0000, v39
	v_and_b32_e32 v40, 0xffff0000, v37
	v_or_b32_sdwa v37, v39, v38 dst_sel:DWORD dst_unused:UNUSED_PAD src0_sel:DWORD src1_sel:WORD_1
	v_or_b32_sdwa v36, v40, v36 dst_sel:DWORD dst_unused:UNUSED_PAD src0_sel:DWORD src1_sel:WORD_1
	global_store_dwordx2 v[56:57], v[36:37], off offset:32
	v_and_b32_sdwa v36, v34, v142 dst_sel:DWORD dst_unused:UNUSED_PAD src0_sel:WORD_1 src1_sel:DWORD
	v_and_b32_sdwa v37, v32, v142 dst_sel:DWORD dst_unused:UNUSED_PAD src0_sel:WORD_1 src1_sel:DWORD
	v_add3_u32 v32, v32, v37, s46
	v_add3_u32 v34, v34, v36, s46
	v_and_b32_sdwa v36, v35, v142 dst_sel:DWORD dst_unused:UNUSED_PAD src0_sel:WORD_1 src1_sel:DWORD
	v_and_b32_sdwa v37, v33, v142 dst_sel:DWORD dst_unused:UNUSED_PAD src0_sel:WORD_1 src1_sel:DWORD
	v_add3_u32 v35, v35, v36, s46
	v_add3_u32 v33, v33, v37, s46
	v_and_b32_e32 v35, 0xffff0000, v35
	v_and_b32_e32 v36, 0xffff0000, v33
	v_or_b32_sdwa v33, v35, v34 dst_sel:DWORD dst_unused:UNUSED_PAD src0_sel:DWORD src1_sel:WORD_1
	v_or_b32_sdwa v32, v36, v32 dst_sel:DWORD dst_unused:UNUSED_PAD src0_sel:DWORD src1_sel:WORD_1
	global_store_dwordx2 v[52:53], v[32:33], off offset:32
	v_and_b32_sdwa v32, v30, v142 dst_sel:DWORD dst_unused:UNUSED_PAD src0_sel:WORD_1 src1_sel:DWORD
	v_and_b32_sdwa v33, v28, v142 dst_sel:DWORD dst_unused:UNUSED_PAD src0_sel:WORD_1 src1_sel:DWORD
	v_add3_u32 v28, v28, v33, s46
	v_add3_u32 v30, v30, v32, s46
	v_and_b32_sdwa v32, v31, v142 dst_sel:DWORD dst_unused:UNUSED_PAD src0_sel:WORD_1 src1_sel:DWORD
	v_and_b32_sdwa v33, v29, v142 dst_sel:DWORD dst_unused:UNUSED_PAD src0_sel:WORD_1 src1_sel:DWORD
	v_add3_u32 v31, v31, v32, s46
	v_add3_u32 v29, v29, v33, s46
	v_and_b32_e32 v31, 0xffff0000, v31
	v_and_b32_e32 v32, 0xffff0000, v29
	v_or_b32_sdwa v29, v31, v30 dst_sel:DWORD dst_unused:UNUSED_PAD src0_sel:DWORD src1_sel:WORD_1
	v_or_b32_sdwa v28, v32, v28 dst_sel:DWORD dst_unused:UNUSED_PAD src0_sel:DWORD src1_sel:WORD_1
	global_store_dwordx2 v[66:67], v[28:29], off offset:64
	v_and_b32_sdwa v28, v26, v142 dst_sel:DWORD dst_unused:UNUSED_PAD src0_sel:WORD_1 src1_sel:DWORD
	v_and_b32_sdwa v29, v24, v142 dst_sel:DWORD dst_unused:UNUSED_PAD src0_sel:WORD_1 src1_sel:DWORD
	v_add3_u32 v24, v24, v29, s46
	v_add3_u32 v26, v26, v28, s46
	v_and_b32_sdwa v28, v27, v142 dst_sel:DWORD dst_unused:UNUSED_PAD src0_sel:WORD_1 src1_sel:DWORD
	v_and_b32_sdwa v29, v25, v142 dst_sel:DWORD dst_unused:UNUSED_PAD src0_sel:WORD_1 src1_sel:DWORD
	v_add3_u32 v27, v27, v28, s46
	v_add3_u32 v25, v25, v29, s46
	v_and_b32_e32 v27, 0xffff0000, v27
	v_and_b32_e32 v28, 0xffff0000, v25
	v_or_b32_sdwa v25, v27, v26 dst_sel:DWORD dst_unused:UNUSED_PAD src0_sel:DWORD src1_sel:WORD_1
	v_or_b32_sdwa v24, v28, v24 dst_sel:DWORD dst_unused:UNUSED_PAD src0_sel:DWORD src1_sel:WORD_1
	global_store_dwordx2 v[60:61], v[24:25], off offset:64
	v_and_b32_sdwa v24, v22, v142 dst_sel:DWORD dst_unused:UNUSED_PAD src0_sel:WORD_1 src1_sel:DWORD
	v_and_b32_sdwa v25, v20, v142 dst_sel:DWORD dst_unused:UNUSED_PAD src0_sel:WORD_1 src1_sel:DWORD
	v_add3_u32 v20, v20, v25, s46
	v_add3_u32 v22, v22, v24, s46
	v_and_b32_sdwa v24, v23, v142 dst_sel:DWORD dst_unused:UNUSED_PAD src0_sel:WORD_1 src1_sel:DWORD
	v_and_b32_sdwa v25, v21, v142 dst_sel:DWORD dst_unused:UNUSED_PAD src0_sel:WORD_1 src1_sel:DWORD
	v_add3_u32 v23, v23, v24, s46
	v_add3_u32 v21, v21, v25, s46
	v_and_b32_e32 v23, 0xffff0000, v23
	v_and_b32_e32 v24, 0xffff0000, v21
	v_or_b32_sdwa v21, v23, v22 dst_sel:DWORD dst_unused:UNUSED_PAD src0_sel:DWORD src1_sel:WORD_1
	v_or_b32_sdwa v20, v24, v20 dst_sel:DWORD dst_unused:UNUSED_PAD src0_sel:DWORD src1_sel:WORD_1
	global_store_dwordx2 v[56:57], v[20:21], off offset:64
	v_and_b32_sdwa v20, v18, v142 dst_sel:DWORD dst_unused:UNUSED_PAD src0_sel:WORD_1 src1_sel:DWORD
	v_and_b32_sdwa v21, v16, v142 dst_sel:DWORD dst_unused:UNUSED_PAD src0_sel:WORD_1 src1_sel:DWORD
	v_add3_u32 v16, v16, v21, s46
	v_add3_u32 v18, v18, v20, s46
	v_and_b32_sdwa v20, v19, v142 dst_sel:DWORD dst_unused:UNUSED_PAD src0_sel:WORD_1 src1_sel:DWORD
	v_and_b32_sdwa v21, v17, v142 dst_sel:DWORD dst_unused:UNUSED_PAD src0_sel:WORD_1 src1_sel:DWORD
	v_add3_u32 v19, v19, v20, s46
	v_add3_u32 v17, v17, v21, s46
	v_and_b32_e32 v19, 0xffff0000, v19
	v_and_b32_e32 v20, 0xffff0000, v17
	v_or_b32_sdwa v17, v19, v18 dst_sel:DWORD dst_unused:UNUSED_PAD src0_sel:DWORD src1_sel:WORD_1
	v_or_b32_sdwa v16, v20, v16 dst_sel:DWORD dst_unused:UNUSED_PAD src0_sel:DWORD src1_sel:WORD_1
	global_store_dwordx2 v[52:53], v[16:17], off offset:64
	v_and_b32_sdwa v16, v14, v142 dst_sel:DWORD dst_unused:UNUSED_PAD src0_sel:WORD_1 src1_sel:DWORD
	v_and_b32_sdwa v17, v12, v142 dst_sel:DWORD dst_unused:UNUSED_PAD src0_sel:WORD_1 src1_sel:DWORD
	v_add3_u32 v12, v12, v17, s46
	v_add3_u32 v14, v14, v16, s46
	v_and_b32_sdwa v16, v15, v142 dst_sel:DWORD dst_unused:UNUSED_PAD src0_sel:WORD_1 src1_sel:DWORD
	v_and_b32_sdwa v17, v13, v142 dst_sel:DWORD dst_unused:UNUSED_PAD src0_sel:WORD_1 src1_sel:DWORD
	v_add3_u32 v15, v15, v16, s46
	v_add3_u32 v13, v13, v17, s46
	v_and_b32_e32 v15, 0xffff0000, v15
	v_and_b32_e32 v16, 0xffff0000, v13
	v_or_b32_sdwa v13, v15, v14 dst_sel:DWORD dst_unused:UNUSED_PAD src0_sel:DWORD src1_sel:WORD_1
	v_or_b32_sdwa v12, v16, v12 dst_sel:DWORD dst_unused:UNUSED_PAD src0_sel:DWORD src1_sel:WORD_1
	global_store_dwordx2 v[66:67], v[12:13], off offset:96
	v_and_b32_sdwa v12, v10, v142 dst_sel:DWORD dst_unused:UNUSED_PAD src0_sel:WORD_1 src1_sel:DWORD
	v_and_b32_sdwa v13, v8, v142 dst_sel:DWORD dst_unused:UNUSED_PAD src0_sel:WORD_1 src1_sel:DWORD
	v_add3_u32 v8, v8, v13, s46
	v_add3_u32 v10, v10, v12, s46
	v_and_b32_sdwa v12, v11, v142 dst_sel:DWORD dst_unused:UNUSED_PAD src0_sel:WORD_1 src1_sel:DWORD
	v_and_b32_sdwa v13, v9, v142 dst_sel:DWORD dst_unused:UNUSED_PAD src0_sel:WORD_1 src1_sel:DWORD
	v_add3_u32 v11, v11, v12, s46
	v_add3_u32 v9, v9, v13, s46
	v_and_b32_e32 v11, 0xffff0000, v11
	v_and_b32_e32 v12, 0xffff0000, v9
	v_or_b32_sdwa v9, v11, v10 dst_sel:DWORD dst_unused:UNUSED_PAD src0_sel:DWORD src1_sel:WORD_1
	v_or_b32_sdwa v8, v12, v8 dst_sel:DWORD dst_unused:UNUSED_PAD src0_sel:DWORD src1_sel:WORD_1
	global_store_dwordx2 v[60:61], v[8:9], off offset:96
	v_and_b32_sdwa v8, v6, v142 dst_sel:DWORD dst_unused:UNUSED_PAD src0_sel:WORD_1 src1_sel:DWORD
	v_and_b32_sdwa v9, v4, v142 dst_sel:DWORD dst_unused:UNUSED_PAD src0_sel:WORD_1 src1_sel:DWORD
	v_add3_u32 v4, v4, v9, s46
	v_add3_u32 v6, v6, v8, s46
	v_and_b32_sdwa v8, v7, v142 dst_sel:DWORD dst_unused:UNUSED_PAD src0_sel:WORD_1 src1_sel:DWORD
	v_and_b32_sdwa v9, v5, v142 dst_sel:DWORD dst_unused:UNUSED_PAD src0_sel:WORD_1 src1_sel:DWORD
	v_add3_u32 v7, v7, v8, s46
	v_add3_u32 v5, v5, v9, s46
	v_and_b32_e32 v7, 0xffff0000, v7
	v_and_b32_e32 v8, 0xffff0000, v5
	v_or_b32_sdwa v5, v7, v6 dst_sel:DWORD dst_unused:UNUSED_PAD src0_sel:DWORD src1_sel:WORD_1
	v_or_b32_sdwa v4, v8, v4 dst_sel:DWORD dst_unused:UNUSED_PAD src0_sel:DWORD src1_sel:WORD_1
	global_store_dwordx2 v[56:57], v[4:5], off offset:96
	v_and_b32_sdwa v4, v2, v142 dst_sel:DWORD dst_unused:UNUSED_PAD src0_sel:WORD_1 src1_sel:DWORD
	v_and_b32_sdwa v5, v0, v142 dst_sel:DWORD dst_unused:UNUSED_PAD src0_sel:WORD_1 src1_sel:DWORD
	v_add3_u32 v0, v0, v5, s46
	v_add3_u32 v2, v2, v4, s46
	v_and_b32_sdwa v4, v3, v142 dst_sel:DWORD dst_unused:UNUSED_PAD src0_sel:WORD_1 src1_sel:DWORD
	v_and_b32_sdwa v5, v1, v142 dst_sel:DWORD dst_unused:UNUSED_PAD src0_sel:WORD_1 src1_sel:DWORD
	v_add3_u32 v3, v3, v4, s46
	v_add3_u32 v1, v1, v5, s46
	v_and_b32_e32 v3, 0xffff0000, v3
	v_and_b32_e32 v4, 0xffff0000, v1
	v_or_b32_sdwa v1, v3, v2 dst_sel:DWORD dst_unused:UNUSED_PAD src0_sel:DWORD src1_sel:WORD_1
	v_or_b32_sdwa v0, v4, v0 dst_sel:DWORD dst_unused:UNUSED_PAD src0_sel:DWORD src1_sel:WORD_1
	global_store_dwordx2 v[52:53], v[0:1], off offset:96
	s_branch .LBB0_119

.LBB0_126:
	s_add_i32 s43, s5, 2
	s_mul_hi_i32 s44, s43, 0x55555556
	s_lshr_b32 s45, s44, 31
	s_add_i32 s44, s44, s45
	s_mul_i32 s44, s44, 3
	s_sub_i32 s43, s43, s44
	s_mulk_i32 s43, 0x6000
	s_mul_i32 s54, s5, 0x6000
	v_readfirstlane_b32 s55, v140
	v_lshl_add_u64 v[232:233], v[132:133], 0, s[2:3]
	v_lshl_add_u64 v[234:235], v[130:131], 0, s[2:3]
	s_add_u32 s55, s55, s43
	s_waitcnt vmcnt(6) lgkmcnt(0)
	s_barrier
	s_setprio 1
	s_mov_b32 m0, s55
	v_lshl_add_u64 v[236:237], v[232:233], 0, s[20:21]
	global_load_lds_dwordx4 v[236:237], off
	s_add_u32 m0, s55, 0x1000
	v_lshl_add_u64 v[236:237], v[232:233], 0, s[22:23]
	global_load_lds_dwordx4 v[236:237], off
	s_add_u32 m0, s55, 0x2000
	v_lshl_add_u64 v[236:237], v[232:233], 0, s[24:25]
	global_load_lds_dwordx4 v[236:237], off
	s_add_u32 m0, s55, 0x3000
	v_lshl_add_u64 v[236:237], v[232:233], 0, s[26:27]
	global_load_lds_dwordx4 v[236:237], off
	s_add_u32 m0, s55, 0x4000
	v_lshl_add_u64 v[236:237], v[234:235], 0, s[28:29]
	global_load_lds_dwordx4 v[236:237], off
	s_add_u32 m0, s55, 0x5000
	v_lshl_add_u64 v[236:237], v[234:235], 0, s[30:31]
	global_load_lds_dwordx4 v[236:237], off
	v_or_b32_e32 v128, s54, v138
	v_add3_u32 v128, v128, v139, v137
	ds_read_b128 v[176:179], v128 offset:16384
	ds_read_b128 v[180:183], v128 offset:16640
	ds_read_b128 v[184:187], v128 offset:18432
	ds_read_b128 v[192:195], v128 offset:18688
	v_add3_u32 v128, s54, v141, v137
	ds_read_b128 v[144:147], v128
	ds_read_b128 v[148:151], v128 offset:1024
	ds_read_b128 v[152:155], v128 offset:2048
	ds_read_b128 v[156:159], v128 offset:3072
	ds_read_b128 v[160:163], v128 offset:4096
	ds_read_b128 v[164:167], v128 offset:5120
	ds_read_b128 v[168:171], v128 offset:6144
	ds_read_b128 v[172:175], v128 offset:7168
	s_setprio 0
	s_waitcnt lgkmcnt(7)
	v_mfma_f32_16x16x32_bf16 v[124:127], v[176:179], v[144:147], v[124:127]
	v_mfma_f32_16x16x32_bf16 v[120:123], v[180:183], v[144:147], v[120:123]
	v_mfma_f32_16x16x32_bf16 v[116:119], v[184:187], v[144:147], v[116:119]
	v_mfma_f32_16x16x32_bf16 v[112:115], v[192:195], v[144:147], v[112:115]
	s_waitcnt lgkmcnt(6)
	v_mfma_f32_16x16x32_bf16 v[108:111], v[176:179], v[148:151], v[108:111]
	v_mfma_f32_16x16x32_bf16 v[104:107], v[180:183], v[148:151], v[104:107]
	v_mfma_f32_16x16x32_bf16 v[100:103], v[184:187], v[148:151], v[100:103]
	v_mfma_f32_16x16x32_bf16 v[96:99], v[192:195], v[148:151], v[96:99]
	s_waitcnt lgkmcnt(5)
	v_mfma_f32_16x16x32_bf16 v[92:95], v[176:179], v[152:155], v[92:95]
	v_mfma_f32_16x16x32_bf16 v[88:91], v[180:183], v[152:155], v[88:91]
	v_mfma_f32_16x16x32_bf16 v[84:87], v[184:187], v[152:155], v[84:87]
	v_mfma_f32_16x16x32_bf16 v[80:83], v[192:195], v[152:155], v[80:83]
	s_waitcnt lgkmcnt(4)
	v_mfma_f32_16x16x32_bf16 v[76:79], v[176:179], v[156:159], v[76:79]
	v_mfma_f32_16x16x32_bf16 v[72:75], v[180:183], v[156:159], v[72:75]
	v_mfma_f32_16x16x32_bf16 v[68:71], v[184:187], v[156:159], v[68:71]
	v_mfma_f32_16x16x32_bf16 v[64:67], v[192:195], v[156:159], v[64:67]
	s_waitcnt lgkmcnt(3)
	v_mfma_f32_16x16x32_bf16 v[60:63], v[176:179], v[160:163], v[60:63]
	v_mfma_f32_16x16x32_bf16 v[56:59], v[180:183], v[160:163], v[56:59]
	v_mfma_f32_16x16x32_bf16 v[52:55], v[184:187], v[160:163], v[52:55]
	v_mfma_f32_16x16x32_bf16 v[48:51], v[192:195], v[160:163], v[48:51]
	s_waitcnt lgkmcnt(2)
	v_mfma_f32_16x16x32_bf16 v[44:47], v[176:179], v[164:167], v[44:47]
	v_mfma_f32_16x16x32_bf16 v[40:43], v[180:183], v[164:167], v[40:43]
	v_mfma_f32_16x16x32_bf16 v[36:39], v[184:187], v[164:167], v[36:39]
	v_mfma_f32_16x16x32_bf16 v[32:35], v[192:195], v[164:167], v[32:35]
	s_waitcnt lgkmcnt(1)
	v_mfma_f32_16x16x32_bf16 v[28:31], v[176:179], v[168:171], v[28:31]
	v_mfma_f32_16x16x32_bf16 v[24:27], v[180:183], v[168:171], v[24:27]
	v_mfma_f32_16x16x32_bf16 v[20:23], v[184:187], v[168:171], v[20:23]
	v_mfma_f32_16x16x32_bf16 v[16:19], v[192:195], v[168:171], v[16:19]
	s_waitcnt lgkmcnt(0)
	v_mfma_f32_16x16x32_bf16 v[12:15], v[176:179], v[172:175], v[12:15]
	v_mfma_f32_16x16x32_bf16 v[8:11], v[180:183], v[172:175], v[8:11]
	v_mfma_f32_16x16x32_bf16 v[4:7], v[184:187], v[172:175], v[4:7]
	v_mfma_f32_16x16x32_bf16 v[0:3], v[192:195], v[172:175], v[0:3]
	s_add_i32 s43, s5, 1
	s_cmp_lg_u32 s5, 2
	s_cselect_b32 s5, s43, 0
	s_add_u32 s2, s2, 0x80
	s_addc_u32 s3, s3, 0
	s_cmpk_eq_i32 s2, 0xf00
	s_cbranch_scc0 .LBB0_126
	s_waitcnt vmcnt(6) lgkmcnt(0)
	s_barrier
	v_add_u32_e32 v128, v141, v137
	ds_read_b128 v[130:133], v128
	ds_read_b128 v[144:147], v128 offset:1024
	ds_read_b128 v[148:151], v128 offset:2048
	ds_read_b128 v[152:155], v128 offset:3072
	ds_read_b128 v[156:159], v128 offset:4096
	ds_read_b128 v[160:163], v128 offset:5120
	ds_read_b128 v[164:167], v128 offset:6144
	ds_read_b128 v[168:171], v128 offset:7168
	v_add3_u32 v137, v138, v139, v137
	ds_read_b128 v[138:141], v137 offset:16384
	ds_read_b128 v[172:175], v137 offset:16640
	ds_read_b128 v[176:179], v137 offset:18432
	ds_read_b128 v[180:183], v137 offset:18688
	s_setprio 1
	s_waitcnt lgkmcnt(0)
	v_mfma_f32_16x16x32_bf16 v[124:127], v[138:141], v[130:133], v[124:127]
	v_mfma_f32_16x16x32_bf16 v[184:187], v[172:175], v[130:133], v[120:123]
	v_mfma_f32_16x16x32_bf16 v[116:119], v[176:179], v[130:133], v[116:119]
	v_mfma_f32_16x16x32_bf16 v[130:133], v[180:183], v[130:133], v[112:115]
	v_mfma_f32_16x16x32_bf16 v[108:111], v[138:141], v[144:147], v[108:111]
	v_mfma_f32_16x16x32_bf16 v[100:103], v[176:179], v[144:147], v[100:103]
	v_mfma_f32_16x16x32_bf16 v[92:95], v[138:141], v[148:151], v[92:95]
	v_mfma_f32_16x16x32_bf16 v[84:87], v[176:179], v[148:151], v[84:87]
	v_mfma_f32_16x16x32_bf16 v[76:79], v[138:141], v[152:155], v[76:79]
	v_mfma_f32_16x16x32_bf16 v[68:71], v[176:179], v[152:155], v[68:71]
	v_mfma_f32_16x16x32_bf16 v[60:63], v[138:141], v[156:159], v[60:63]
	v_mfma_f32_16x16x32_bf16 v[52:55], v[176:179], v[156:159], v[52:55]
	v_mfma_f32_16x16x32_bf16 v[44:47], v[138:141], v[160:163], v[44:47]
	v_mfma_f32_16x16x32_bf16 v[36:39], v[176:179], v[160:163], v[36:39]
	v_mfma_f32_16x16x32_bf16 v[28:31], v[138:141], v[164:167], v[28:31]
	v_mfma_f32_16x16x32_bf16 v[20:23], v[176:179], v[164:167], v[20:23]
	v_mfma_f32_16x16x32_bf16 v[12:15], v[138:141], v[168:171], v[12:15]
	v_mfma_f32_16x16x32_bf16 v[138:141], v[172:175], v[168:171], v[8:11]
	v_mfma_f32_16x16x32_bf16 v[4:7], v[176:179], v[168:171], v[4:7]
	v_mfma_f32_16x16x32_bf16 v[192:195], v[172:175], v[144:147], v[104:107]
	v_mfma_f32_16x16x32_bf16 v[144:147], v[180:183], v[144:147], v[96:99]
	v_mfma_f32_16x16x32_bf16 v[196:199], v[172:175], v[148:151], v[88:91]
	v_mfma_f32_16x16x32_bf16 v[148:151], v[180:183], v[148:151], v[80:83]
	v_mfma_f32_16x16x32_bf16 v[200:203], v[172:175], v[152:155], v[72:75]
	v_mfma_f32_16x16x32_bf16 v[152:155], v[180:183], v[152:155], v[64:67]
	v_mfma_f32_16x16x32_bf16 v[204:207], v[172:175], v[156:159], v[56:59]
	v_mfma_f32_16x16x32_bf16 v[156:159], v[180:183], v[156:159], v[48:51]
	v_mfma_f32_16x16x32_bf16 v[208:211], v[172:175], v[160:163], v[40:43]
	v_mfma_f32_16x16x32_bf16 v[160:163], v[180:183], v[160:163], v[32:35]
	v_mfma_f32_16x16x32_bf16 v[212:215], v[172:175], v[164:167], v[24:27]
	v_mfma_f32_16x16x32_bf16 v[164:167], v[180:183], v[164:167], v[16:19]
	v_mfma_f32_16x16x32_bf16 v[168:171], v[180:183], v[168:171], v[0:3]
	s_setprio 0
	s_waitcnt vmcnt(0) lgkmcnt(0)
	s_barrier
	s_nop 1
	ds_read_b128 v[0:3], v128 offset:24576
	ds_read_b128 v[8:11], v128 offset:25600
	ds_read_b128 v[16:19], v128 offset:26624
	ds_read_b128 v[24:27], v128 offset:27648
	ds_read_b128 v[32:35], v128 offset:28672
	ds_read_b128 v[172:175], v128 offset:29696
	ds_read_b128 v[176:179], v128 offset:30720
	ds_read_b128 v[180:183], v128 offset:31744
	ds_read_b128 v[216:219], v137 offset:40960
	ds_read_b128 v[220:223], v137 offset:41216
	ds_read_b128 v[224:227], v137 offset:43008
	ds_read_b128 v[228:231], v137 offset:43264
	s_setprio 1
	s_waitcnt lgkmcnt(0)
	v_mfma_f32_16x16x32_bf16 v[120:123], v[216:219], v[0:3], v[124:127]
	v_mfma_f32_16x16x32_bf16 v[124:127], v[220:223], v[0:3], v[184:187]
	v_mfma_f32_16x16x32_bf16 v[112:115], v[224:227], v[0:3], v[116:119]
	v_mfma_f32_16x16x32_bf16 v[116:119], v[228:231], v[0:3], v[130:133]
	v_mfma_f32_16x16x32_bf16 v[104:107], v[216:219], v[8:11], v[108:111]
	v_mfma_f32_16x16x32_bf16 v[108:111], v[220:223], v[8:11], v[192:195]
	v_mfma_f32_16x16x32_bf16 v[96:99], v[224:227], v[8:11], v[100:103]
	v_mfma_f32_16x16x32_bf16 v[100:103], v[228:231], v[8:11], v[144:147]
	v_mfma_f32_16x16x32_bf16 v[88:91], v[216:219], v[16:19], v[92:95]
	v_mfma_f32_16x16x32_bf16 v[92:95], v[220:223], v[16:19], v[196:199]
	v_mfma_f32_16x16x32_bf16 v[80:83], v[224:227], v[16:19], v[84:87]
	v_mfma_f32_16x16x32_bf16 v[84:87], v[228:231], v[16:19], v[148:151]
	v_mfma_f32_16x16x32_bf16 v[72:75], v[216:219], v[24:27], v[76:79]
	v_mfma_f32_16x16x32_bf16 v[76:79], v[220:223], v[24:27], v[200:203]
	v_mfma_f32_16x16x32_bf16 v[64:67], v[224:227], v[24:27], v[68:71]
	v_mfma_f32_16x16x32_bf16 v[68:71], v[228:231], v[24:27], v[152:155]
	v_mfma_f32_16x16x32_bf16 v[56:59], v[216:219], v[32:35], v[60:63]
	v_mfma_f32_16x16x32_bf16 v[60:63], v[220:223], v[32:35], v[204:207]
	v_mfma_f32_16x16x32_bf16 v[48:51], v[224:227], v[32:35], v[52:55]
	v_mfma_f32_16x16x32_bf16 v[52:55], v[228:231], v[32:35], v[156:159]
	v_mfma_f32_16x16x32_bf16 v[40:43], v[216:219], v[172:175], v[44:47]
	v_mfma_f32_16x16x32_bf16 v[44:47], v[220:223], v[172:175], v[208:211]
	v_mfma_f32_16x16x32_bf16 v[32:35], v[224:227], v[172:175], v[36:39]
	v_mfma_f32_16x16x32_bf16 v[36:39], v[228:231], v[172:175], v[160:163]
	v_mfma_f32_16x16x32_bf16 v[24:27], v[216:219], v[176:179], v[28:31]
	v_mfma_f32_16x16x32_bf16 v[28:31], v[220:223], v[176:179], v[212:215]
	v_mfma_f32_16x16x32_bf16 v[16:19], v[224:227], v[176:179], v[20:23]
	v_mfma_f32_16x16x32_bf16 v[20:23], v[228:231], v[176:179], v[164:167]
	v_mfma_f32_16x16x32_bf16 v[8:11], v[216:219], v[180:183], v[12:15]
	v_mfma_f32_16x16x32_bf16 v[12:15], v[220:223], v[180:183], v[138:141]
	v_mfma_f32_16x16x32_bf16 v[0:3], v[224:227], v[180:183], v[4:7]
	v_mfma_f32_16x16x32_bf16 v[4:7], v[228:231], v[180:183], v[168:171]
	s_setprio 0
	v_and_b32_e32 v128, 0xffffff80, v134
	v_add_u32_e32 v128, s42, v128
	v_or_b32_e32 v132, v128, v135
	v_lshrrev_b32_e32 v130, 1, v134
	v_lshlrev_b32_e32 v128, 6, v136
	v_and_b32_e32 v130, 24, v130
	v_ashrrev_i32_e32 v133, 31, v132
	v_readlane_b32 s2, v254, 62
	v_or3_b32 v128, v128, v130, s4
	v_lshlrev_b64 v[130:131], 11, v[132:133]
	v_readlane_b32 s3, v254, 63
	s_nop 1
	v_lshl_add_u64 v[136:137], s[2:3], 0, v[130:131]
	v_lshlrev_b64 v[130:131], 10, v[132:133]
	v_lshl_add_u64 v[134:135], s[96:97], 0, v[130:131]
	v_cmp_lt_i32_e64 s[2:3], s48, v128
	s_and_saveexec_b64 s[4:5], s[2:3]
	s_xor_b64 s[4:5], exec, s[4:5]
	s_cbranch_execz .LBB0_132
	s_cmpk_gt_u32 s33, 0x3ff
	s_mov_b64 s[42:43], -1
	s_cbranch_scc0 .LBB0_130
	v_lshl_add_u64 v[138:139], v[128:129], 1, v[136:137]
	v_lshl_add_u64 v[138:139], v[138:139], 0, s[34:35]
	s_mov_b64 s[42:43], 0

.LBB0_823:
	s_add_i32 s15, s14, 2
	s_mul_hi_i32 s16, s15, 0x55555556
	s_lshr_b32 s17, s16, 31
	s_add_i32 s16, s16, s17
	s_mul_i32 s16, s16, 3
	s_sub_i32 s15, s15, s16
	s_mulk_i32 s15, 0x6000
	s_mul_i32 s54, s14, 0x6000
	v_readfirstlane_b32 s55, v140
	v_lshl_add_u64 v[232:233], v[132:133], 0, s[4:5]
	v_lshl_add_u64 v[234:235], v[130:131], 0, s[4:5]
	s_add_u32 s55, s55, s15
	s_waitcnt vmcnt(6) lgkmcnt(0)
	s_barrier
	s_setprio 1
	s_mov_b32 m0, s55
	s_mov_b64 s[16:17], 0xa510080
	v_lshl_add_u64 v[236:237], v[232:233], 0, s[16:17]
	global_load_lds_dwordx4 v[236:237], off
	s_add_u32 m0, s55, 0x1000
	s_mov_b64 s[16:17], 0xa530080
	v_lshl_add_u64 v[236:237], v[232:233], 0, s[16:17]
	global_load_lds_dwordx4 v[236:237], off
	s_add_u32 m0, s55, 0x2000
	s_mov_b64 s[16:17], 0xa550080
	v_lshl_add_u64 v[236:237], v[232:233], 0, s[16:17]
	global_load_lds_dwordx4 v[236:237], off
	s_add_u32 m0, s55, 0x3000
	s_mov_b64 s[16:17], 0xa570080
	v_lshl_add_u64 v[236:237], v[232:233], 0, s[16:17]
	global_load_lds_dwordx4 v[236:237], off
	s_add_u32 m0, s55, 0x4000
	s_mov_b64 s[16:17], 0xa40080
	v_lshl_add_u64 v[236:237], v[234:235], 0, s[16:17]
	global_load_lds_dwordx4 v[236:237], off
	s_add_u32 m0, s55, 0x5000
	s_mov_b64 s[16:17], 0xa60080
	v_lshl_add_u64 v[236:237], v[234:235], 0, s[16:17]
	global_load_lds_dwordx4 v[236:237], off
	v_or_b32_e32 v128, s54, v138
	v_add3_u32 v128, v128, v139, v137
	ds_read_b128 v[174:177], v128 offset:16384
	ds_read_b128 v[178:181], v128 offset:16640
	ds_read_b128 v[182:185], v128 offset:18432
	ds_read_b128 v[186:189], v128 offset:18688
	v_add3_u32 v128, s54, v141, v137
	ds_read_b128 v[142:145], v128
	ds_read_b128 v[146:149], v128 offset:1024
	ds_read_b128 v[150:153], v128 offset:2048
	ds_read_b128 v[154:157], v128 offset:3072
	ds_read_b128 v[158:161], v128 offset:4096
	ds_read_b128 v[162:165], v128 offset:5120
	ds_read_b128 v[166:169], v128 offset:6144
	ds_read_b128 v[170:173], v128 offset:7168
	s_setprio 0
	s_waitcnt lgkmcnt(7)
	v_mfma_f32_16x16x32_bf16 v[124:127], v[174:177], v[142:145], v[124:127]
	v_mfma_f32_16x16x32_bf16 v[120:123], v[178:181], v[142:145], v[120:123]
	v_mfma_f32_16x16x32_bf16 v[116:119], v[182:185], v[142:145], v[116:119]
	v_mfma_f32_16x16x32_bf16 v[112:115], v[186:189], v[142:145], v[112:115]
	s_waitcnt lgkmcnt(6)
	v_mfma_f32_16x16x32_bf16 v[108:111], v[174:177], v[146:149], v[108:111]
	v_mfma_f32_16x16x32_bf16 v[104:107], v[178:181], v[146:149], v[104:107]
	v_mfma_f32_16x16x32_bf16 v[100:103], v[182:185], v[146:149], v[100:103]
	v_mfma_f32_16x16x32_bf16 v[96:99], v[186:189], v[146:149], v[96:99]
	s_waitcnt lgkmcnt(5)
	v_mfma_f32_16x16x32_bf16 v[92:95], v[174:177], v[150:153], v[92:95]
	v_mfma_f32_16x16x32_bf16 v[88:91], v[178:181], v[150:153], v[88:91]
	v_mfma_f32_16x16x32_bf16 v[84:87], v[182:185], v[150:153], v[84:87]
	v_mfma_f32_16x16x32_bf16 v[80:83], v[186:189], v[150:153], v[80:83]
	s_waitcnt lgkmcnt(4)
	v_mfma_f32_16x16x32_bf16 v[76:79], v[174:177], v[154:157], v[76:79]
	v_mfma_f32_16x16x32_bf16 v[72:75], v[178:181], v[154:157], v[72:75]
	v_mfma_f32_16x16x32_bf16 v[68:71], v[182:185], v[154:157], v[68:71]
	v_mfma_f32_16x16x32_bf16 v[64:67], v[186:189], v[154:157], v[64:67]
	s_waitcnt lgkmcnt(3)
	v_mfma_f32_16x16x32_bf16 v[60:63], v[174:177], v[158:161], v[60:63]
	v_mfma_f32_16x16x32_bf16 v[56:59], v[178:181], v[158:161], v[56:59]
	v_mfma_f32_16x16x32_bf16 v[52:55], v[182:185], v[158:161], v[52:55]
	v_mfma_f32_16x16x32_bf16 v[48:51], v[186:189], v[158:161], v[48:51]
	s_waitcnt lgkmcnt(2)
	v_mfma_f32_16x16x32_bf16 v[44:47], v[174:177], v[162:165], v[44:47]
	v_mfma_f32_16x16x32_bf16 v[40:43], v[178:181], v[162:165], v[40:43]
	v_mfma_f32_16x16x32_bf16 v[36:39], v[182:185], v[162:165], v[36:39]
	v_mfma_f32_16x16x32_bf16 v[32:35], v[186:189], v[162:165], v[32:35]
	s_waitcnt lgkmcnt(1)
	v_mfma_f32_16x16x32_bf16 v[28:31], v[174:177], v[166:169], v[28:31]
	v_mfma_f32_16x16x32_bf16 v[24:27], v[178:181], v[166:169], v[24:27]
	v_mfma_f32_16x16x32_bf16 v[20:23], v[182:185], v[166:169], v[20:23]
	v_mfma_f32_16x16x32_bf16 v[16:19], v[186:189], v[166:169], v[16:19]
	s_waitcnt lgkmcnt(0)
	v_mfma_f32_16x16x32_bf16 v[12:15], v[174:177], v[170:173], v[12:15]
	v_mfma_f32_16x16x32_bf16 v[8:11], v[178:181], v[170:173], v[8:11]
	v_mfma_f32_16x16x32_bf16 v[4:7], v[182:185], v[170:173], v[4:7]
	v_mfma_f32_16x16x32_bf16 v[0:3], v[186:189], v[170:173], v[0:3]
	s_add_i32 s15, s14, 1
	s_cmp_lg_u32 s14, 2
	s_cselect_b32 s14, s15, 0
	s_add_u32 s4, s4, 64
	s_addc_u32 s5, s5, 0
	s_cmpk_eq_i32 s4, 0x780
	s_cbranch_scc0 .LBB0_823
	s_waitcnt vmcnt(6) lgkmcnt(0)
	s_barrier
	v_add_u32_e32 v128, v141, v137
	ds_read_b128 v[130:133], v128
	ds_read_b128 v[140:143], v128 offset:1024
	ds_read_b128 v[144:147], v128 offset:2048
	ds_read_b128 v[148:151], v128 offset:3072
	ds_read_b128 v[152:155], v128 offset:4096
	ds_read_b128 v[156:159], v128 offset:5120
	ds_read_b128 v[160:163], v128 offset:6144
	ds_read_b128 v[164:167], v128 offset:7168
	v_add3_u32 v137, v138, v139, v137
	ds_read_b128 v[168:171], v137 offset:16384
	ds_read_b128 v[172:175], v137 offset:16640
	ds_read_b128 v[176:179], v137 offset:18432
	ds_read_b128 v[180:183], v137 offset:18688
	s_setprio 1
	s_waitcnt lgkmcnt(0)
	v_mfma_f32_16x16x32_bf16 v[124:127], v[168:171], v[130:133], v[124:127]
	v_mfma_f32_16x16x32_bf16 v[120:123], v[172:175], v[130:133], v[120:123]
	v_mfma_f32_16x16x32_bf16 v[116:119], v[176:179], v[130:133], v[116:119]
	v_mfma_f32_16x16x32_bf16 v[112:115], v[180:183], v[130:133], v[112:115]
	v_mfma_f32_16x16x32_bf16 v[108:111], v[168:171], v[140:143], v[108:111]
	v_mfma_f32_16x16x32_bf16 v[104:107], v[172:175], v[140:143], v[104:107]
	v_mfma_f32_16x16x32_bf16 v[100:103], v[176:179], v[140:143], v[100:103]
	v_mfma_f32_16x16x32_bf16 v[96:99], v[180:183], v[140:143], v[96:99]
	v_mfma_f32_16x16x32_bf16 v[92:95], v[168:171], v[144:147], v[92:95]
	v_mfma_f32_16x16x32_bf16 v[88:91], v[172:175], v[144:147], v[88:91]
	v_mfma_f32_16x16x32_bf16 v[84:87], v[176:179], v[144:147], v[84:87]
	v_mfma_f32_16x16x32_bf16 v[80:83], v[180:183], v[144:147], v[80:83]
	v_mfma_f32_16x16x32_bf16 v[76:79], v[168:171], v[148:151], v[76:79]
	v_mfma_f32_16x16x32_bf16 v[72:75], v[172:175], v[148:151], v[72:75]
	v_mfma_f32_16x16x32_bf16 v[68:71], v[176:179], v[148:151], v[68:71]
	v_mfma_f32_16x16x32_bf16 v[64:67], v[180:183], v[148:151], v[64:67]
	v_mfma_f32_16x16x32_bf16 v[60:63], v[168:171], v[152:155], v[60:63]
	v_mfma_f32_16x16x32_bf16 v[56:59], v[172:175], v[152:155], v[56:59]
	v_mfma_f32_16x16x32_bf16 v[52:55], v[176:179], v[152:155], v[52:55]
	v_mfma_f32_16x16x32_bf16 v[48:51], v[180:183], v[152:155], v[48:51]
	v_mfma_f32_16x16x32_bf16 v[44:47], v[168:171], v[156:159], v[44:47]
	v_mfma_f32_16x16x32_bf16 v[40:43], v[172:175], v[156:159], v[40:43]
	v_mfma_f32_16x16x32_bf16 v[36:39], v[176:179], v[156:159], v[36:39]
	v_mfma_f32_16x16x32_bf16 v[32:35], v[180:183], v[156:159], v[32:35]
	v_mfma_f32_16x16x32_bf16 v[28:31], v[168:171], v[160:163], v[28:31]
	v_mfma_f32_16x16x32_bf16 v[24:27], v[172:175], v[160:163], v[24:27]
	v_mfma_f32_16x16x32_bf16 v[20:23], v[176:179], v[160:163], v[20:23]
	v_mfma_f32_16x16x32_bf16 v[16:19], v[180:183], v[160:163], v[16:19]
	v_mfma_f32_16x16x32_bf16 v[12:15], v[168:171], v[164:167], v[12:15]
	v_mfma_f32_16x16x32_bf16 v[8:11], v[172:175], v[164:167], v[8:11]
	v_mfma_f32_16x16x32_bf16 v[4:7], v[176:179], v[164:167], v[4:7]
	v_mfma_f32_16x16x32_bf16 v[0:3], v[180:183], v[164:167], v[0:3]
	s_setprio 0
	s_waitcnt vmcnt(0) lgkmcnt(0)
	s_barrier
	ds_read_b128 v[130:133], v128 offset:24576
	ds_read_b128 v[138:141], v128 offset:25600
	ds_read_b128 v[142:145], v128 offset:26624
	ds_read_b128 v[146:149], v128 offset:27648
	ds_read_b128 v[150:153], v128 offset:28672
	ds_read_b128 v[154:157], v128 offset:29696
	ds_read_b128 v[158:161], v128 offset:30720
	ds_read_b128 v[162:165], v128 offset:31744
	ds_read_b128 v[166:169], v137 offset:40960
	ds_read_b128 v[170:173], v137 offset:41216
	ds_read_b128 v[174:177], v137 offset:43008
	ds_read_b128 v[178:181], v137 offset:43264
	s_setprio 1
	s_waitcnt lgkmcnt(0)
	v_mfma_f32_16x16x32_bf16 v[124:127], v[166:169], v[130:133], v[124:127]
	v_mfma_f32_16x16x32_bf16 v[120:123], v[170:173], v[130:133], v[120:123]
	v_mfma_f32_16x16x32_bf16 v[116:119], v[174:177], v[130:133], v[116:119]
	v_mfma_f32_16x16x32_bf16 v[112:115], v[178:181], v[130:133], v[112:115]
	v_mfma_f32_16x16x32_bf16 v[108:111], v[166:169], v[138:141], v[108:111]
	v_mfma_f32_16x16x32_bf16 v[104:107], v[170:173], v[138:141], v[104:107]
	v_mfma_f32_16x16x32_bf16 v[130:133], v[174:177], v[138:141], v[100:103]
	v_mfma_f32_16x16x32_bf16 v[96:99], v[178:181], v[138:141], v[96:99]
	v_mfma_f32_16x16x32_bf16 v[92:95], v[166:169], v[142:145], v[92:95]
	v_mfma_f32_16x16x32_bf16 v[88:91], v[170:173], v[142:145], v[88:91]
	v_mfma_f32_16x16x32_bf16 v[84:87], v[174:177], v[142:145], v[84:87]
	v_mfma_f32_16x16x32_bf16 v[80:83], v[178:181], v[142:145], v[80:83]
	v_mfma_f32_16x16x32_bf16 v[76:79], v[166:169], v[146:149], v[76:79]
	v_mfma_f32_16x16x32_bf16 v[72:75], v[170:173], v[146:149], v[72:75]
	v_mfma_f32_16x16x32_bf16 v[68:71], v[174:177], v[146:149], v[68:71]
	v_mfma_f32_16x16x32_bf16 v[64:67], v[178:181], v[146:149], v[64:67]
	v_mfma_f32_16x16x32_bf16 v[60:63], v[166:169], v[150:153], v[60:63]
	v_mfma_f32_16x16x32_bf16 v[56:59], v[170:173], v[150:153], v[56:59]
	v_mfma_f32_16x16x32_bf16 v[52:55], v[174:177], v[150:153], v[52:55]
	v_mfma_f32_16x16x32_bf16 v[48:51], v[178:181], v[150:153], v[48:51]
	v_mfma_f32_16x16x32_bf16 v[44:47], v[166:169], v[154:157], v[44:47]
	v_mfma_f32_16x16x32_bf16 v[40:43], v[170:173], v[154:157], v[40:43]
	v_mfma_f32_16x16x32_bf16 v[36:39], v[174:177], v[154:157], v[36:39]
	v_mfma_f32_16x16x32_bf16 v[32:35], v[178:181], v[154:157], v[32:35]
	v_mfma_f32_16x16x32_bf16 v[28:31], v[166:169], v[158:161], v[28:31]
	v_mfma_f32_16x16x32_bf16 v[24:27], v[170:173], v[158:161], v[24:27]
	v_mfma_f32_16x16x32_bf16 v[20:23], v[174:177], v[158:161], v[20:23]
	v_mfma_f32_16x16x32_bf16 v[16:19], v[178:181], v[158:161], v[16:19]
	v_mfma_f32_16x16x32_bf16 v[12:15], v[166:169], v[162:165], v[12:15]
	v_mfma_f32_16x16x32_bf16 v[8:11], v[170:173], v[162:165], v[8:11]
	v_mfma_f32_16x16x32_bf16 v[4:7], v[174:177], v[162:165], v[4:7]
	v_mfma_f32_16x16x32_bf16 v[0:3], v[178:181], v[162:165], v[0:3]
	s_setprio 0
	v_and_b32_e32 v100, 0xffffff80, v134
	v_lshrrev_b32_e32 v102, 1, v134
	v_add_u32_e32 v100, s12, v100
	v_lshlrev_b32_e32 v101, 6, v136
	v_and_b32_e32 v102, 24, v102
	v_or_b32_e32 v100, v100, v135
	v_or3_b32 v102, v101, v102, s13
	v_mov_b32_e32 v101, v129
	v_add_u32_e32 v128, 0xffffc000, v100
	v_readlane_b32 s12, v254, 2
	v_lshlrev_b64 v[138:139], 12, v[100:101]
	v_ashrrev_i32_e32 v101, 31, v100
	v_lshlrev_b64 v[134:135], 12, v[128:129]
	v_readlane_b32 s13, v254, 3
	v_readlane_b32 s14, v254, 4
	v_readlane_b32 s15, v254, 5
	v_lshlrev_b64 v[140:141], 12, v[100:101]
	v_lshl_add_u64 v[136:137], s[12:13], 0, v[140:141]
	v_lshl_add_u64 v[134:135], s[14:15], 0, v[134:135]
	v_cmp_gt_i32_e32 vcc, s10, v100
	v_ashrrev_i32_e32 v103, 31, v102
	v_lshlrev_b64 v[102:103], 2, v[102:103]
	v_cndmask_b32_e32 v135, v135, v137, vcc
	v_cndmask_b32_e32 v134, v134, v136, vcc
	v_lshl_add_u64 v[142:143], v[134:135], 0, v[102:103]
	global_load_dwordx4 v[134:137], v[142:143], off
	v_readlane_b32 s16, v254, 6
	v_readlane_b32 s17, v254, 7
	v_readlane_b32 s18, v254, 8
	v_readlane_b32 s19, v254, 9
	v_readlane_b32 s20, v254, 10
	v_readlane_b32 s21, v254, 11
	v_readlane_b32 s22, v254, 12
	v_readlane_b32 s23, v254, 13
	v_readlane_b32 s24, v254, 14
	v_readlane_b32 s25, v254, 15
	v_readlane_b32 s26, v254, 16
	v_readlane_b32 s27, v254, 17
	v_readlane_b32 s16, v254, 34
	v_cndmask_b32_e32 v139, v139, v141, vcc
	v_cndmask_b32_e32 v138, v138, v140, vcc
	v_readlane_b32 s30, v254, 48
	v_readlane_b32 s31, v254, 49
	v_add_u32_e32 v128, 0xffffc010, v100
	s_add_i32 s11, s11, s86
	v_lshl_add_u64 v[138:139], s[30:31], 0, v[138:139]
	v_lshl_add_u64 v[138:139], v[138:139], 0, v[102:103]
	s_add_i32 s6, s6, s7
	s_add_i32 s8, s8, s9
	s_cmpk_gt_i32 s11, 0x1ff
	v_readlane_b32 s17, v254, 35
	v_readlane_b32 s18, v254, 36
	v_readlane_b32 s19, v254, 37
	v_readlane_b32 s20, v254, 38
	v_readlane_b32 s21, v254, 39
	v_readlane_b32 s22, v254, 40
	v_readlane_b32 s23, v254, 41
	v_readlane_b32 s24, v254, 42
	v_readlane_b32 s25, v254, 43
	v_readlane_b32 s26, v254, 44
	v_readlane_b32 s27, v254, 45
	v_readlane_b32 s28, v254, 46
	v_readlane_b32 s29, v254, 47
	s_waitcnt vmcnt(0)
	v_pk_add_f32 v[124:125], v[124:125], v[134:135]
	v_pk_add_f32 v[126:127], v[126:127], v[136:137]
	global_store_dwordx4 v[138:139], v[124:127], off
	global_load_dwordx4 v[124:127], v[142:143], off offset:16
	s_waitcnt vmcnt(0)
	v_pk_add_f32 v[120:121], v[120:121], v[124:125]
	v_pk_add_f32 v[122:123], v[122:123], v[126:127]
	global_store_dwordx4 v[138:139], v[120:123], off offset:16
	global_load_dwordx4 v[120:123], v[142:143], off offset:128
	v_lshlrev_b64 v[124:125], 12, v[128:129]
	v_lshl_add_u64 v[124:125], s[14:15], 0, v[124:125]
	v_add_u32_e32 v128, 0xffffc020, v100
	s_waitcnt vmcnt(0)
	v_pk_add_f32 v[116:117], v[116:117], v[120:121]
	v_pk_add_f32 v[118:119], v[118:119], v[122:123]
	global_store_dwordx4 v[138:139], v[116:119], off offset:128
	global_load_dwordx4 v[116:119], v[142:143], off offset:144
	v_mov_b32_e32 v121, v129
	v_or_b32_e32 v120, 16, v100
	v_lshlrev_b64 v[122:123], 12, v[120:121]
	v_ashrrev_i32_e32 v121, 31, v120
	v_lshlrev_b64 v[126:127], 12, v[120:121]
	v_lshl_add_u64 v[134:135], s[12:13], 0, v[126:127]
	v_cmp_gt_i32_e32 vcc, s10, v120
	s_waitcnt vmcnt(0)
	v_pk_add_f32 v[112:113], v[112:113], v[116:117]
	v_cndmask_b32_e32 v125, v125, v135, vcc
	v_cndmask_b32_e32 v124, v124, v134, vcc
	v_pk_add_f32 v[114:115], v[114:115], v[118:119]
	v_lshl_add_u64 v[124:125], v[124:125], 0, v[102:103]
	global_store_dwordx4 v[138:139], v[112:115], off offset:144
	global_load_dwordx4 v[112:115], v[124:125], off
	v_cndmask_b32_e32 v121, v123, v127, vcc
	v_cndmask_b32_e32 v120, v122, v126, vcc
	v_lshl_add_u64 v[116:117], s[30:31], 0, v[120:121]
	v_lshl_add_u64 v[116:117], v[116:117], 0, v[102:103]
	s_waitcnt vmcnt(0)
	v_pk_add_f32 v[108:109], v[108:109], v[112:113]
	v_pk_add_f32 v[110:111], v[110:111], v[114:115]
	global_store_dwordx4 v[116:117], v[108:111], off
	global_load_dwordx4 v[108:111], v[124:125], off offset:16
	v_lshlrev_b64 v[114:115], 12, v[128:129]
	v_lshl_add_u64 v[114:115], s[14:15], 0, v[114:115]
	v_add_u32_e32 v128, 0xffffc030, v100
	s_waitcnt vmcnt(0)
	v_pk_add_f32 v[104:105], v[104:105], v[108:109]
	v_pk_add_f32 v[106:107], v[106:107], v[110:111]
	global_store_dwordx4 v[116:117], v[104:107], off offset:16
	global_load_dwordx4 v[104:107], v[124:125], off offset:128
	v_mov_b32_e32 v109, v129
	v_or_b32_e32 v108, 32, v100
	v_lshlrev_b64 v[110:111], 12, v[108:109]
	v_ashrrev_i32_e32 v109, 31, v108
	v_lshlrev_b64 v[112:113], 12, v[108:109]
	v_lshl_add_u64 v[118:119], s[12:13], 0, v[112:113]
	v_cmp_gt_i32_e32 vcc, s10, v108
	s_waitcnt vmcnt(0)
	v_pk_add_f32 v[104:105], v[130:131], v[104:105]
	v_pk_add_f32 v[106:107], v[132:133], v[106:107]
	global_store_dwordx4 v[116:117], v[104:107], off offset:128
	global_load_dwordx4 v[104:107], v[124:125], off offset:144
	v_cndmask_b32_e32 v115, v115, v119, vcc
	v_cndmask_b32_e32 v114, v114, v118, vcc
	v_lshl_add_u64 v[114:115], v[114:115], 0, v[102:103]
	v_cndmask_b32_e32 v109, v111, v113, vcc
	v_cndmask_b32_e32 v108, v110, v112, vcc
	s_waitcnt vmcnt(0)
	v_pk_add_f32 v[96:97], v[96:97], v[104:105]
	v_pk_add_f32 v[98:99], v[98:99], v[106:107]
	global_store_dwordx4 v[116:117], v[96:99], off offset:144
	global_load_dwordx4 v[96:99], v[114:115], off
	v_lshl_add_u64 v[104:105], s[30:31], 0, v[108:109]
	v_lshl_add_u64 v[104:105], v[104:105], 0, v[102:103]
	s_waitcnt vmcnt(0)
	v_pk_add_f32 v[92:93], v[92:93], v[96:97]
	v_pk_add_f32 v[94:95], v[94:95], v[98:99]
	global_store_dwordx4 v[104:105], v[92:95], off
	global_load_dwordx4 v[92:95], v[114:115], off offset:16
	v_lshlrev_b64 v[96:97], 12, v[128:129]
	v_lshl_add_u64 v[96:97], s[14:15], 0, v[96:97]
	v_add_u32_e32 v128, 0xffffc040, v100
	s_waitcnt vmcnt(0)
	v_pk_add_f32 v[88:89], v[88:89], v[92:93]
	v_pk_add_f32 v[90:91], v[90:91], v[94:95]
	global_store_dwordx4 v[104:105], v[88:91], off offset:16
	global_load_dwordx4 v[88:91], v[114:115], off offset:128
	s_waitcnt vmcnt(0)
	v_pk_add_f32 v[84:85], v[84:85], v[88:89]
	v_pk_add_f32 v[86:87], v[86:87], v[90:91]
	global_store_dwordx4 v[104:105], v[84:87], off offset:128
	global_load_dwordx4 v[84:87], v[114:115], off offset:144
	v_mov_b32_e32 v89, v129
	v_or_b32_e32 v88, 48, v100
	v_lshlrev_b64 v[90:91], 12, v[88:89]
	v_ashrrev_i32_e32 v89, 31, v88
	v_lshlrev_b64 v[92:93], 12, v[88:89]
	v_lshl_add_u64 v[94:95], s[12:13], 0, v[92:93]
	v_cmp_gt_i32_e32 vcc, s10, v88
	s_waitcnt vmcnt(0)
	v_pk_add_f32 v[80:81], v[80:81], v[84:85]
	v_cndmask_b32_e32 v95, v97, v95, vcc
	v_cndmask_b32_e32 v94, v96, v94, vcc
	v_pk_add_f32 v[82:83], v[82:83], v[86:87]
	v_lshl_add_u64 v[94:95], v[94:95], 0, v[102:103]
	global_store_dwordx4 v[104:105], v[80:83], off offset:144
	global_load_dwordx4 v[80:83], v[94:95], off
	v_cndmask_b32_e32 v89, v91, v93, vcc
	v_cndmask_b32_e32 v88, v90, v92, vcc
	v_lshl_add_u64 v[84:85], s[30:31], 0, v[88:89]
	v_lshl_add_u64 v[84:85], v[84:85], 0, v[102:103]
	s_waitcnt vmcnt(0)
	v_pk_add_f32 v[76:77], v[76:77], v[80:81]
	v_pk_add_f32 v[78:79], v[78:79], v[82:83]
	global_store_dwordx4 v[84:85], v[76:79], off
	global_load_dwordx4 v[76:79], v[94:95], off offset:16
	v_lshlrev_b64 v[80:81], 12, v[128:129]
	v_lshl_add_u64 v[80:81], s[14:15], 0, v[80:81]
	v_add_u32_e32 v128, 0xffffc050, v100
	s_waitcnt vmcnt(0)
	v_pk_add_f32 v[72:73], v[72:73], v[76:77]
	v_pk_add_f32 v[74:75], v[74:75], v[78:79]
	global_store_dwordx4 v[84:85], v[72:75], off offset:16
	global_load_dwordx4 v[72:75], v[94:95], off offset:128
	s_waitcnt vmcnt(0)
	v_pk_add_f32 v[68:69], v[68:69], v[72:73]
	v_pk_add_f32 v[70:71], v[70:71], v[74:75]
	global_store_dwordx4 v[84:85], v[68:71], off offset:128
	global_load_dwordx4 v[68:71], v[94:95], off offset:144
	v_mov_b32_e32 v73, v129
	v_or_b32_e32 v72, 64, v100
	v_lshlrev_b64 v[74:75], 12, v[72:73]
	v_ashrrev_i32_e32 v73, 31, v72
	v_lshlrev_b64 v[76:77], 12, v[72:73]
	v_lshl_add_u64 v[78:79], s[12:13], 0, v[76:77]
	v_cmp_gt_i32_e32 vcc, s10, v72
	s_waitcnt vmcnt(0)
	v_pk_add_f32 v[64:65], v[64:65], v[68:69]
	v_cndmask_b32_e32 v79, v81, v79, vcc
	v_cndmask_b32_e32 v78, v80, v78, vcc
	v_pk_add_f32 v[66:67], v[66:67], v[70:71]
	v_lshl_add_u64 v[78:79], v[78:79], 0, v[102:103]
	global_store_dwordx4 v[84:85], v[64:67], off offset:144
	global_load_dwordx4 v[64:67], v[78:79], off
	v_cndmask_b32_e32 v73, v75, v77, vcc
	v_cndmask_b32_e32 v72, v74, v76, vcc
	v_lshl_add_u64 v[68:69], s[30:31], 0, v[72:73]
	v_lshl_add_u64 v[68:69], v[68:69], 0, v[102:103]
	s_waitcnt vmcnt(0)
	v_pk_add_f32 v[60:61], v[60:61], v[64:65]
	v_pk_add_f32 v[62:63], v[62:63], v[66:67]
	global_store_dwordx4 v[68:69], v[60:63], off
	global_load_dwordx4 v[60:63], v[78:79], off offset:16
	v_lshlrev_b64 v[64:65], 12, v[128:129]
	v_lshl_add_u64 v[64:65], s[14:15], 0, v[64:65]
	v_add_u32_e32 v128, 0xffffc060, v100
	s_waitcnt vmcnt(0)
	v_pk_add_f32 v[56:57], v[56:57], v[60:61]
	v_pk_add_f32 v[58:59], v[58:59], v[62:63]
	global_store_dwordx4 v[68:69], v[56:59], off offset:16
	global_load_dwordx4 v[56:59], v[78:79], off offset:128
	s_waitcnt vmcnt(0)
	v_pk_add_f32 v[52:53], v[52:53], v[56:57]
	v_pk_add_f32 v[54:55], v[54:55], v[58:59]
	global_store_dwordx4 v[68:69], v[52:55], off offset:128
	global_load_dwordx4 v[52:55], v[78:79], off offset:144
	v_mov_b32_e32 v57, v129
	v_or_b32_e32 v56, 0x50, v100
	v_lshlrev_b64 v[58:59], 12, v[56:57]
	v_ashrrev_i32_e32 v57, 31, v56
	v_lshlrev_b64 v[60:61], 12, v[56:57]
	v_lshl_add_u64 v[62:63], s[12:13], 0, v[60:61]
	v_cmp_gt_i32_e32 vcc, s10, v56
	s_waitcnt vmcnt(0)
	v_pk_add_f32 v[48:49], v[48:49], v[52:53]
	v_cndmask_b32_e32 v63, v65, v63, vcc
	v_cndmask_b32_e32 v62, v64, v62, vcc
	v_pk_add_f32 v[50:51], v[50:51], v[54:55]
	v_lshl_add_u64 v[62:63], v[62:63], 0, v[102:103]
	global_store_dwordx4 v[68:69], v[48:51], off offset:144
	global_load_dwordx4 v[48:51], v[62:63], off
	v_cndmask_b32_e32 v57, v59, v61, vcc
	v_cndmask_b32_e32 v56, v58, v60, vcc
	v_lshl_add_u64 v[52:53], s[30:31], 0, v[56:57]
	v_lshl_add_u64 v[52:53], v[52:53], 0, v[102:103]
	s_waitcnt vmcnt(0)
	v_pk_add_f32 v[44:45], v[44:45], v[48:49]
	v_pk_add_f32 v[46:47], v[46:47], v[50:51]
	global_store_dwordx4 v[52:53], v[44:47], off
	global_load_dwordx4 v[44:47], v[62:63], off offset:16
	v_lshlrev_b64 v[48:49], 12, v[128:129]
	v_lshl_add_u64 v[48:49], s[14:15], 0, v[48:49]
	v_add_u32_e32 v128, 0xffffc070, v100
	s_waitcnt vmcnt(0)
	v_pk_add_f32 v[40:41], v[40:41], v[44:45]
	v_pk_add_f32 v[42:43], v[42:43], v[46:47]
	global_store_dwordx4 v[52:53], v[40:43], off offset:16
	global_load_dwordx4 v[40:43], v[62:63], off offset:128
	s_waitcnt vmcnt(0)
	v_pk_add_f32 v[36:37], v[36:37], v[40:41]
	v_pk_add_f32 v[38:39], v[38:39], v[42:43]
	global_store_dwordx4 v[52:53], v[36:39], off offset:128
	global_load_dwordx4 v[36:39], v[62:63], off offset:144
	v_mov_b32_e32 v41, v129
	v_or_b32_e32 v40, 0x60, v100
	v_lshlrev_b64 v[42:43], 12, v[40:41]
	v_ashrrev_i32_e32 v41, 31, v40
	v_lshlrev_b64 v[44:45], 12, v[40:41]
	v_lshl_add_u64 v[46:47], s[12:13], 0, v[44:45]
	v_cmp_gt_i32_e32 vcc, s10, v40
	s_waitcnt vmcnt(0)
	v_pk_add_f32 v[32:33], v[32:33], v[36:37]
	v_cndmask_b32_e32 v47, v49, v47, vcc
	v_cndmask_b32_e32 v46, v48, v46, vcc
	v_pk_add_f32 v[34:35], v[34:35], v[38:39]
	v_lshl_add_u64 v[46:47], v[46:47], 0, v[102:103]
	global_store_dwordx4 v[52:53], v[32:35], off offset:144
	global_load_dwordx4 v[32:35], v[46:47], off
	v_cndmask_b32_e32 v41, v43, v45, vcc
	v_cndmask_b32_e32 v40, v42, v44, vcc
	v_lshl_add_u64 v[36:37], s[30:31], 0, v[40:41]
	v_lshl_add_u64 v[36:37], v[36:37], 0, v[102:103]
	s_waitcnt vmcnt(0)
	v_pk_add_f32 v[28:29], v[28:29], v[32:33]
	v_pk_add_f32 v[30:31], v[30:31], v[34:35]
	global_store_dwordx4 v[36:37], v[28:31], off
	global_load_dwordx4 v[28:31], v[46:47], off offset:16
	v_lshlrev_b64 v[32:33], 12, v[128:129]
	v_lshl_add_u64 v[32:33], s[14:15], 0, v[32:33]
	s_waitcnt vmcnt(0)
	v_pk_add_f32 v[24:25], v[24:25], v[28:29]
	v_pk_add_f32 v[26:27], v[26:27], v[30:31]
	global_store_dwordx4 v[36:37], v[24:27], off offset:16
	global_load_dwordx4 v[24:27], v[46:47], off offset:128
	s_waitcnt vmcnt(0)
	v_pk_add_f32 v[20:21], v[20:21], v[24:25]
	v_pk_add_f32 v[22:23], v[22:23], v[26:27]
	global_store_dwordx4 v[36:37], v[20:23], off offset:128
	global_load_dwordx4 v[20:23], v[46:47], off offset:144
	v_mov_b32_e32 v25, v129
	v_or_b32_e32 v24, 0x70, v100
	v_lshlrev_b64 v[26:27], 12, v[24:25]
	v_ashrrev_i32_e32 v25, 31, v24
	v_lshlrev_b64 v[28:29], 12, v[24:25]
	v_lshl_add_u64 v[30:31], s[12:13], 0, v[28:29]
	v_cmp_gt_i32_e32 vcc, s10, v24
	s_waitcnt vmcnt(0)
	v_pk_add_f32 v[16:17], v[16:17], v[20:21]
	v_cndmask_b32_e32 v31, v33, v31, vcc
	v_cndmask_b32_e32 v30, v32, v30, vcc
	v_pk_add_f32 v[18:19], v[18:19], v[22:23]
	v_lshl_add_u64 v[30:31], v[30:31], 0, v[102:103]
	global_store_dwordx4 v[36:37], v[16:19], off offset:144
	global_load_dwordx4 v[16:19], v[30:31], off
	v_cndmask_b32_e32 v25, v27, v29, vcc
	v_cndmask_b32_e32 v24, v26, v28, vcc
	v_lshl_add_u64 v[20:21], s[30:31], 0, v[24:25]
	v_lshl_add_u64 v[20:21], v[20:21], 0, v[102:103]
	s_waitcnt vmcnt(0)
	v_pk_add_f32 v[12:13], v[12:13], v[16:17]
	v_pk_add_f32 v[14:15], v[14:15], v[18:19]
	global_store_dwordx4 v[20:21], v[12:15], off
	global_load_dwordx4 v[12:15], v[30:31], off offset:16
	s_waitcnt vmcnt(0)
	v_pk_add_f32 v[8:9], v[8:9], v[12:13]
	v_pk_add_f32 v[10:11], v[10:11], v[14:15]
	global_store_dwordx4 v[20:21], v[8:11], off offset:16
	global_load_dwordx4 v[8:11], v[30:31], off offset:128
	s_waitcnt vmcnt(0)
	v_pk_add_f32 v[4:5], v[4:5], v[8:9]
	v_pk_add_f32 v[6:7], v[6:7], v[10:11]
	global_store_dwordx4 v[20:21], v[4:7], off offset:128
	global_load_dwordx4 v[4:7], v[30:31], off offset:144
	s_waitcnt vmcnt(0)
	v_pk_add_f32 v[0:1], v[0:1], v[4:5]
	v_pk_add_f32 v[2:3], v[2:3], v[6:7]
	global_store_dwordx4 v[20:21], v[0:3], off offset:144
	s_cbranch_scc0 .LBB0_822
	v_readlane_b32 s11, v254, 56

.LBB0_887:
	s_add_i32 s20, s19, 2
	s_mul_hi_i32 s21, s20, 0x55555556
	s_lshr_b32 s22, s21, 31
	s_add_i32 s21, s21, s22
	s_mul_i32 s21, s21, 3
	s_sub_i32 s20, s20, s21
	s_mulk_i32 s20, 0x6000
	s_mul_i32 s54, s19, 0x6000
	v_readfirstlane_b32 s55, v140
	v_lshl_add_u64 v[232:233], v[132:133], 0, s[6:7]
	v_lshl_add_u64 v[234:235], v[130:131], 0, s[6:7]
	s_add_u32 s55, s55, s20
	s_waitcnt vmcnt(6) lgkmcnt(0)
	s_barrier
	s_setprio 1
	s_mov_b32 m0, s55
	s_mov_b64 s[20:21], 0x12d0100
	v_lshl_add_u64 v[236:237], v[232:233], 0, s[20:21]
	global_load_lds_dwordx4 v[236:237], off
	s_add_u32 m0, s55, 0x1000
	s_mov_b64 s[20:21], 0x12f0100
	v_lshl_add_u64 v[236:237], v[232:233], 0, s[20:21]
	global_load_lds_dwordx4 v[236:237], off
	s_add_u32 m0, s55, 0x2000
	s_mov_b64 s[20:21], 0x1310100
	v_lshl_add_u64 v[236:237], v[232:233], 0, s[20:21]
	global_load_lds_dwordx4 v[236:237], off
	s_add_u32 m0, s55, 0x3000
	s_mov_b64 s[20:21], 0x1330100
	v_lshl_add_u64 v[236:237], v[232:233], 0, s[20:21]
	global_load_lds_dwordx4 v[236:237], off
	s_add_u32 m0, s55, 0x4000
	s_mov_b64 s[20:21], 0x100
	v_lshl_add_u64 v[236:237], v[234:235], 0, s[20:21]
	global_load_lds_dwordx4 v[236:237], off
	s_add_u32 m0, s55, 0x5000
	s_mov_b64 s[20:21], 0x20100
	v_lshl_add_u64 v[236:237], v[234:235], 0, s[20:21]
	global_load_lds_dwordx4 v[236:237], off
	v_or_b32_e32 v128, s54, v138
	v_add3_u32 v128, v128, v139, v137
	ds_read_b128 v[174:177], v128 offset:16384
	ds_read_b128 v[178:181], v128 offset:16640
	ds_read_b128 v[182:185], v128 offset:18432
	ds_read_b128 v[186:189], v128 offset:18688
	v_add3_u32 v128, s54, v141, v137
	ds_read_b128 v[142:145], v128
	ds_read_b128 v[146:149], v128 offset:1024
	ds_read_b128 v[150:153], v128 offset:2048
	ds_read_b128 v[154:157], v128 offset:3072
	ds_read_b128 v[158:161], v128 offset:4096
	ds_read_b128 v[162:165], v128 offset:5120
	ds_read_b128 v[166:169], v128 offset:6144
	ds_read_b128 v[170:173], v128 offset:7168
	s_setprio 0
	s_waitcnt lgkmcnt(7)
	v_mfma_f32_16x16x32_bf16 v[124:127], v[174:177], v[142:145], v[124:127]
	v_mfma_f32_16x16x32_bf16 v[120:123], v[178:181], v[142:145], v[120:123]
	v_mfma_f32_16x16x32_bf16 v[116:119], v[182:185], v[142:145], v[116:119]
	v_mfma_f32_16x16x32_bf16 v[112:115], v[186:189], v[142:145], v[112:115]
	s_waitcnt lgkmcnt(6)
	v_mfma_f32_16x16x32_bf16 v[108:111], v[174:177], v[146:149], v[108:111]
	v_mfma_f32_16x16x32_bf16 v[104:107], v[178:181], v[146:149], v[104:107]
	v_mfma_f32_16x16x32_bf16 v[100:103], v[182:185], v[146:149], v[100:103]
	v_mfma_f32_16x16x32_bf16 v[96:99], v[186:189], v[146:149], v[96:99]
	s_waitcnt lgkmcnt(5)
	v_mfma_f32_16x16x32_bf16 v[92:95], v[174:177], v[150:153], v[92:95]
	v_mfma_f32_16x16x32_bf16 v[88:91], v[178:181], v[150:153], v[88:91]
	v_mfma_f32_16x16x32_bf16 v[84:87], v[182:185], v[150:153], v[84:87]
	v_mfma_f32_16x16x32_bf16 v[80:83], v[186:189], v[150:153], v[80:83]
	s_waitcnt lgkmcnt(4)
	v_mfma_f32_16x16x32_bf16 v[76:79], v[174:177], v[154:157], v[76:79]
	v_mfma_f32_16x16x32_bf16 v[72:75], v[178:181], v[154:157], v[72:75]
	v_mfma_f32_16x16x32_bf16 v[68:71], v[182:185], v[154:157], v[68:71]
	v_mfma_f32_16x16x32_bf16 v[64:67], v[186:189], v[154:157], v[64:67]
	s_waitcnt lgkmcnt(3)
	v_mfma_f32_16x16x32_bf16 v[60:63], v[174:177], v[158:161], v[60:63]
	v_mfma_f32_16x16x32_bf16 v[56:59], v[178:181], v[158:161], v[56:59]
	v_mfma_f32_16x16x32_bf16 v[52:55], v[182:185], v[158:161], v[52:55]
	v_mfma_f32_16x16x32_bf16 v[48:51], v[186:189], v[158:161], v[48:51]
	s_waitcnt lgkmcnt(2)
	v_mfma_f32_16x16x32_bf16 v[44:47], v[174:177], v[162:165], v[44:47]
	v_mfma_f32_16x16x32_bf16 v[40:43], v[178:181], v[162:165], v[40:43]
	v_mfma_f32_16x16x32_bf16 v[36:39], v[182:185], v[162:165], v[36:39]
	v_mfma_f32_16x16x32_bf16 v[32:35], v[186:189], v[162:165], v[32:35]
	s_waitcnt lgkmcnt(1)
	v_mfma_f32_16x16x32_bf16 v[28:31], v[174:177], v[166:169], v[28:31]
	v_mfma_f32_16x16x32_bf16 v[24:27], v[178:181], v[166:169], v[24:27]
	v_mfma_f32_16x16x32_bf16 v[20:23], v[182:185], v[166:169], v[20:23]
	v_mfma_f32_16x16x32_bf16 v[16:19], v[186:189], v[166:169], v[16:19]
	s_waitcnt lgkmcnt(0)
	v_mfma_f32_16x16x32_bf16 v[12:15], v[174:177], v[170:173], v[12:15]
	v_mfma_f32_16x16x32_bf16 v[8:11], v[178:181], v[170:173], v[8:11]
	v_mfma_f32_16x16x32_bf16 v[4:7], v[182:185], v[170:173], v[4:7]
	v_mfma_f32_16x16x32_bf16 v[0:3], v[186:189], v[170:173], v[0:3]
	s_add_i32 s20, s19, 1
	s_cmp_lg_u32 s19, 2
	s_cselect_b32 s19, s20, 0
	s_add_u32 s6, s6, 0x80
	s_addc_u32 s7, s7, 0
	s_cmpk_lg_i32 s6, 0xf00
	s_cbranch_scc1 .LBB0_887
	s_waitcnt vmcnt(6) lgkmcnt(0)
	s_barrier
	v_add_u32_e32 v128, v141, v137
	ds_read_b128 v[130:133], v128
	ds_read_b128 v[140:143], v128 offset:1024
	ds_read_b128 v[144:147], v128 offset:2048
	ds_read_b128 v[148:151], v128 offset:3072
	ds_read_b128 v[152:155], v128 offset:4096
	ds_read_b128 v[156:159], v128 offset:5120
	ds_read_b128 v[160:163], v128 offset:6144
	ds_read_b128 v[164:167], v128 offset:7168
	v_add3_u32 v137, v138, v139, v137
	ds_read_b128 v[168:171], v137 offset:16384
	ds_read_b128 v[172:175], v137 offset:16640
	ds_read_b128 v[176:179], v137 offset:18432
	ds_read_b128 v[180:183], v137 offset:18688
	s_setprio 1
	s_waitcnt lgkmcnt(0)
	v_mfma_f32_16x16x32_bf16 v[124:127], v[168:171], v[130:133], v[124:127]
	v_mfma_f32_16x16x32_bf16 v[120:123], v[172:175], v[130:133], v[120:123]
	v_mfma_f32_16x16x32_bf16 v[116:119], v[176:179], v[130:133], v[116:119]
	v_mfma_f32_16x16x32_bf16 v[112:115], v[180:183], v[130:133], v[112:115]
	v_mfma_f32_16x16x32_bf16 v[108:111], v[168:171], v[140:143], v[108:111]
	v_mfma_f32_16x16x32_bf16 v[104:107], v[172:175], v[140:143], v[104:107]
	v_mfma_f32_16x16x32_bf16 v[100:103], v[176:179], v[140:143], v[100:103]
	v_mfma_f32_16x16x32_bf16 v[96:99], v[180:183], v[140:143], v[96:99]
	v_mfma_f32_16x16x32_bf16 v[92:95], v[168:171], v[144:147], v[92:95]
	v_mfma_f32_16x16x32_bf16 v[88:91], v[172:175], v[144:147], v[88:91]
	v_mfma_f32_16x16x32_bf16 v[84:87], v[176:179], v[144:147], v[84:87]
	v_mfma_f32_16x16x32_bf16 v[80:83], v[180:183], v[144:147], v[80:83]
	v_mfma_f32_16x16x32_bf16 v[76:79], v[168:171], v[148:151], v[76:79]
	v_mfma_f32_16x16x32_bf16 v[72:75], v[172:175], v[148:151], v[72:75]
	v_mfma_f32_16x16x32_bf16 v[68:71], v[176:179], v[148:151], v[68:71]
	v_mfma_f32_16x16x32_bf16 v[64:67], v[180:183], v[148:151], v[64:67]
	v_mfma_f32_16x16x32_bf16 v[60:63], v[168:171], v[152:155], v[60:63]
	v_mfma_f32_16x16x32_bf16 v[56:59], v[172:175], v[152:155], v[56:59]
	v_mfma_f32_16x16x32_bf16 v[52:55], v[176:179], v[152:155], v[52:55]
	v_mfma_f32_16x16x32_bf16 v[48:51], v[180:183], v[152:155], v[48:51]
	v_mfma_f32_16x16x32_bf16 v[44:47], v[168:171], v[156:159], v[44:47]
	v_mfma_f32_16x16x32_bf16 v[40:43], v[172:175], v[156:159], v[40:43]
	v_mfma_f32_16x16x32_bf16 v[36:39], v[176:179], v[156:159], v[36:39]
	v_mfma_f32_16x16x32_bf16 v[32:35], v[180:183], v[156:159], v[32:35]
	v_mfma_f32_16x16x32_bf16 v[28:31], v[168:171], v[160:163], v[28:31]
	v_mfma_f32_16x16x32_bf16 v[24:27], v[172:175], v[160:163], v[24:27]
	v_mfma_f32_16x16x32_bf16 v[20:23], v[176:179], v[160:163], v[20:23]
	v_mfma_f32_16x16x32_bf16 v[16:19], v[180:183], v[160:163], v[16:19]
	v_mfma_f32_16x16x32_bf16 v[12:15], v[168:171], v[164:167], v[12:15]
	v_mfma_f32_16x16x32_bf16 v[8:11], v[172:175], v[164:167], v[8:11]
	v_mfma_f32_16x16x32_bf16 v[4:7], v[176:179], v[164:167], v[4:7]
	v_mfma_f32_16x16x32_bf16 v[0:3], v[180:183], v[164:167], v[0:3]
	s_setprio 0
	s_waitcnt vmcnt(0) lgkmcnt(0)
	s_barrier
	ds_read_b128 v[130:133], v128 offset:24576
	ds_read_b128 v[138:141], v128 offset:25600
	ds_read_b128 v[142:145], v128 offset:26624
	ds_read_b128 v[146:149], v128 offset:27648
	ds_read_b128 v[150:153], v128 offset:28672
	ds_read_b128 v[154:157], v128 offset:29696
	ds_read_b128 v[158:161], v128 offset:30720
	ds_read_b128 v[162:165], v128 offset:31744
	ds_read_b128 v[166:169], v137 offset:40960
	ds_read_b128 v[170:173], v137 offset:41216
	ds_read_b128 v[174:177], v137 offset:43008
	ds_read_b128 v[178:181], v137 offset:43264
	s_setprio 1
	s_waitcnt lgkmcnt(0)
	v_mfma_f32_16x16x32_bf16 v[124:127], v[166:169], v[130:133], v[124:127]
	v_mfma_f32_16x16x32_bf16 v[120:123], v[170:173], v[130:133], v[120:123]
	v_mfma_f32_16x16x32_bf16 v[116:119], v[174:177], v[130:133], v[116:119]
	v_mfma_f32_16x16x32_bf16 v[112:115], v[178:181], v[130:133], v[112:115]
	v_mfma_f32_16x16x32_bf16 v[108:111], v[166:169], v[138:141], v[108:111]
	v_mfma_f32_16x16x32_bf16 v[104:107], v[170:173], v[138:141], v[104:107]
	v_mfma_f32_16x16x32_bf16 v[100:103], v[174:177], v[138:141], v[100:103]
	v_mfma_f32_16x16x32_bf16 v[96:99], v[178:181], v[138:141], v[96:99]
	v_mfma_f32_16x16x32_bf16 v[92:95], v[166:169], v[142:145], v[92:95]
	v_mfma_f32_16x16x32_bf16 v[88:91], v[170:173], v[142:145], v[88:91]
	v_mfma_f32_16x16x32_bf16 v[84:87], v[174:177], v[142:145], v[84:87]
	v_mfma_f32_16x16x32_bf16 v[80:83], v[178:181], v[142:145], v[80:83]
	v_mfma_f32_16x16x32_bf16 v[130:133], v[166:169], v[146:149], v[76:79]
	v_mfma_f32_16x16x32_bf16 v[72:75], v[170:173], v[146:149], v[72:75]
	v_mfma_f32_16x16x32_bf16 v[68:71], v[174:177], v[146:149], v[68:71]
	v_mfma_f32_16x16x32_bf16 v[64:67], v[178:181], v[146:149], v[64:67]
	v_mfma_f32_16x16x32_bf16 v[60:63], v[166:169], v[150:153], v[60:63]
	v_mfma_f32_16x16x32_bf16 v[56:59], v[170:173], v[150:153], v[56:59]
	v_mfma_f32_16x16x32_bf16 v[52:55], v[174:177], v[150:153], v[52:55]
	v_mfma_f32_16x16x32_bf16 v[48:51], v[178:181], v[150:153], v[48:51]
	v_mfma_f32_16x16x32_bf16 v[44:47], v[166:169], v[154:157], v[44:47]
	v_mfma_f32_16x16x32_bf16 v[40:43], v[170:173], v[154:157], v[40:43]
	v_mfma_f32_16x16x32_bf16 v[36:39], v[174:177], v[154:157], v[36:39]
	v_mfma_f32_16x16x32_bf16 v[32:35], v[178:181], v[154:157], v[32:35]
	v_mfma_f32_16x16x32_bf16 v[28:31], v[166:169], v[158:161], v[28:31]
	v_mfma_f32_16x16x32_bf16 v[24:27], v[170:173], v[158:161], v[24:27]
	v_mfma_f32_16x16x32_bf16 v[20:23], v[174:177], v[158:161], v[20:23]
	v_mfma_f32_16x16x32_bf16 v[16:19], v[178:181], v[158:161], v[16:19]
	v_mfma_f32_16x16x32_bf16 v[12:15], v[166:169], v[162:165], v[12:15]
	v_mfma_f32_16x16x32_bf16 v[8:11], v[170:173], v[162:165], v[8:11]
	v_mfma_f32_16x16x32_bf16 v[4:7], v[174:177], v[162:165], v[4:7]
	v_mfma_f32_16x16x32_bf16 v[0:3], v[178:181], v[162:165], v[0:3]
	s_setprio 0
	v_and_b32_e32 v76, 0xffffff80, v134
	v_add_u32_e32 v76, s17, v76
	v_lshrrev_b32_e32 v77, 1, v134
	v_or_b32_e32 v128, v76, v135
	v_lshlrev_b32_e32 v76, 6, v136
	v_and_b32_e32 v77, 24, v77
	v_or3_b32 v78, v76, v77, s18
	v_ashrrev_i32_e32 v79, 31, v78
	v_lshl_add_u64 v[76:77], v[78:79], 1, s[94:95]
	v_mov_b32_e32 v79, v129
	v_lshl_add_u64 v[134:135], v[78:79], 1, s[40:41]
	v_bfe_u32 v79, v124, 16, 1
	v_add3_u32 v79, v124, v79, s13
	v_bfe_u32 v124, v125, 16, 1
	v_lshrrev_b32_e32 v79, 16, v79
	v_add3_u32 v124, v125, v124, s13
	v_and_or_b32 v124, v124, s14, v79
	v_bfe_u32 v79, v126, 16, 1
	v_add3_u32 v79, v126, v79, s13
	v_bfe_u32 v125, v127, 16, 1
	v_lshrrev_b32_e32 v79, 16, v79
	v_add3_u32 v125, v127, v125, s13
	v_and_or_b32 v125, v125, s14, v79
	v_bfe_u32 v79, v120, 16, 1
	v_add3_u32 v79, v120, v79, s13
	v_bfe_u32 v120, v121, 16, 1
	v_lshrrev_b32_e32 v79, 16, v79
	v_add3_u32 v120, v121, v120, s13
	v_and_or_b32 v126, v120, s14, v79
	v_bfe_u32 v79, v122, 16, 1
	v_lshl_add_u64 v[134:135], v[134:135], 0, s[4:5]
	v_cmp_gt_i32_e32 vcc, s12, v78
	v_add3_u32 v79, v122, v79, s13
	v_bfe_u32 v120, v123, 16, 1
	v_cndmask_b32_e32 v77, v135, v77, vcc
	v_cndmask_b32_e32 v76, v134, v76, vcc
	v_lshrrev_b32_e32 v79, 16, v79
	v_add3_u32 v120, v123, v120, s13
	v_or_b32_e32 v78, 32, v78
	v_and_or_b32 v127, v120, s14, v79
	v_mad_i64_i32 v[120:121], s[6:7], v128, s15, v[76:77]
	v_ashrrev_i32_e32 v79, 31, v78
	global_store_dwordx4 v[120:121], v[124:127], off
	v_lshl_add_u64 v[120:121], v[78:79], 1, s[94:95]
	v_mov_b32_e32 v79, v129
	v_lshl_add_u64 v[122:123], v[78:79], 1, s[40:41]
	v_lshl_add_u64 v[122:123], v[122:123], 0, s[4:5]
	v_cmp_gt_i32_e32 vcc, s12, v78
	s_add_i32 s16, s16, s86
	s_add_i32 s8, s8, s9
	v_cndmask_b32_e32 v78, v122, v120, vcc
	v_bfe_u32 v120, v116, 16, 1
	v_add3_u32 v116, v116, v120, s13
	v_bfe_u32 v120, v117, 16, 1
	v_lshrrev_b32_e32 v116, 16, v116
	v_add3_u32 v117, v117, v120, s13
	v_and_or_b32 v116, v117, s14, v116
	v_bfe_u32 v117, v118, 16, 1
	v_add3_u32 v117, v118, v117, s13
	v_bfe_u32 v118, v119, 16, 1
	v_lshrrev_b32_e32 v117, 16, v117
	v_add3_u32 v118, v119, v118, s13
	v_and_or_b32 v117, v118, s14, v117
	v_bfe_u32 v118, v112, 16, 1
	v_add3_u32 v112, v112, v118, s13
	v_bfe_u32 v118, v113, 16, 1
	v_lshrrev_b32_e32 v112, 16, v112
	v_add3_u32 v113, v113, v118, s13
	v_and_or_b32 v118, v113, s14, v112
	v_bfe_u32 v112, v114, 16, 1
	v_add3_u32 v112, v114, v112, s13
	v_bfe_u32 v113, v115, 16, 1
	v_cndmask_b32_e32 v79, v123, v121, vcc
	v_lshrrev_b32_e32 v112, 16, v112
	v_add3_u32 v113, v115, v113, s13
	v_and_or_b32 v119, v113, s14, v112
	v_mad_i64_i32 v[112:113], s[6:7], v128, s15, v[78:79]
	global_store_dwordx4 v[112:113], v[116:119], off
	v_bfe_u32 v113, v108, 16, 1
	v_add3_u32 v108, v108, v113, s13
	v_bfe_u32 v113, v109, 16, 1
	v_lshrrev_b32_e32 v108, 16, v108
	v_add3_u32 v109, v109, v113, s13
	v_and_or_b32 v108, v109, s14, v108
	v_bfe_u32 v109, v110, 16, 1
	v_add3_u32 v109, v110, v109, s13
	v_bfe_u32 v110, v111, 16, 1
	v_lshrrev_b32_e32 v109, 16, v109
	v_add3_u32 v110, v111, v110, s13
	v_and_or_b32 v109, v110, s14, v109
	v_bfe_u32 v110, v104, 16, 1
	v_add3_u32 v104, v104, v110, s13
	v_bfe_u32 v110, v105, 16, 1
	v_lshrrev_b32_e32 v104, 16, v104
	v_add3_u32 v105, v105, v110, s13
	v_and_or_b32 v110, v105, s14, v104
	v_bfe_u32 v104, v106, 16, 1
	v_add3_u32 v104, v106, v104, s13
	v_bfe_u32 v105, v107, 16, 1
	v_or_b32_e32 v112, 16, v128
	v_lshrrev_b32_e32 v104, 16, v104
	v_add3_u32 v105, v107, v105, s13
	v_and_or_b32 v111, v105, s14, v104
	v_mad_i64_i32 v[104:105], s[6:7], v112, s15, v[76:77]
	global_store_dwordx4 v[104:105], v[108:111], off
	v_bfe_u32 v104, v100, 16, 1
	v_add3_u32 v100, v100, v104, s13
	v_bfe_u32 v104, v101, 16, 1
	v_lshrrev_b32_e32 v100, 16, v100
	v_add3_u32 v101, v101, v104, s13
	v_and_or_b32 v100, v101, s14, v100
	v_bfe_u32 v101, v102, 16, 1
	v_add3_u32 v101, v102, v101, s13
	v_bfe_u32 v102, v103, 16, 1
	v_lshrrev_b32_e32 v101, 16, v101
	v_add3_u32 v102, v103, v102, s13
	v_and_or_b32 v101, v102, s14, v101
	v_bfe_u32 v102, v96, 16, 1
	v_add3_u32 v96, v96, v102, s13
	v_bfe_u32 v102, v97, 16, 1
	v_lshrrev_b32_e32 v96, 16, v96
	v_add3_u32 v97, v97, v102, s13
	v_and_or_b32 v102, v97, s14, v96
	v_bfe_u32 v96, v98, 16, 1
	v_add3_u32 v96, v98, v96, s13
	v_bfe_u32 v97, v99, 16, 1
	v_lshrrev_b32_e32 v96, 16, v96
	v_add3_u32 v97, v99, v97, s13
	v_and_or_b32 v103, v97, s14, v96
	v_mad_i64_i32 v[96:97], s[6:7], v112, s15, v[78:79]
	global_store_dwordx4 v[96:97], v[100:103], off
	v_bfe_u32 v97, v92, 16, 1
	v_add3_u32 v92, v92, v97, s13
	v_bfe_u32 v97, v93, 16, 1
	v_lshrrev_b32_e32 v92, 16, v92
	v_add3_u32 v93, v93, v97, s13
	v_and_or_b32 v92, v93, s14, v92
	v_bfe_u32 v93, v94, 16, 1
	v_add3_u32 v93, v94, v93, s13
	v_bfe_u32 v94, v95, 16, 1
	v_lshrrev_b32_e32 v93, 16, v93
	v_add3_u32 v94, v95, v94, s13
	v_and_or_b32 v93, v94, s14, v93
	v_bfe_u32 v94, v88, 16, 1
	v_add3_u32 v88, v88, v94, s13
	v_bfe_u32 v94, v89, 16, 1
	v_lshrrev_b32_e32 v88, 16, v88
	v_add3_u32 v89, v89, v94, s13
	v_and_or_b32 v94, v89, s14, v88
	v_bfe_u32 v88, v90, 16, 1
	v_add3_u32 v88, v90, v88, s13
	v_bfe_u32 v89, v91, 16, 1
	v_or_b32_e32 v96, 32, v128
	v_lshrrev_b32_e32 v88, 16, v88
	v_add3_u32 v89, v91, v89, s13
	v_and_or_b32 v95, v89, s14, v88
	v_mad_i64_i32 v[88:89], s[6:7], v96, s15, v[76:77]
	global_store_dwordx4 v[88:89], v[92:95], off
	v_bfe_u32 v88, v84, 16, 1
	v_add3_u32 v84, v84, v88, s13
	v_bfe_u32 v88, v85, 16, 1
	v_lshrrev_b32_e32 v84, 16, v84
	v_add3_u32 v85, v85, v88, s13
	v_and_or_b32 v84, v85, s14, v84
	v_bfe_u32 v85, v86, 16, 1
	v_add3_u32 v85, v86, v85, s13
	v_bfe_u32 v86, v87, 16, 1
	v_lshrrev_b32_e32 v85, 16, v85
	v_add3_u32 v86, v87, v86, s13
	v_and_or_b32 v85, v86, s14, v85
	v_bfe_u32 v86, v80, 16, 1
	v_add3_u32 v80, v80, v86, s13
	v_bfe_u32 v86, v81, 16, 1
	v_lshrrev_b32_e32 v80, 16, v80
	v_add3_u32 v81, v81, v86, s13
	v_and_or_b32 v86, v81, s14, v80
	v_bfe_u32 v80, v82, 16, 1
	v_add3_u32 v80, v82, v80, s13
	v_bfe_u32 v81, v83, 16, 1
	v_lshrrev_b32_e32 v80, 16, v80
	v_add3_u32 v81, v83, v81, s13
	v_and_or_b32 v87, v81, s14, v80
	v_mad_i64_i32 v[80:81], s[6:7], v96, s15, v[78:79]
	global_store_dwordx4 v[80:81], v[84:87], off
	v_bfe_u32 v80, v130, 16, 1
	v_add3_u32 v80, v130, v80, s13
	v_bfe_u32 v81, v131, 16, 1
	v_lshrrev_b32_e32 v80, 16, v80
	v_add3_u32 v81, v131, v81, s13
	v_and_or_b32 v80, v81, s14, v80
	v_bfe_u32 v81, v132, 16, 1
	v_add3_u32 v81, v132, v81, s13
	v_bfe_u32 v82, v133, 16, 1
	v_lshrrev_b32_e32 v81, 16, v81
	v_add3_u32 v82, v133, v82, s13
	v_and_or_b32 v81, v82, s14, v81
	v_bfe_u32 v82, v72, 16, 1
	v_add3_u32 v72, v72, v82, s13
	v_bfe_u32 v82, v73, 16, 1
	v_lshrrev_b32_e32 v72, 16, v72
	v_add3_u32 v73, v73, v82, s13
	v_and_or_b32 v82, v73, s14, v72
	v_bfe_u32 v72, v74, 16, 1
	v_add3_u32 v72, v74, v72, s13
	v_bfe_u32 v73, v75, 16, 1
	v_or_b32_e32 v84, 48, v128
	v_lshrrev_b32_e32 v72, 16, v72
	v_add3_u32 v73, v75, v73, s13
	v_and_or_b32 v83, v73, s14, v72
	v_mad_i64_i32 v[72:73], s[6:7], v84, s15, v[76:77]
	global_store_dwordx4 v[72:73], v[80:83], off
	v_bfe_u32 v72, v68, 16, 1
	v_add3_u32 v68, v68, v72, s13
	v_bfe_u32 v72, v69, 16, 1
	v_lshrrev_b32_e32 v68, 16, v68
	v_add3_u32 v69, v69, v72, s13
	v_and_or_b32 v68, v69, s14, v68
	v_bfe_u32 v69, v70, 16, 1
	v_add3_u32 v69, v70, v69, s13
	v_bfe_u32 v70, v71, 16, 1
	v_lshrrev_b32_e32 v69, 16, v69
	v_add3_u32 v70, v71, v70, s13
	v_and_or_b32 v69, v70, s14, v69
	v_bfe_u32 v70, v64, 16, 1
	v_add3_u32 v64, v64, v70, s13
	v_bfe_u32 v70, v65, 16, 1
	v_lshrrev_b32_e32 v64, 16, v64
	v_add3_u32 v65, v65, v70, s13
	v_and_or_b32 v70, v65, s14, v64
	v_bfe_u32 v64, v66, 16, 1
	v_add3_u32 v64, v66, v64, s13
	v_bfe_u32 v65, v67, 16, 1
	v_lshrrev_b32_e32 v64, 16, v64
	v_add3_u32 v65, v67, v65, s13
	v_and_or_b32 v71, v65, s14, v64
	v_mad_i64_i32 v[64:65], s[6:7], v84, s15, v[78:79]
	global_store_dwordx4 v[64:65], v[68:71], off
	v_bfe_u32 v65, v60, 16, 1
	v_add3_u32 v60, v60, v65, s13
	v_bfe_u32 v65, v61, 16, 1
	v_lshrrev_b32_e32 v60, 16, v60
	v_add3_u32 v61, v61, v65, s13
	v_and_or_b32 v60, v61, s14, v60
	v_bfe_u32 v61, v62, 16, 1
	v_add3_u32 v61, v62, v61, s13
	v_bfe_u32 v62, v63, 16, 1
	v_lshrrev_b32_e32 v61, 16, v61
	v_add3_u32 v62, v63, v62, s13
	v_and_or_b32 v61, v62, s14, v61
	v_bfe_u32 v62, v56, 16, 1
	v_add3_u32 v56, v56, v62, s13
	v_bfe_u32 v62, v57, 16, 1
	v_lshrrev_b32_e32 v56, 16, v56
	v_add3_u32 v57, v57, v62, s13
	v_and_or_b32 v62, v57, s14, v56
	v_bfe_u32 v56, v58, 16, 1
	v_add3_u32 v56, v58, v56, s13
	v_bfe_u32 v57, v59, 16, 1
	v_or_b32_e32 v64, 64, v128
	v_lshrrev_b32_e32 v56, 16, v56
	v_add3_u32 v57, v59, v57, s13
	v_and_or_b32 v63, v57, s14, v56
	v_mad_i64_i32 v[56:57], s[6:7], v64, s15, v[76:77]
	global_store_dwordx4 v[56:57], v[60:63], off
	v_bfe_u32 v56, v52, 16, 1
	v_add3_u32 v52, v52, v56, s13
	v_bfe_u32 v56, v53, 16, 1
	v_lshrrev_b32_e32 v52, 16, v52
	v_add3_u32 v53, v53, v56, s13
	v_and_or_b32 v52, v53, s14, v52
	v_bfe_u32 v53, v54, 16, 1
	v_add3_u32 v53, v54, v53, s13
	v_bfe_u32 v54, v55, 16, 1
	v_lshrrev_b32_e32 v53, 16, v53
	v_add3_u32 v54, v55, v54, s13
	v_and_or_b32 v53, v54, s14, v53
	v_bfe_u32 v54, v48, 16, 1
	v_add3_u32 v48, v48, v54, s13
	v_bfe_u32 v54, v49, 16, 1
	v_lshrrev_b32_e32 v48, 16, v48
	v_add3_u32 v49, v49, v54, s13
	v_and_or_b32 v54, v49, s14, v48
	v_bfe_u32 v48, v50, 16, 1
	v_add3_u32 v48, v50, v48, s13
	v_bfe_u32 v49, v51, 16, 1
	v_lshrrev_b32_e32 v48, 16, v48
	v_add3_u32 v49, v51, v49, s13
	v_and_or_b32 v55, v49, s14, v48
	v_mad_i64_i32 v[48:49], s[6:7], v64, s15, v[78:79]
	global_store_dwordx4 v[48:49], v[52:55], off
	v_bfe_u32 v49, v44, 16, 1
	v_add3_u32 v44, v44, v49, s13
	v_bfe_u32 v49, v45, 16, 1
	v_lshrrev_b32_e32 v44, 16, v44
	v_add3_u32 v45, v45, v49, s13
	v_and_or_b32 v44, v45, s14, v44
	v_bfe_u32 v45, v46, 16, 1
	v_add3_u32 v45, v46, v45, s13
	v_bfe_u32 v46, v47, 16, 1
	v_lshrrev_b32_e32 v45, 16, v45
	v_add3_u32 v46, v47, v46, s13
	v_and_or_b32 v45, v46, s14, v45
	v_bfe_u32 v46, v40, 16, 1
	v_add3_u32 v40, v40, v46, s13
	v_bfe_u32 v46, v41, 16, 1
	v_lshrrev_b32_e32 v40, 16, v40
	v_add3_u32 v41, v41, v46, s13
	v_and_or_b32 v46, v41, s14, v40
	v_bfe_u32 v40, v42, 16, 1
	v_add3_u32 v40, v42, v40, s13
	v_bfe_u32 v41, v43, 16, 1
	v_or_b32_e32 v48, 0x50, v128
	v_lshrrev_b32_e32 v40, 16, v40
	v_add3_u32 v41, v43, v41, s13
	v_and_or_b32 v47, v41, s14, v40
	v_mad_i64_i32 v[40:41], s[6:7], v48, s15, v[76:77]
	global_store_dwordx4 v[40:41], v[44:47], off
	v_bfe_u32 v40, v36, 16, 1
	v_add3_u32 v36, v36, v40, s13
	v_bfe_u32 v40, v37, 16, 1
	v_lshrrev_b32_e32 v36, 16, v36
	v_add3_u32 v37, v37, v40, s13
	v_and_or_b32 v36, v37, s14, v36
	v_bfe_u32 v37, v38, 16, 1
	v_add3_u32 v37, v38, v37, s13
	v_bfe_u32 v38, v39, 16, 1
	v_lshrrev_b32_e32 v37, 16, v37
	v_add3_u32 v38, v39, v38, s13
	v_and_or_b32 v37, v38, s14, v37
	v_bfe_u32 v38, v32, 16, 1
	v_add3_u32 v32, v32, v38, s13
	v_bfe_u32 v38, v33, 16, 1
	v_lshrrev_b32_e32 v32, 16, v32
	v_add3_u32 v33, v33, v38, s13
	v_and_or_b32 v38, v33, s14, v32
	v_bfe_u32 v32, v34, 16, 1
	v_add3_u32 v32, v34, v32, s13
	v_bfe_u32 v33, v35, 16, 1
	v_lshrrev_b32_e32 v32, 16, v32
	v_add3_u32 v33, v35, v33, s13
	v_and_or_b32 v39, v33, s14, v32
	v_mad_i64_i32 v[32:33], s[6:7], v48, s15, v[78:79]
	global_store_dwordx4 v[32:33], v[36:39], off
	v_bfe_u32 v33, v28, 16, 1
	v_add3_u32 v28, v28, v33, s13
	v_bfe_u32 v33, v29, 16, 1
	v_lshrrev_b32_e32 v28, 16, v28
	v_add3_u32 v29, v29, v33, s13
	v_and_or_b32 v28, v29, s14, v28
	v_bfe_u32 v29, v30, 16, 1
	v_add3_u32 v29, v30, v29, s13
	v_bfe_u32 v30, v31, 16, 1
	v_lshrrev_b32_e32 v29, 16, v29
	v_add3_u32 v30, v31, v30, s13
	v_and_or_b32 v29, v30, s14, v29
	v_bfe_u32 v30, v24, 16, 1
	v_add3_u32 v24, v24, v30, s13
	v_bfe_u32 v30, v25, 16, 1
	v_lshrrev_b32_e32 v24, 16, v24
	v_add3_u32 v25, v25, v30, s13
	v_and_or_b32 v30, v25, s14, v24
	v_bfe_u32 v24, v26, 16, 1
	v_add3_u32 v24, v26, v24, s13
	v_bfe_u32 v25, v27, 16, 1
	v_or_b32_e32 v32, 0x60, v128
	v_lshrrev_b32_e32 v24, 16, v24
	v_add3_u32 v25, v27, v25, s13
	v_and_or_b32 v31, v25, s14, v24
	v_mad_i64_i32 v[24:25], s[6:7], v32, s15, v[76:77]
	global_store_dwordx4 v[24:25], v[28:31], off
	v_bfe_u32 v24, v20, 16, 1
	v_add3_u32 v20, v20, v24, s13
	v_bfe_u32 v24, v21, 16, 1
	v_lshrrev_b32_e32 v20, 16, v20
	v_add3_u32 v21, v21, v24, s13
	v_and_or_b32 v20, v21, s14, v20
	v_bfe_u32 v21, v22, 16, 1
	v_add3_u32 v21, v22, v21, s13
	v_bfe_u32 v22, v23, 16, 1
	v_lshrrev_b32_e32 v21, 16, v21
	v_add3_u32 v22, v23, v22, s13
	v_and_or_b32 v21, v22, s14, v21
	v_bfe_u32 v22, v16, 16, 1
	v_add3_u32 v16, v16, v22, s13
	v_bfe_u32 v22, v17, 16, 1
	v_lshrrev_b32_e32 v16, 16, v16
	v_add3_u32 v17, v17, v22, s13
	v_and_or_b32 v22, v17, s14, v16
	v_bfe_u32 v16, v18, 16, 1
	v_add3_u32 v16, v18, v16, s13
	v_bfe_u32 v17, v19, 16, 1
	v_lshrrev_b32_e32 v16, 16, v16
	v_add3_u32 v17, v19, v17, s13
	v_and_or_b32 v23, v17, s14, v16
	v_mad_i64_i32 v[16:17], s[6:7], v32, s15, v[78:79]
	global_store_dwordx4 v[16:17], v[20:23], off
	v_bfe_u32 v17, v12, 16, 1
	v_add3_u32 v12, v12, v17, s13
	v_bfe_u32 v17, v13, 16, 1
	v_lshrrev_b32_e32 v12, 16, v12
	v_add3_u32 v13, v13, v17, s13
	v_and_or_b32 v12, v13, s14, v12
	v_bfe_u32 v13, v14, 16, 1
	v_add3_u32 v13, v14, v13, s13
	v_bfe_u32 v14, v15, 16, 1
	v_lshrrev_b32_e32 v13, 16, v13
	v_add3_u32 v14, v15, v14, s13
	v_and_or_b32 v13, v14, s14, v13
	v_bfe_u32 v14, v8, 16, 1
	v_add3_u32 v8, v8, v14, s13
	v_bfe_u32 v14, v9, 16, 1
	v_lshrrev_b32_e32 v8, 16, v8
	v_add3_u32 v9, v9, v14, s13
	v_and_or_b32 v14, v9, s14, v8
	v_bfe_u32 v8, v10, 16, 1
	v_add3_u32 v8, v10, v8, s13
	v_bfe_u32 v9, v11, 16, 1
	v_or_b32_e32 v16, 0x70, v128
	v_lshrrev_b32_e32 v8, 16, v8
	v_add3_u32 v9, v11, v9, s13
	v_and_or_b32 v15, v9, s14, v8
	v_mad_i64_i32 v[8:9], s[6:7], v16, s15, v[76:77]
	global_store_dwordx4 v[8:9], v[12:15], off
	v_bfe_u32 v8, v4, 16, 1
	v_add3_u32 v4, v4, v8, s13
	v_bfe_u32 v8, v5, 16, 1
	v_lshrrev_b32_e32 v4, 16, v4
	v_add3_u32 v5, v5, v8, s13
	v_and_or_b32 v4, v5, s14, v4
	v_bfe_u32 v5, v6, 16, 1
	v_add3_u32 v5, v6, v5, s13
	v_bfe_u32 v6, v7, 16, 1
	v_lshrrev_b32_e32 v5, 16, v5
	v_add3_u32 v6, v7, v6, s13
	v_and_or_b32 v5, v6, s14, v5
	v_bfe_u32 v6, v0, 16, 1
	v_add3_u32 v0, v0, v6, s13
	v_bfe_u32 v6, v1, 16, 1
	v_lshrrev_b32_e32 v0, 16, v0
	v_add3_u32 v1, v1, v6, s13
	v_and_or_b32 v6, v1, s14, v0
	v_bfe_u32 v0, v2, 16, 1
	v_add3_u32 v0, v2, v0, s13
	v_bfe_u32 v1, v3, 16, 1
	v_lshrrev_b32_e32 v0, 16, v0
	v_add3_u32 v1, v3, v1, s13
	s_add_i32 s10, s10, s11
	v_and_or_b32 v7, v1, s14, v0
	v_mad_i64_i32 v[0:1], s[6:7], v16, s15, v[78:79]
	s_cmpk_lt_i32 s16, 0x580
	global_store_dwordx4 v[0:1], v[4:7], off
	s_cbranch_scc1 .LBB0_886
	v_readlane_b32 s16, v254, 56

.LBB0_1259:
	s_add_i32 s16, s15, 2
	s_mul_hi_i32 s17, s16, 0x55555556
	s_lshr_b32 s18, s17, 31
	s_add_i32 s17, s17, s18
	s_mul_i32 s17, s17, 3
	s_sub_i32 s16, s16, s17
	s_mulk_i32 s16, 0x6000
	s_mul_i32 s54, s15, 0x6000
	v_readfirstlane_b32 s55, v144
	v_lshl_add_u64 v[232:233], v[136:137], 0, s[4:5]
	v_lshl_add_u64 v[234:235], v[134:135], 0, s[4:5]
	s_add_u32 s55, s55, s16
	s_waitcnt vmcnt(6) lgkmcnt(0)
	s_barrier
	s_setprio 1
	s_mov_b32 m0, s55
	s_mov_b64 s[16:17], 0x8bc0080
	v_lshl_add_u64 v[236:237], v[232:233], 0, s[16:17]
	global_load_lds_dwordx4 v[236:237], off
	s_add_u32 m0, s55, 0x1000
	s_mov_b64 s[16:17], 0x8bec080
	v_lshl_add_u64 v[236:237], v[232:233], 0, s[16:17]
	global_load_lds_dwordx4 v[236:237], off
	s_add_u32 m0, s55, 0x2000
	s_mov_b64 s[16:17], 0x8c18080
	v_lshl_add_u64 v[236:237], v[232:233], 0, s[16:17]
	global_load_lds_dwordx4 v[236:237], off
	s_add_u32 m0, s55, 0x3000
	s_mov_b64 s[16:17], 0x8c44080
	v_lshl_add_u64 v[236:237], v[232:233], 0, s[16:17]
	global_load_lds_dwordx4 v[236:237], off
	s_add_u32 m0, s55, 0x4000
	s_mov_b64 s[16:17], 0xe40080
	v_lshl_add_u64 v[236:237], v[234:235], 0, s[16:17]
	global_load_lds_dwordx4 v[236:237], off
	s_add_u32 m0, s55, 0x5000
	s_mov_b64 s[16:17], 0xe6c080
	v_lshl_add_u64 v[236:237], v[234:235], 0, s[16:17]
	global_load_lds_dwordx4 v[236:237], off
	v_or_b32_e32 v130, s54, v142
	v_add3_u32 v130, v130, v143, v141
	ds_read_b128 v[178:181], v130 offset:16384
	ds_read_b128 v[182:185], v130 offset:16640
	ds_read_b128 v[186:189], v130 offset:18432
	ds_read_b128 v[192:195], v130 offset:18688
	v_add3_u32 v130, s54, v145, v141
	ds_read_b128 v[146:149], v130
	ds_read_b128 v[150:153], v130 offset:1024
	ds_read_b128 v[154:157], v130 offset:2048
	ds_read_b128 v[158:161], v130 offset:3072
	ds_read_b128 v[162:165], v130 offset:4096
	ds_read_b128 v[166:169], v130 offset:5120
	ds_read_b128 v[170:173], v130 offset:6144
	ds_read_b128 v[174:177], v130 offset:7168
	s_setprio 0
	s_waitcnt lgkmcnt(7)
	v_mfma_f32_16x16x32_bf16 v[124:127], v[178:181], v[146:149], v[124:127]
	v_mfma_f32_16x16x32_bf16 v[120:123], v[182:185], v[146:149], v[120:123]
	v_mfma_f32_16x16x32_bf16 v[116:119], v[186:189], v[146:149], v[116:119]
	v_mfma_f32_16x16x32_bf16 v[112:115], v[192:195], v[146:149], v[112:115]
	s_waitcnt lgkmcnt(6)
	v_mfma_f32_16x16x32_bf16 v[108:111], v[178:181], v[150:153], v[108:111]
	v_mfma_f32_16x16x32_bf16 v[104:107], v[182:185], v[150:153], v[104:107]
	v_mfma_f32_16x16x32_bf16 v[100:103], v[186:189], v[150:153], v[100:103]
	v_mfma_f32_16x16x32_bf16 v[96:99], v[192:195], v[150:153], v[96:99]
	s_waitcnt lgkmcnt(5)
	v_mfma_f32_16x16x32_bf16 v[92:95], v[178:181], v[154:157], v[92:95]
	v_mfma_f32_16x16x32_bf16 v[88:91], v[182:185], v[154:157], v[88:91]
	v_mfma_f32_16x16x32_bf16 v[84:87], v[186:189], v[154:157], v[84:87]
	v_mfma_f32_16x16x32_bf16 v[80:83], v[192:195], v[154:157], v[80:83]
	s_waitcnt lgkmcnt(4)
	v_mfma_f32_16x16x32_bf16 v[76:79], v[178:181], v[158:161], v[76:79]
	v_mfma_f32_16x16x32_bf16 v[72:75], v[182:185], v[158:161], v[72:75]
	v_mfma_f32_16x16x32_bf16 v[68:71], v[186:189], v[158:161], v[68:71]
	v_mfma_f32_16x16x32_bf16 v[64:67], v[192:195], v[158:161], v[64:67]
	s_waitcnt lgkmcnt(3)
	v_mfma_f32_16x16x32_bf16 v[60:63], v[178:181], v[162:165], v[60:63]
	v_mfma_f32_16x16x32_bf16 v[56:59], v[182:185], v[162:165], v[56:59]
	v_mfma_f32_16x16x32_bf16 v[52:55], v[186:189], v[162:165], v[52:55]
	v_mfma_f32_16x16x32_bf16 v[48:51], v[192:195], v[162:165], v[48:51]
	s_waitcnt lgkmcnt(2)
	v_mfma_f32_16x16x32_bf16 v[44:47], v[178:181], v[166:169], v[44:47]
	v_mfma_f32_16x16x32_bf16 v[40:43], v[182:185], v[166:169], v[40:43]
	v_mfma_f32_16x16x32_bf16 v[36:39], v[186:189], v[166:169], v[36:39]
	v_mfma_f32_16x16x32_bf16 v[32:35], v[192:195], v[166:169], v[32:35]
	s_waitcnt lgkmcnt(1)
	v_mfma_f32_16x16x32_bf16 v[28:31], v[178:181], v[170:173], v[28:31]
	v_mfma_f32_16x16x32_bf16 v[24:27], v[182:185], v[170:173], v[24:27]
	v_mfma_f32_16x16x32_bf16 v[20:23], v[186:189], v[170:173], v[20:23]
	v_mfma_f32_16x16x32_bf16 v[16:19], v[192:195], v[170:173], v[16:19]
	s_waitcnt lgkmcnt(0)
	v_mfma_f32_16x16x32_bf16 v[12:15], v[178:181], v[174:177], v[12:15]
	v_mfma_f32_16x16x32_bf16 v[8:11], v[182:185], v[174:177], v[8:11]
	v_mfma_f32_16x16x32_bf16 v[4:7], v[186:189], v[174:177], v[4:7]
	v_mfma_f32_16x16x32_bf16 v[0:3], v[192:195], v[174:177], v[0:3]
	s_add_i32 s16, s15, 1
	s_cmp_lg_u32 s15, 2
	s_cselect_b32 s15, s16, 0
	s_add_u32 s4, s4, 64
	s_addc_u32 s5, s5, 0
	s_cmpk_eq_i32 s4, 0xa80
	s_cbranch_scc0 .LBB0_1259
	s_waitcnt vmcnt(6) lgkmcnt(0)
	s_barrier
	v_add_u32_e32 v130, v145, v141
	ds_read_b128 v[134:137], v130
	ds_read_b128 v[144:147], v130 offset:1024
	ds_read_b128 v[148:151], v130 offset:2048
	ds_read_b128 v[152:155], v130 offset:3072
	ds_read_b128 v[156:159], v130 offset:4096
	ds_read_b128 v[160:163], v130 offset:5120
	ds_read_b128 v[164:167], v130 offset:6144
	ds_read_b128 v[168:171], v130 offset:7168
	v_add3_u32 v141, v142, v143, v141
	ds_read_b128 v[172:175], v141 offset:16384
	ds_read_b128 v[176:179], v141 offset:16640
	ds_read_b128 v[180:183], v141 offset:18432
	ds_read_b128 v[184:187], v141 offset:18688
	s_setprio 1
	s_waitcnt lgkmcnt(0)
	v_mfma_f32_16x16x32_bf16 v[124:127], v[172:175], v[134:137], v[124:127]
	v_mfma_f32_16x16x32_bf16 v[120:123], v[176:179], v[134:137], v[120:123]
	v_mfma_f32_16x16x32_bf16 v[116:119], v[180:183], v[134:137], v[116:119]
	v_mfma_f32_16x16x32_bf16 v[112:115], v[184:187], v[134:137], v[112:115]
	v_mfma_f32_16x16x32_bf16 v[108:111], v[172:175], v[144:147], v[108:111]
	v_mfma_f32_16x16x32_bf16 v[104:107], v[176:179], v[144:147], v[104:107]
	v_mfma_f32_16x16x32_bf16 v[100:103], v[180:183], v[144:147], v[100:103]
	v_mfma_f32_16x16x32_bf16 v[96:99], v[184:187], v[144:147], v[96:99]
	v_mfma_f32_16x16x32_bf16 v[92:95], v[172:175], v[148:151], v[92:95]
	v_mfma_f32_16x16x32_bf16 v[88:91], v[176:179], v[148:151], v[88:91]
	v_mfma_f32_16x16x32_bf16 v[84:87], v[180:183], v[148:151], v[84:87]
	v_mfma_f32_16x16x32_bf16 v[80:83], v[184:187], v[148:151], v[80:83]
	v_mfma_f32_16x16x32_bf16 v[76:79], v[172:175], v[152:155], v[76:79]
	v_mfma_f32_16x16x32_bf16 v[72:75], v[176:179], v[152:155], v[72:75]
	v_mfma_f32_16x16x32_bf16 v[68:71], v[180:183], v[152:155], v[68:71]
	v_mfma_f32_16x16x32_bf16 v[64:67], v[184:187], v[152:155], v[64:67]
	v_mfma_f32_16x16x32_bf16 v[60:63], v[172:175], v[156:159], v[60:63]
	v_mfma_f32_16x16x32_bf16 v[56:59], v[176:179], v[156:159], v[56:59]
	v_mfma_f32_16x16x32_bf16 v[52:55], v[180:183], v[156:159], v[52:55]
	v_mfma_f32_16x16x32_bf16 v[48:51], v[184:187], v[156:159], v[48:51]
	v_mfma_f32_16x16x32_bf16 v[44:47], v[172:175], v[160:163], v[44:47]
	v_mfma_f32_16x16x32_bf16 v[40:43], v[176:179], v[160:163], v[40:43]
	v_mfma_f32_16x16x32_bf16 v[36:39], v[180:183], v[160:163], v[36:39]
	v_mfma_f32_16x16x32_bf16 v[32:35], v[184:187], v[160:163], v[32:35]
	v_mfma_f32_16x16x32_bf16 v[28:31], v[172:175], v[164:167], v[28:31]
	v_mfma_f32_16x16x32_bf16 v[24:27], v[176:179], v[164:167], v[24:27]
	v_mfma_f32_16x16x32_bf16 v[20:23], v[180:183], v[164:167], v[20:23]
	v_mfma_f32_16x16x32_bf16 v[16:19], v[184:187], v[164:167], v[16:19]
	v_mfma_f32_16x16x32_bf16 v[12:15], v[172:175], v[168:171], v[12:15]
	v_mfma_f32_16x16x32_bf16 v[8:11], v[176:179], v[168:171], v[8:11]
	v_mfma_f32_16x16x32_bf16 v[4:7], v[180:183], v[168:171], v[4:7]
	v_mfma_f32_16x16x32_bf16 v[0:3], v[184:187], v[168:171], v[0:3]
	s_setprio 0
	s_waitcnt vmcnt(0) lgkmcnt(0)
	s_barrier
	ds_read_b128 v[134:137], v130 offset:24576
	ds_read_b128 v[142:145], v130 offset:25600
	ds_read_b128 v[146:149], v130 offset:26624
	ds_read_b128 v[150:153], v130 offset:27648
	ds_read_b128 v[154:157], v130 offset:28672
	ds_read_b128 v[158:161], v130 offset:29696
	ds_read_b128 v[162:165], v130 offset:30720
	ds_read_b128 v[166:169], v130 offset:31744
	ds_read_b128 v[170:173], v141 offset:40960
	ds_read_b128 v[174:177], v141 offset:41216
	ds_read_b128 v[178:181], v141 offset:43008
	ds_read_b128 v[182:185], v141 offset:43264
	s_setprio 1
	s_waitcnt lgkmcnt(0)
	v_mfma_f32_16x16x32_bf16 v[124:127], v[170:173], v[134:137], v[124:127]
	v_mfma_f32_16x16x32_bf16 v[120:123], v[174:177], v[134:137], v[120:123]
	v_mfma_f32_16x16x32_bf16 v[116:119], v[178:181], v[134:137], v[116:119]
	v_mfma_f32_16x16x32_bf16 v[112:115], v[182:185], v[134:137], v[112:115]
	v_mfma_f32_16x16x32_bf16 v[108:111], v[170:173], v[142:145], v[108:111]
	v_mfma_f32_16x16x32_bf16 v[104:107], v[174:177], v[142:145], v[104:107]
	v_mfma_f32_16x16x32_bf16 v[134:137], v[178:181], v[142:145], v[100:103]
	v_mfma_f32_16x16x32_bf16 v[96:99], v[182:185], v[142:145], v[96:99]
	v_mfma_f32_16x16x32_bf16 v[92:95], v[170:173], v[146:149], v[92:95]
	v_mfma_f32_16x16x32_bf16 v[88:91], v[174:177], v[146:149], v[88:91]
	v_mfma_f32_16x16x32_bf16 v[84:87], v[178:181], v[146:149], v[84:87]
	v_mfma_f32_16x16x32_bf16 v[80:83], v[182:185], v[146:149], v[80:83]
	v_mfma_f32_16x16x32_bf16 v[76:79], v[170:173], v[150:153], v[76:79]
	v_mfma_f32_16x16x32_bf16 v[72:75], v[174:177], v[150:153], v[72:75]
	v_mfma_f32_16x16x32_bf16 v[68:71], v[178:181], v[150:153], v[68:71]
	v_mfma_f32_16x16x32_bf16 v[64:67], v[182:185], v[150:153], v[64:67]
	v_mfma_f32_16x16x32_bf16 v[60:63], v[170:173], v[154:157], v[60:63]
	v_mfma_f32_16x16x32_bf16 v[56:59], v[174:177], v[154:157], v[56:59]
	v_mfma_f32_16x16x32_bf16 v[52:55], v[178:181], v[154:157], v[52:55]
	v_mfma_f32_16x16x32_bf16 v[48:51], v[182:185], v[154:157], v[48:51]
	v_mfma_f32_16x16x32_bf16 v[44:47], v[170:173], v[158:161], v[44:47]
	v_mfma_f32_16x16x32_bf16 v[40:43], v[174:177], v[158:161], v[40:43]
	v_mfma_f32_16x16x32_bf16 v[36:39], v[178:181], v[158:161], v[36:39]
	v_mfma_f32_16x16x32_bf16 v[32:35], v[182:185], v[158:161], v[32:35]
	v_mfma_f32_16x16x32_bf16 v[28:31], v[170:173], v[162:165], v[28:31]
	v_mfma_f32_16x16x32_bf16 v[24:27], v[174:177], v[162:165], v[24:27]
	v_mfma_f32_16x16x32_bf16 v[20:23], v[178:181], v[162:165], v[20:23]
	v_mfma_f32_16x16x32_bf16 v[16:19], v[182:185], v[162:165], v[16:19]
	v_mfma_f32_16x16x32_bf16 v[12:15], v[170:173], v[166:169], v[12:15]
	v_mfma_f32_16x16x32_bf16 v[8:11], v[174:177], v[166:169], v[8:11]
	v_mfma_f32_16x16x32_bf16 v[4:7], v[178:181], v[166:169], v[4:7]
	v_mfma_f32_16x16x32_bf16 v[0:3], v[182:185], v[166:169], v[0:3]
	s_setprio 0
	v_and_b32_e32 v100, 0xffffff80, v138
	v_lshrrev_b32_e32 v102, 1, v138
	v_add_u32_e32 v100, s13, v100
	v_lshlrev_b32_e32 v101, 6, v140
	v_and_b32_e32 v102, 24, v102
	v_or_b32_e32 v100, v100, v139
	v_or3_b32 v102, v101, v102, s14
	v_mov_b32_e32 v101, v131
	v_add_u32_e32 v130, 0xffffc000, v100
	v_readlane_b32 s4, v255, 39
	v_lshlrev_b64 v[142:143], 12, v[100:101]
	v_ashrrev_i32_e32 v101, 31, v100
	v_readlane_b32 s16, v254, 34
	v_lshlrev_b64 v[138:139], 12, v[130:131]
	v_readlane_b32 s5, v255, 40
	v_lshlrev_b64 v[144:145], 12, v[100:101]
	v_readlane_b32 s30, v254, 48
	v_readlane_b32 s31, v254, 49
	v_lshl_add_u64 v[138:139], s[4:5], 0, v[138:139]
	v_cmp_gt_i32_e32 vcc, s11, v100
	v_lshl_add_u64 v[140:141], s[30:31], 0, v[144:145]
	v_ashrrev_i32_e32 v103, 31, v102
	v_cndmask_b32_e32 v139, v139, v141, vcc
	v_cndmask_b32_e32 v138, v138, v140, vcc
	v_lshlrev_b64 v[102:103], 2, v[102:103]
	v_lshl_add_u64 v[146:147], v[138:139], 0, v[102:103]
	global_load_dwordx4 v[138:141], v[146:147], off
	v_cndmask_b32_e32 v143, v143, v145, vcc
	v_cndmask_b32_e32 v142, v142, v144, vcc
	v_lshl_add_u64 v[142:143], s[30:31], 0, v[142:143]
	v_lshl_add_u64 v[142:143], v[142:143], 0, v[102:103]
	v_add_u32_e32 v130, 0xffffc010, v100
	s_add_i32 s12, s12, s86
	s_add_i32 s6, s6, s7
	s_add_i32 s8, s8, s9
	s_cmpk_gt_i32 s12, 0x1ff
	v_readlane_b32 s17, v254, 35
	v_readlane_b32 s18, v254, 36
	v_readlane_b32 s19, v254, 37
	v_readlane_b32 s20, v254, 38
	v_readlane_b32 s21, v254, 39
	v_readlane_b32 s22, v254, 40
	v_readlane_b32 s23, v254, 41
	v_readlane_b32 s24, v254, 42
	v_readlane_b32 s25, v254, 43
	v_readlane_b32 s26, v254, 44
	v_readlane_b32 s27, v254, 45
	v_readlane_b32 s28, v254, 46
	v_readlane_b32 s29, v254, 47
	s_waitcnt vmcnt(0)
	v_pk_add_f32 v[124:125], v[124:125], v[138:139]
	v_pk_add_f32 v[126:127], v[126:127], v[140:141]
	global_store_dwordx4 v[142:143], v[124:127], off
	global_load_dwordx4 v[124:127], v[146:147], off offset:16
	s_waitcnt vmcnt(0)
	v_pk_add_f32 v[120:121], v[120:121], v[124:125]
	v_pk_add_f32 v[122:123], v[122:123], v[126:127]
	global_store_dwordx4 v[142:143], v[120:123], off offset:16
	global_load_dwordx4 v[120:123], v[146:147], off offset:128
	v_lshlrev_b64 v[124:125], 12, v[130:131]
	v_lshl_add_u64 v[124:125], s[4:5], 0, v[124:125]
	v_add_u32_e32 v130, 0xffffc020, v100
	s_waitcnt vmcnt(0)
	v_pk_add_f32 v[116:117], v[116:117], v[120:121]
	v_pk_add_f32 v[118:119], v[118:119], v[122:123]
	global_store_dwordx4 v[142:143], v[116:119], off offset:128
	global_load_dwordx4 v[116:119], v[146:147], off offset:144
	v_mov_b32_e32 v121, v131
	v_or_b32_e32 v120, 16, v100
	v_lshlrev_b64 v[122:123], 12, v[120:121]
	v_ashrrev_i32_e32 v121, 31, v120
	v_lshlrev_b64 v[126:127], 12, v[120:121]
	v_lshl_add_u64 v[138:139], s[30:31], 0, v[126:127]
	v_cmp_gt_i32_e32 vcc, s11, v120
	s_waitcnt vmcnt(0)
	v_pk_add_f32 v[112:113], v[112:113], v[116:117]
	v_cndmask_b32_e32 v125, v125, v139, vcc
	v_cndmask_b32_e32 v124, v124, v138, vcc
	v_pk_add_f32 v[114:115], v[114:115], v[118:119]
	v_lshl_add_u64 v[124:125], v[124:125], 0, v[102:103]
	global_store_dwordx4 v[142:143], v[112:115], off offset:144
	global_load_dwordx4 v[112:115], v[124:125], off
	v_cndmask_b32_e32 v121, v123, v127, vcc
	v_cndmask_b32_e32 v120, v122, v126, vcc
	v_lshl_add_u64 v[116:117], s[30:31], 0, v[120:121]
	v_lshl_add_u64 v[116:117], v[116:117], 0, v[102:103]
	s_waitcnt vmcnt(0)
	v_pk_add_f32 v[108:109], v[108:109], v[112:113]
	v_pk_add_f32 v[110:111], v[110:111], v[114:115]
	global_store_dwordx4 v[116:117], v[108:111], off
	global_load_dwordx4 v[108:111], v[124:125], off offset:16
	v_lshlrev_b64 v[114:115], 12, v[130:131]
	v_lshl_add_u64 v[114:115], s[4:5], 0, v[114:115]
	v_add_u32_e32 v130, 0xffffc030, v100
	s_waitcnt vmcnt(0)
	v_pk_add_f32 v[104:105], v[104:105], v[108:109]
	v_pk_add_f32 v[106:107], v[106:107], v[110:111]
	global_store_dwordx4 v[116:117], v[104:107], off offset:16
	global_load_dwordx4 v[104:107], v[124:125], off offset:128
	v_mov_b32_e32 v109, v131
	v_or_b32_e32 v108, 32, v100
	v_lshlrev_b64 v[110:111], 12, v[108:109]
	v_ashrrev_i32_e32 v109, 31, v108
	v_lshlrev_b64 v[112:113], 12, v[108:109]
	v_lshl_add_u64 v[118:119], s[30:31], 0, v[112:113]
	v_cmp_gt_i32_e32 vcc, s11, v108
	s_waitcnt vmcnt(0)
	v_pk_add_f32 v[104:105], v[134:135], v[104:105]
	v_pk_add_f32 v[106:107], v[136:137], v[106:107]
	global_store_dwordx4 v[116:117], v[104:107], off offset:128
	global_load_dwordx4 v[104:107], v[124:125], off offset:144
	v_cndmask_b32_e32 v115, v115, v119, vcc
	v_cndmask_b32_e32 v114, v114, v118, vcc
	v_lshl_add_u64 v[114:115], v[114:115], 0, v[102:103]
	v_cndmask_b32_e32 v109, v111, v113, vcc
	v_cndmask_b32_e32 v108, v110, v112, vcc
	s_waitcnt vmcnt(0)
	v_pk_add_f32 v[96:97], v[96:97], v[104:105]
	v_pk_add_f32 v[98:99], v[98:99], v[106:107]
	global_store_dwordx4 v[116:117], v[96:99], off offset:144
	global_load_dwordx4 v[96:99], v[114:115], off
	v_lshl_add_u64 v[104:105], s[30:31], 0, v[108:109]
	v_lshl_add_u64 v[104:105], v[104:105], 0, v[102:103]
	s_waitcnt vmcnt(0)
	v_pk_add_f32 v[92:93], v[92:93], v[96:97]
	v_pk_add_f32 v[94:95], v[94:95], v[98:99]
	global_store_dwordx4 v[104:105], v[92:95], off
	global_load_dwordx4 v[92:95], v[114:115], off offset:16
	v_lshlrev_b64 v[96:97], 12, v[130:131]
	v_lshl_add_u64 v[96:97], s[4:5], 0, v[96:97]
	v_add_u32_e32 v130, 0xffffc040, v100
	s_waitcnt vmcnt(0)
	v_pk_add_f32 v[88:89], v[88:89], v[92:93]
	v_pk_add_f32 v[90:91], v[90:91], v[94:95]
	global_store_dwordx4 v[104:105], v[88:91], off offset:16
	global_load_dwordx4 v[88:91], v[114:115], off offset:128
	s_waitcnt vmcnt(0)
	v_pk_add_f32 v[84:85], v[84:85], v[88:89]
	v_pk_add_f32 v[86:87], v[86:87], v[90:91]
	global_store_dwordx4 v[104:105], v[84:87], off offset:128
	global_load_dwordx4 v[84:87], v[114:115], off offset:144
	v_mov_b32_e32 v89, v131
	v_or_b32_e32 v88, 48, v100
	v_lshlrev_b64 v[90:91], 12, v[88:89]
	v_ashrrev_i32_e32 v89, 31, v88
	v_lshlrev_b64 v[92:93], 12, v[88:89]
	v_lshl_add_u64 v[94:95], s[30:31], 0, v[92:93]
	v_cmp_gt_i32_e32 vcc, s11, v88
	s_waitcnt vmcnt(0)
	v_pk_add_f32 v[80:81], v[80:81], v[84:85]
	v_cndmask_b32_e32 v95, v97, v95, vcc
	v_cndmask_b32_e32 v94, v96, v94, vcc
	v_pk_add_f32 v[82:83], v[82:83], v[86:87]
	v_lshl_add_u64 v[94:95], v[94:95], 0, v[102:103]
	global_store_dwordx4 v[104:105], v[80:83], off offset:144
	global_load_dwordx4 v[80:83], v[94:95], off
	v_cndmask_b32_e32 v89, v91, v93, vcc
	v_cndmask_b32_e32 v88, v90, v92, vcc
	v_lshl_add_u64 v[84:85], s[30:31], 0, v[88:89]
	v_lshl_add_u64 v[84:85], v[84:85], 0, v[102:103]
	s_waitcnt vmcnt(0)
	v_pk_add_f32 v[76:77], v[76:77], v[80:81]
	v_pk_add_f32 v[78:79], v[78:79], v[82:83]
	global_store_dwordx4 v[84:85], v[76:79], off
	global_load_dwordx4 v[76:79], v[94:95], off offset:16
	v_lshlrev_b64 v[80:81], 12, v[130:131]
	v_lshl_add_u64 v[80:81], s[4:5], 0, v[80:81]
	v_add_u32_e32 v130, 0xffffc050, v100
	s_waitcnt vmcnt(0)
	v_pk_add_f32 v[72:73], v[72:73], v[76:77]
	v_pk_add_f32 v[74:75], v[74:75], v[78:79]
	global_store_dwordx4 v[84:85], v[72:75], off offset:16
	global_load_dwordx4 v[72:75], v[94:95], off offset:128
	s_waitcnt vmcnt(0)
	v_pk_add_f32 v[68:69], v[68:69], v[72:73]
	v_pk_add_f32 v[70:71], v[70:71], v[74:75]
	global_store_dwordx4 v[84:85], v[68:71], off offset:128
	global_load_dwordx4 v[68:71], v[94:95], off offset:144
	v_mov_b32_e32 v73, v131
	v_or_b32_e32 v72, 64, v100
	v_lshlrev_b64 v[74:75], 12, v[72:73]
	v_ashrrev_i32_e32 v73, 31, v72
	v_lshlrev_b64 v[76:77], 12, v[72:73]
	v_lshl_add_u64 v[78:79], s[30:31], 0, v[76:77]
	v_cmp_gt_i32_e32 vcc, s11, v72
	s_waitcnt vmcnt(0)
	v_pk_add_f32 v[64:65], v[64:65], v[68:69]
	v_cndmask_b32_e32 v79, v81, v79, vcc
	v_cndmask_b32_e32 v78, v80, v78, vcc
	v_pk_add_f32 v[66:67], v[66:67], v[70:71]
	v_lshl_add_u64 v[78:79], v[78:79], 0, v[102:103]
	global_store_dwordx4 v[84:85], v[64:67], off offset:144
	global_load_dwordx4 v[64:67], v[78:79], off
	v_cndmask_b32_e32 v73, v75, v77, vcc
	v_cndmask_b32_e32 v72, v74, v76, vcc
	v_lshl_add_u64 v[68:69], s[30:31], 0, v[72:73]
	v_lshl_add_u64 v[68:69], v[68:69], 0, v[102:103]
	s_waitcnt vmcnt(0)
	v_pk_add_f32 v[60:61], v[60:61], v[64:65]
	v_pk_add_f32 v[62:63], v[62:63], v[66:67]
	global_store_dwordx4 v[68:69], v[60:63], off
	global_load_dwordx4 v[60:63], v[78:79], off offset:16
	v_lshlrev_b64 v[64:65], 12, v[130:131]
	v_lshl_add_u64 v[64:65], s[4:5], 0, v[64:65]
	v_add_u32_e32 v130, 0xffffc060, v100
	s_waitcnt vmcnt(0)
	v_pk_add_f32 v[56:57], v[56:57], v[60:61]
	v_pk_add_f32 v[58:59], v[58:59], v[62:63]
	global_store_dwordx4 v[68:69], v[56:59], off offset:16
	global_load_dwordx4 v[56:59], v[78:79], off offset:128
	s_waitcnt vmcnt(0)
	v_pk_add_f32 v[52:53], v[52:53], v[56:57]
	v_pk_add_f32 v[54:55], v[54:55], v[58:59]
	global_store_dwordx4 v[68:69], v[52:55], off offset:128
	global_load_dwordx4 v[52:55], v[78:79], off offset:144
	v_mov_b32_e32 v57, v131
	v_or_b32_e32 v56, 0x50, v100
	v_lshlrev_b64 v[58:59], 12, v[56:57]
	v_ashrrev_i32_e32 v57, 31, v56
	v_lshlrev_b64 v[60:61], 12, v[56:57]
	v_lshl_add_u64 v[62:63], s[30:31], 0, v[60:61]
	v_cmp_gt_i32_e32 vcc, s11, v56
	s_waitcnt vmcnt(0)
	v_pk_add_f32 v[48:49], v[48:49], v[52:53]
	v_cndmask_b32_e32 v63, v65, v63, vcc
	v_cndmask_b32_e32 v62, v64, v62, vcc
	v_pk_add_f32 v[50:51], v[50:51], v[54:55]
	v_lshl_add_u64 v[62:63], v[62:63], 0, v[102:103]
	global_store_dwordx4 v[68:69], v[48:51], off offset:144
	global_load_dwordx4 v[48:51], v[62:63], off
	v_cndmask_b32_e32 v57, v59, v61, vcc
	v_cndmask_b32_e32 v56, v58, v60, vcc
	v_lshl_add_u64 v[52:53], s[30:31], 0, v[56:57]
	v_lshl_add_u64 v[52:53], v[52:53], 0, v[102:103]
	s_waitcnt vmcnt(0)
	v_pk_add_f32 v[44:45], v[44:45], v[48:49]
	v_pk_add_f32 v[46:47], v[46:47], v[50:51]
	global_store_dwordx4 v[52:53], v[44:47], off
	global_load_dwordx4 v[44:47], v[62:63], off offset:16
	v_lshlrev_b64 v[48:49], 12, v[130:131]
	v_lshl_add_u64 v[48:49], s[4:5], 0, v[48:49]
	v_add_u32_e32 v130, 0xffffc070, v100
	s_waitcnt vmcnt(0)
	v_pk_add_f32 v[40:41], v[40:41], v[44:45]
	v_pk_add_f32 v[42:43], v[42:43], v[46:47]
	global_store_dwordx4 v[52:53], v[40:43], off offset:16
	global_load_dwordx4 v[40:43], v[62:63], off offset:128
	s_waitcnt vmcnt(0)
	v_pk_add_f32 v[36:37], v[36:37], v[40:41]
	v_pk_add_f32 v[38:39], v[38:39], v[42:43]
	global_store_dwordx4 v[52:53], v[36:39], off offset:128
	global_load_dwordx4 v[36:39], v[62:63], off offset:144
	v_mov_b32_e32 v41, v131
	v_or_b32_e32 v40, 0x60, v100
	v_lshlrev_b64 v[42:43], 12, v[40:41]
	v_ashrrev_i32_e32 v41, 31, v40
	v_lshlrev_b64 v[44:45], 12, v[40:41]
	v_lshl_add_u64 v[46:47], s[30:31], 0, v[44:45]
	v_cmp_gt_i32_e32 vcc, s11, v40
	s_waitcnt vmcnt(0)
	v_pk_add_f32 v[32:33], v[32:33], v[36:37]
	v_cndmask_b32_e32 v47, v49, v47, vcc
	v_cndmask_b32_e32 v46, v48, v46, vcc
	v_pk_add_f32 v[34:35], v[34:35], v[38:39]
	v_lshl_add_u64 v[46:47], v[46:47], 0, v[102:103]
	global_store_dwordx4 v[52:53], v[32:35], off offset:144
	global_load_dwordx4 v[32:35], v[46:47], off
	v_cndmask_b32_e32 v41, v43, v45, vcc
	v_cndmask_b32_e32 v40, v42, v44, vcc
	v_lshl_add_u64 v[36:37], s[30:31], 0, v[40:41]
	v_lshl_add_u64 v[36:37], v[36:37], 0, v[102:103]
	s_waitcnt vmcnt(0)
	v_pk_add_f32 v[28:29], v[28:29], v[32:33]
	v_pk_add_f32 v[30:31], v[30:31], v[34:35]
	global_store_dwordx4 v[36:37], v[28:31], off
	global_load_dwordx4 v[28:31], v[46:47], off offset:16
	v_lshlrev_b64 v[32:33], 12, v[130:131]
	v_lshl_add_u64 v[32:33], s[4:5], 0, v[32:33]
	s_waitcnt vmcnt(0)
	v_pk_add_f32 v[24:25], v[24:25], v[28:29]
	v_pk_add_f32 v[26:27], v[26:27], v[30:31]
	global_store_dwordx4 v[36:37], v[24:27], off offset:16
	global_load_dwordx4 v[24:27], v[46:47], off offset:128
	s_waitcnt vmcnt(0)
	v_pk_add_f32 v[20:21], v[20:21], v[24:25]
	v_pk_add_f32 v[22:23], v[22:23], v[26:27]
	global_store_dwordx4 v[36:37], v[20:23], off offset:128
	global_load_dwordx4 v[20:23], v[46:47], off offset:144
	v_mov_b32_e32 v25, v131
	v_or_b32_e32 v24, 0x70, v100
	v_lshlrev_b64 v[26:27], 12, v[24:25]
	v_ashrrev_i32_e32 v25, 31, v24
	v_lshlrev_b64 v[28:29], 12, v[24:25]
	v_lshl_add_u64 v[30:31], s[30:31], 0, v[28:29]
	v_cmp_gt_i32_e32 vcc, s11, v24
	s_waitcnt vmcnt(0)
	v_pk_add_f32 v[16:17], v[16:17], v[20:21]
	v_cndmask_b32_e32 v31, v33, v31, vcc
	v_cndmask_b32_e32 v30, v32, v30, vcc
	v_pk_add_f32 v[18:19], v[18:19], v[22:23]
	v_lshl_add_u64 v[30:31], v[30:31], 0, v[102:103]
	global_store_dwordx4 v[36:37], v[16:19], off offset:144
	global_load_dwordx4 v[16:19], v[30:31], off
	v_cndmask_b32_e32 v25, v27, v29, vcc
	v_cndmask_b32_e32 v24, v26, v28, vcc
	v_lshl_add_u64 v[20:21], s[30:31], 0, v[24:25]
	v_lshl_add_u64 v[20:21], v[20:21], 0, v[102:103]
	s_waitcnt vmcnt(0)
	v_pk_add_f32 v[12:13], v[12:13], v[16:17]
	v_pk_add_f32 v[14:15], v[14:15], v[18:19]
	global_store_dwordx4 v[20:21], v[12:15], off
	global_load_dwordx4 v[12:15], v[30:31], off offset:16
	s_waitcnt vmcnt(0)
	v_pk_add_f32 v[8:9], v[8:9], v[12:13]
	v_pk_add_f32 v[10:11], v[10:11], v[14:15]
	global_store_dwordx4 v[20:21], v[8:11], off offset:16
	global_load_dwordx4 v[8:11], v[30:31], off offset:128
	s_waitcnt vmcnt(0)
	v_pk_add_f32 v[4:5], v[4:5], v[8:9]
	v_pk_add_f32 v[6:7], v[6:7], v[10:11]
	global_store_dwordx4 v[20:21], v[4:7], off offset:128
	global_load_dwordx4 v[4:7], v[30:31], off offset:144
	s_waitcnt vmcnt(0)
	v_pk_add_f32 v[0:1], v[0:1], v[4:5]
	v_pk_add_f32 v[2:3], v[2:3], v[6:7]
	global_store_dwordx4 v[20:21], v[0:3], off offset:144
	s_cbranch_scc0 .LBB0_1258

.LBB0_1322:
	s_add_i32 s46, s45, 2
	s_mul_hi_i32 s47, s46, 0x55555556
	s_lshr_b32 s48, s47, 31
	s_add_i32 s47, s47, s48
	s_mul_i32 s47, s47, 3
	s_sub_i32 s46, s46, s47
	s_mulk_i32 s46, 0x6000
	s_mul_i32 s54, s45, 0x6000
	v_readfirstlane_b32 s55, v141
	v_lshl_add_u64 v[232:233], v[132:133], 0, s[24:25]
	v_lshl_add_u64 v[234:235], v[130:131], 0, s[24:25]
	s_add_u32 s55, s55, s46
	s_waitcnt vmcnt(6) lgkmcnt(0)
	s_barrier
	s_setprio 1
	s_mov_b32 m0, s55
	v_lshl_add_u64 v[236:237], v[232:233], 0, s[12:13]
	global_load_lds_dwordx4 v[236:237], off
	s_add_u32 m0, s55, 0x1000
	v_lshl_add_u64 v[236:237], v[232:233], 0, s[14:15]
	global_load_lds_dwordx4 v[236:237], off
	s_add_u32 m0, s55, 0x2000
	v_lshl_add_u64 v[236:237], v[232:233], 0, s[16:17]
	global_load_lds_dwordx4 v[236:237], off
	s_add_u32 m0, s55, 0x3000
	v_lshl_add_u64 v[236:237], v[232:233], 0, s[18:19]
	global_load_lds_dwordx4 v[236:237], off
	s_add_u32 m0, s55, 0x4000
	v_lshl_add_u64 v[236:237], v[234:235], 0, s[20:21]
	global_load_lds_dwordx4 v[236:237], off
	s_add_u32 m0, s55, 0x5000
	v_lshl_add_u64 v[236:237], v[234:235], 0, s[22:23]
	global_load_lds_dwordx4 v[236:237], off
	v_or_b32_e32 v128, s54, v140
	v_add3_u32 v128, v128, v138, v139
	ds_read_b128 v[176:179], v128 offset:16384
	ds_read_b128 v[180:183], v128 offset:17408
	ds_read_b128 v[184:187], v128 offset:18432
	ds_read_b128 v[192:195], v128 offset:19456
	v_add_u32_e32 v128, s54, v142
	v_add3_u32 v128, v128, v138, v139
	ds_read_b128 v[144:147], v128
	ds_read_b128 v[148:151], v128 offset:1024
	ds_read_b128 v[152:155], v128 offset:2048
	ds_read_b128 v[156:159], v128 offset:3072
	ds_read_b128 v[160:163], v128 offset:4096
	ds_read_b128 v[164:167], v128 offset:5120
	ds_read_b128 v[168:171], v128 offset:6144
	ds_read_b128 v[172:175], v128 offset:7168
	s_setprio 0
	s_waitcnt lgkmcnt(7)
	v_mfma_f32_16x16x32_bf16 v[124:127], v[144:147], v[176:179], v[124:127]
	v_mfma_f32_16x16x32_bf16 v[120:123], v[144:147], v[180:183], v[120:123]
	v_mfma_f32_16x16x32_bf16 v[116:119], v[144:147], v[184:187], v[116:119]
	v_mfma_f32_16x16x32_bf16 v[112:115], v[144:147], v[192:195], v[112:115]
	s_waitcnt lgkmcnt(6)
	v_mfma_f32_16x16x32_bf16 v[108:111], v[148:151], v[176:179], v[108:111]
	v_mfma_f32_16x16x32_bf16 v[104:107], v[148:151], v[180:183], v[104:107]
	v_mfma_f32_16x16x32_bf16 v[100:103], v[148:151], v[184:187], v[100:103]
	v_mfma_f32_16x16x32_bf16 v[96:99], v[148:151], v[192:195], v[96:99]
	s_waitcnt lgkmcnt(5)
	v_mfma_f32_16x16x32_bf16 v[92:95], v[152:155], v[176:179], v[92:95]
	v_mfma_f32_16x16x32_bf16 v[88:91], v[152:155], v[180:183], v[88:91]
	v_mfma_f32_16x16x32_bf16 v[84:87], v[152:155], v[184:187], v[84:87]
	v_mfma_f32_16x16x32_bf16 v[80:83], v[152:155], v[192:195], v[80:83]
	s_waitcnt lgkmcnt(4)
	v_mfma_f32_16x16x32_bf16 v[76:79], v[156:159], v[176:179], v[76:79]
	v_mfma_f32_16x16x32_bf16 v[72:75], v[156:159], v[180:183], v[72:75]
	v_mfma_f32_16x16x32_bf16 v[68:71], v[156:159], v[184:187], v[68:71]
	v_mfma_f32_16x16x32_bf16 v[64:67], v[156:159], v[192:195], v[64:67]
	s_waitcnt lgkmcnt(3)
	v_mfma_f32_16x16x32_bf16 v[60:63], v[160:163], v[176:179], v[60:63]
	v_mfma_f32_16x16x32_bf16 v[56:59], v[160:163], v[180:183], v[56:59]
	v_mfma_f32_16x16x32_bf16 v[52:55], v[160:163], v[184:187], v[52:55]
	v_mfma_f32_16x16x32_bf16 v[48:51], v[160:163], v[192:195], v[48:51]
	s_waitcnt lgkmcnt(2)
	v_mfma_f32_16x16x32_bf16 v[44:47], v[164:167], v[176:179], v[44:47]
	v_mfma_f32_16x16x32_bf16 v[40:43], v[164:167], v[180:183], v[40:43]
	v_mfma_f32_16x16x32_bf16 v[36:39], v[164:167], v[184:187], v[36:39]
	v_mfma_f32_16x16x32_bf16 v[32:35], v[164:167], v[192:195], v[32:35]
	s_waitcnt lgkmcnt(1)
	v_mfma_f32_16x16x32_bf16 v[28:31], v[168:171], v[176:179], v[28:31]
	v_mfma_f32_16x16x32_bf16 v[24:27], v[168:171], v[180:183], v[24:27]
	v_mfma_f32_16x16x32_bf16 v[20:23], v[168:171], v[184:187], v[20:23]
	v_mfma_f32_16x16x32_bf16 v[16:19], v[168:171], v[192:195], v[16:19]
	s_waitcnt lgkmcnt(0)
	v_mfma_f32_16x16x32_bf16 v[12:15], v[172:175], v[176:179], v[12:15]
	v_mfma_f32_16x16x32_bf16 v[8:11], v[172:175], v[180:183], v[8:11]
	v_mfma_f32_16x16x32_bf16 v[4:7], v[172:175], v[184:187], v[4:7]
	v_mfma_f32_16x16x32_bf16 v[0:3], v[172:175], v[192:195], v[0:3]
	s_add_i32 s46, s45, 1
	s_cmp_lg_u32 s45, 2
	s_cselect_b32 s45, s46, 0
	s_add_u32 s24, s24, 0x80
	s_addc_u32 s25, s25, 0
	s_cmpk_eq_i32 s24, 0xf00
	s_cbranch_scc0 .LBB0_1322
	s_waitcnt vmcnt(6) lgkmcnt(0)
	s_barrier
	v_add3_u32 v128, v142, v138, v139
	ds_read_b128 v[130:133], v128
	ds_read_b128 v[142:145], v128 offset:1024
	ds_read_b128 v[146:149], v128 offset:2048
	ds_read_b128 v[150:153], v128 offset:3072
	ds_read_b128 v[154:157], v128 offset:4096
	ds_read_b128 v[158:161], v128 offset:5120
	ds_read_b128 v[162:165], v128 offset:6144
	ds_read_b128 v[166:169], v128 offset:7168
	v_add3_u32 v182, v140, v138, v139
	ds_read_b128 v[138:141], v182 offset:16384
	ds_read_b128 v[170:173], v182 offset:17408
	ds_read_b128 v[174:177], v182 offset:18432
	ds_read_b128 v[178:181], v182 offset:19456
	s_setprio 1
	s_waitcnt lgkmcnt(0)
	v_mfma_f32_16x16x32_bf16 v[100:103], v[142:145], v[174:177], v[100:103]
	v_mfma_f32_16x16x32_bf16 v[96:99], v[142:145], v[178:181], v[96:99]
	v_mfma_f32_16x16x32_bf16 v[92:95], v[146:149], v[138:141], v[92:95]
	v_mfma_f32_16x16x32_bf16 v[88:91], v[146:149], v[170:173], v[88:91]
	v_mfma_f32_16x16x32_bf16 v[84:87], v[146:149], v[174:177], v[84:87]
	v_mfma_f32_16x16x32_bf16 v[80:83], v[146:149], v[178:181], v[80:83]
	v_mfma_f32_16x16x32_bf16 v[76:79], v[150:153], v[138:141], v[76:79]
	v_mfma_f32_16x16x32_bf16 v[72:75], v[150:153], v[170:173], v[72:75]
	v_mfma_f32_16x16x32_bf16 v[68:71], v[150:153], v[174:177], v[68:71]
	v_mfma_f32_16x16x32_bf16 v[64:67], v[150:153], v[178:181], v[64:67]
	v_mfma_f32_16x16x32_bf16 v[60:63], v[154:157], v[138:141], v[60:63]
	v_mfma_f32_16x16x32_bf16 v[56:59], v[154:157], v[170:173], v[56:59]
	v_mfma_f32_16x16x32_bf16 v[52:55], v[154:157], v[174:177], v[52:55]
	v_mfma_f32_16x16x32_bf16 v[48:51], v[154:157], v[178:181], v[48:51]
	v_mfma_f32_16x16x32_bf16 v[44:47], v[158:161], v[138:141], v[44:47]
	v_mfma_f32_16x16x32_bf16 v[40:43], v[158:161], v[170:173], v[40:43]
	v_mfma_f32_16x16x32_bf16 v[36:39], v[158:161], v[174:177], v[36:39]
	v_mfma_f32_16x16x32_bf16 v[32:35], v[158:161], v[178:181], v[32:35]
	v_mfma_f32_16x16x32_bf16 v[28:31], v[162:165], v[138:141], v[28:31]
	v_mfma_f32_16x16x32_bf16 v[24:27], v[162:165], v[170:173], v[24:27]
	v_mfma_f32_16x16x32_bf16 v[20:23], v[162:165], v[174:177], v[20:23]
	v_mfma_f32_16x16x32_bf16 v[16:19], v[162:165], v[178:181], v[16:19]
	v_mfma_f32_16x16x32_bf16 v[12:15], v[166:169], v[138:141], v[12:15]
	v_mfma_f32_16x16x32_bf16 v[8:11], v[166:169], v[170:173], v[8:11]
	v_mfma_f32_16x16x32_bf16 v[4:7], v[166:169], v[174:177], v[4:7]
	v_mfma_f32_16x16x32_bf16 v[0:3], v[166:169], v[178:181], v[0:3]
	v_mfma_f32_16x16x32_bf16 v[124:127], v[130:133], v[138:141], v[124:127]
	v_mfma_f32_16x16x32_bf16 v[120:123], v[130:133], v[170:173], v[120:123]
	v_mfma_f32_16x16x32_bf16 v[116:119], v[130:133], v[174:177], v[116:119]
	v_mfma_f32_16x16x32_bf16 v[112:115], v[130:133], v[178:181], v[112:115]
	v_mfma_f32_16x16x32_bf16 v[108:111], v[142:145], v[138:141], v[108:111]
	v_mfma_f32_16x16x32_bf16 v[104:107], v[142:145], v[170:173], v[104:107]
	s_setprio 0
	s_waitcnt vmcnt(0) lgkmcnt(0)
	s_barrier
	ds_read_b128 v[130:133], v128 offset:24576
	ds_read_b128 v[138:141], v128 offset:25600
	ds_read_b128 v[142:145], v128 offset:26624
	ds_read_b128 v[146:149], v128 offset:27648
	ds_read_b128 v[150:153], v128 offset:28672
	ds_read_b128 v[154:157], v128 offset:29696
	ds_read_b128 v[158:161], v128 offset:30720
	ds_read_b128 v[162:165], v128 offset:31744
	ds_read_b128 v[166:169], v182 offset:40960
	ds_read_b128 v[170:173], v182 offset:41984
	ds_read_b128 v[174:177], v182 offset:43008
	ds_read_b128 v[178:181], v182 offset:44032
	s_setprio 1
	s_waitcnt lgkmcnt(0)
	v_mfma_f32_16x16x32_bf16 v[72:75], v[146:149], v[170:173], v[72:75]
	v_mfma_f32_16x16x32_bf16 v[68:71], v[146:149], v[174:177], v[68:71]
	v_mfma_f32_16x16x32_bf16 v[64:67], v[146:149], v[178:181], v[64:67]
	v_mfma_f32_16x16x32_bf16 v[60:63], v[150:153], v[166:169], v[60:63]
	v_mfma_f32_16x16x32_bf16 v[56:59], v[150:153], v[170:173], v[56:59]
	v_mfma_f32_16x16x32_bf16 v[52:55], v[150:153], v[174:177], v[52:55]
	v_mfma_f32_16x16x32_bf16 v[48:51], v[150:153], v[178:181], v[48:51]
	v_mfma_f32_16x16x32_bf16 v[44:47], v[154:157], v[166:169], v[44:47]
	v_mfma_f32_16x16x32_bf16 v[40:43], v[154:157], v[170:173], v[40:43]
	v_mfma_f32_16x16x32_bf16 v[36:39], v[154:157], v[174:177], v[36:39]
	v_mfma_f32_16x16x32_bf16 v[32:35], v[154:157], v[178:181], v[32:35]
	v_mfma_f32_16x16x32_bf16 v[28:31], v[158:161], v[166:169], v[28:31]
	v_mfma_f32_16x16x32_bf16 v[24:27], v[158:161], v[170:173], v[24:27]
	v_mfma_f32_16x16x32_bf16 v[20:23], v[158:161], v[174:177], v[20:23]
	v_mfma_f32_16x16x32_bf16 v[16:19], v[158:161], v[178:181], v[16:19]
	v_mfma_f32_16x16x32_bf16 v[12:15], v[162:165], v[166:169], v[12:15]
	v_mfma_f32_16x16x32_bf16 v[8:11], v[162:165], v[170:173], v[8:11]
	v_mfma_f32_16x16x32_bf16 v[4:7], v[162:165], v[174:177], v[4:7]
	v_mfma_f32_16x16x32_bf16 v[0:3], v[162:165], v[178:181], v[0:3]
	v_mfma_f32_16x16x32_bf16 v[124:127], v[130:133], v[166:169], v[124:127]
	v_mfma_f32_16x16x32_bf16 v[120:123], v[130:133], v[170:173], v[120:123]
	v_mfma_f32_16x16x32_bf16 v[116:119], v[130:133], v[174:177], v[116:119]
	v_mfma_f32_16x16x32_bf16 v[112:115], v[130:133], v[178:181], v[112:115]
	v_mfma_f32_16x16x32_bf16 v[108:111], v[138:141], v[166:169], v[108:111]
	v_mfma_f32_16x16x32_bf16 v[104:107], v[138:141], v[170:173], v[104:107]
	v_mfma_f32_16x16x32_bf16 v[130:133], v[138:141], v[174:177], v[100:103]
	v_mfma_f32_16x16x32_bf16 v[138:141], v[138:141], v[178:181], v[96:99]
	v_mfma_f32_16x16x32_bf16 v[182:185], v[142:145], v[166:169], v[92:95]
	v_mfma_f32_16x16x32_bf16 v[186:189], v[142:145], v[170:173], v[88:91]
	v_mfma_f32_16x16x32_bf16 v[192:195], v[142:145], v[174:177], v[84:87]
	v_mfma_f32_16x16x32_bf16 v[142:145], v[142:145], v[178:181], v[80:83]
	v_mfma_f32_16x16x32_bf16 v[196:199], v[146:149], v[166:169], v[76:79]
	s_setprio 0
	s_nop 1
	v_lshrrev_b32_e32 v77, 2, v136
	v_and_b32_e32 v76, 0xffffff80, v136
	v_and_b32_e32 v101, 12, v77
	v_lshlrev_b32_e32 v77, 6, v137
	s_add_i32 s24, s35, 0xfffff800
	v_add_u32_e32 v76, s44, v76
	v_or3_b32 v84, v77, s24, v135
	v_lshlrev_b32_e32 v128, 1, v101
	v_ashrrev_i32_e32 v100, 6, v76
	v_lshl_add_u64 v[76:77], s[40:41], 0, v[128:129]
	v_mov_b32_e32 v128, v84
	v_mad_i64_i32 v[92:93], s[24:25], v100, s30, v[128:129]
	v_lshlrev_b64 v[78:79], 7, v[92:93]
	v_lshl_add_u64 v[102:103], v[76:77], 0, v[78:79]
	v_and_b32_sdwa v79, v124, v134 dst_sel:DWORD dst_unused:UNUSED_PAD src0_sel:WORD_1 src1_sel:DWORD
	v_add3_u32 v80, v124, v79, s31
	v_and_b32_sdwa v79, v127, v134 dst_sel:DWORD dst_unused:UNUSED_PAD src0_sel:WORD_1 src1_sel:DWORD
	v_and_b32_sdwa v81, v125, v134 dst_sel:DWORD dst_unused:UNUSED_PAD src0_sel:WORD_1 src1_sel:DWORD
	v_and_b32_sdwa v78, v126, v134 dst_sel:DWORD dst_unused:UNUSED_PAD src0_sel:WORD_1 src1_sel:DWORD
	v_add3_u32 v79, v127, v79, s31
	v_add3_u32 v81, v125, v81, s31
	v_add3_u32 v78, v126, v78, s31
	v_and_b32_e32 v79, 0xffff0000, v79
	v_and_b32_e32 v81, 0xffff0000, v81
	v_or_b32_sdwa v79, v79, v78 dst_sel:DWORD dst_unused:UNUSED_PAD src0_sel:DWORD src1_sel:WORD_1
	v_or_b32_sdwa v78, v81, v80 dst_sel:DWORD dst_unused:UNUSED_PAD src0_sel:DWORD src1_sel:WORD_1
	global_store_dwordx2 v[102:103], v[78:79], off
	v_or_b32_e32 v78, 16, v84
	v_mov_b32_e32 v79, v129
	v_mad_i64_i32 v[88:89], s[24:25], v100, s30, v[78:79]
	v_lshlrev_b64 v[80:81], 7, v[88:89]
	v_lshl_add_u64 v[96:97], v[76:77], 0, v[80:81]
	v_and_b32_sdwa v81, v120, v134 dst_sel:DWORD dst_unused:UNUSED_PAD src0_sel:WORD_1 src1_sel:DWORD
	v_add3_u32 v82, v120, v81, s31
	v_and_b32_sdwa v81, v123, v134 dst_sel:DWORD dst_unused:UNUSED_PAD src0_sel:WORD_1 src1_sel:DWORD
	v_and_b32_sdwa v83, v121, v134 dst_sel:DWORD dst_unused:UNUSED_PAD src0_sel:WORD_1 src1_sel:DWORD
	v_and_b32_sdwa v80, v122, v134 dst_sel:DWORD dst_unused:UNUSED_PAD src0_sel:WORD_1 src1_sel:DWORD
	v_add3_u32 v81, v123, v81, s31
	v_add3_u32 v83, v121, v83, s31
	v_add3_u32 v80, v122, v80, s31
	v_and_b32_e32 v81, 0xffff0000, v81
	v_and_b32_e32 v83, 0xffff0000, v83
	v_or_b32_sdwa v81, v81, v80 dst_sel:DWORD dst_unused:UNUSED_PAD src0_sel:DWORD src1_sel:WORD_1
	v_or_b32_sdwa v80, v83, v82 dst_sel:DWORD dst_unused:UNUSED_PAD src0_sel:DWORD src1_sel:WORD_1
	global_store_dwordx2 v[96:97], v[80:81], off
	v_or_b32_e32 v80, 32, v84
	v_mov_b32_e32 v81, v129
	v_mad_i64_i32 v[86:87], s[24:25], v100, s30, v[80:81]
	v_lshlrev_b64 v[82:83], 7, v[86:87]
	v_lshl_add_u64 v[94:95], v[76:77], 0, v[82:83]
	v_and_b32_sdwa v83, v116, v134 dst_sel:DWORD dst_unused:UNUSED_PAD src0_sel:WORD_1 src1_sel:DWORD
	v_add3_u32 v85, v116, v83, s31
	v_and_b32_sdwa v83, v119, v134 dst_sel:DWORD dst_unused:UNUSED_PAD src0_sel:WORD_1 src1_sel:DWORD
	v_and_b32_sdwa v90, v117, v134 dst_sel:DWORD dst_unused:UNUSED_PAD src0_sel:WORD_1 src1_sel:DWORD
	v_and_b32_sdwa v82, v118, v134 dst_sel:DWORD dst_unused:UNUSED_PAD src0_sel:WORD_1 src1_sel:DWORD
	v_add3_u32 v83, v119, v83, s31
	v_add3_u32 v90, v117, v90, s31
	v_add3_u32 v82, v118, v82, s31
	v_and_b32_e32 v83, 0xffff0000, v83
	v_and_b32_e32 v90, 0xffff0000, v90
	v_or_b32_sdwa v83, v83, v82 dst_sel:DWORD dst_unused:UNUSED_PAD src0_sel:DWORD src1_sel:WORD_1
	v_or_b32_sdwa v82, v90, v85 dst_sel:DWORD dst_unused:UNUSED_PAD src0_sel:DWORD src1_sel:WORD_1
	v_and_b32_sdwa v98, v114, v134 dst_sel:DWORD dst_unused:UNUSED_PAD src0_sel:WORD_1 src1_sel:DWORD
	v_and_b32_sdwa v99, v112, v134 dst_sel:DWORD dst_unused:UNUSED_PAD src0_sel:WORD_1 src1_sel:DWORD
	global_store_dwordx2 v[94:95], v[82:83], off
	v_or_b32_e32 v82, 48, v84
	v_mov_b32_e32 v83, v129
	v_add3_u32 v112, v112, v99, s31
	v_add3_u32 v98, v114, v98, s31
	v_and_b32_sdwa v99, v115, v134 dst_sel:DWORD dst_unused:UNUSED_PAD src0_sel:WORD_1 src1_sel:DWORD
	v_and_b32_sdwa v114, v113, v134 dst_sel:DWORD dst_unused:UNUSED_PAD src0_sel:WORD_1 src1_sel:DWORD
	v_mad_i64_i32 v[84:85], s[24:25], v100, s30, v[82:83]
	v_add3_u32 v99, v115, v99, s31
	v_add3_u32 v113, v113, v114, s31
	v_lshlrev_b64 v[90:91], 7, v[84:85]
	v_and_b32_e32 v99, 0xffff0000, v99
	v_and_b32_e32 v113, 0xffff0000, v113
	v_lshl_add_u64 v[90:91], v[76:77], 0, v[90:91]
	v_or_b32_sdwa v99, v99, v98 dst_sel:DWORD dst_unused:UNUSED_PAD src0_sel:DWORD src1_sel:WORD_1
	v_or_b32_sdwa v98, v113, v112 dst_sel:DWORD dst_unused:UNUSED_PAD src0_sel:DWORD src1_sel:WORD_1
	global_store_dwordx2 v[90:91], v[98:99], off
	v_and_b32_sdwa v98, v110, v134 dst_sel:DWORD dst_unused:UNUSED_PAD src0_sel:WORD_1 src1_sel:DWORD
	v_and_b32_sdwa v99, v108, v134 dst_sel:DWORD dst_unused:UNUSED_PAD src0_sel:WORD_1 src1_sel:DWORD
	v_add3_u32 v108, v108, v99, s31
	v_add3_u32 v98, v110, v98, s31
	v_and_b32_sdwa v99, v111, v134 dst_sel:DWORD dst_unused:UNUSED_PAD src0_sel:WORD_1 src1_sel:DWORD
	v_and_b32_sdwa v110, v109, v134 dst_sel:DWORD dst_unused:UNUSED_PAD src0_sel:WORD_1 src1_sel:DWORD
	v_add3_u32 v99, v111, v99, s31
	v_add3_u32 v109, v109, v110, s31
	v_and_b32_e32 v99, 0xffff0000, v99
	v_and_b32_e32 v109, 0xffff0000, v109
	v_or_b32_sdwa v99, v99, v98 dst_sel:DWORD dst_unused:UNUSED_PAD src0_sel:DWORD src1_sel:WORD_1
	v_or_b32_sdwa v98, v109, v108 dst_sel:DWORD dst_unused:UNUSED_PAD src0_sel:DWORD src1_sel:WORD_1
	global_store_dwordx2 v[102:103], v[98:99], off offset:32
	v_and_b32_sdwa v98, v106, v134 dst_sel:DWORD dst_unused:UNUSED_PAD src0_sel:WORD_1 src1_sel:DWORD
	v_and_b32_sdwa v99, v104, v134 dst_sel:DWORD dst_unused:UNUSED_PAD src0_sel:WORD_1 src1_sel:DWORD
	v_add3_u32 v104, v104, v99, s31
	v_add3_u32 v98, v106, v98, s31
	v_and_b32_sdwa v99, v107, v134 dst_sel:DWORD dst_unused:UNUSED_PAD src0_sel:WORD_1 src1_sel:DWORD
	v_and_b32_sdwa v106, v105, v134 dst_sel:DWORD dst_unused:UNUSED_PAD src0_sel:WORD_1 src1_sel:DWORD
	v_add3_u32 v99, v107, v99, s31
	v_add3_u32 v105, v105, v106, s31
	v_and_b32_e32 v99, 0xffff0000, v99
	v_and_b32_e32 v105, 0xffff0000, v105
	v_or_b32_sdwa v99, v99, v98 dst_sel:DWORD dst_unused:UNUSED_PAD src0_sel:DWORD src1_sel:WORD_1
	v_or_b32_sdwa v98, v105, v104 dst_sel:DWORD dst_unused:UNUSED_PAD src0_sel:DWORD src1_sel:WORD_1
	global_store_dwordx2 v[96:97], v[98:99], off offset:32
	v_and_b32_sdwa v99, v130, v134 dst_sel:DWORD dst_unused:UNUSED_PAD src0_sel:WORD_1 src1_sel:DWORD
	v_add3_u32 v104, v130, v99, s31
	v_and_b32_sdwa v99, v133, v134 dst_sel:DWORD dst_unused:UNUSED_PAD src0_sel:WORD_1 src1_sel:DWORD
	v_and_b32_sdwa v105, v131, v134 dst_sel:DWORD dst_unused:UNUSED_PAD src0_sel:WORD_1 src1_sel:DWORD
	v_and_b32_sdwa v98, v132, v134 dst_sel:DWORD dst_unused:UNUSED_PAD src0_sel:WORD_1 src1_sel:DWORD
	v_add3_u32 v99, v133, v99, s31
	v_add3_u32 v105, v131, v105, s31
	v_add3_u32 v98, v132, v98, s31
	v_and_b32_e32 v99, 0xffff0000, v99
	v_and_b32_e32 v105, 0xffff0000, v105
	v_or_b32_sdwa v99, v99, v98 dst_sel:DWORD dst_unused:UNUSED_PAD src0_sel:DWORD src1_sel:WORD_1
	v_or_b32_sdwa v98, v105, v104 dst_sel:DWORD dst_unused:UNUSED_PAD src0_sel:DWORD src1_sel:WORD_1
	global_store_dwordx2 v[94:95], v[98:99], off offset:32
	v_and_b32_sdwa v99, v138, v134 dst_sel:DWORD dst_unused:UNUSED_PAD src0_sel:WORD_1 src1_sel:DWORD
	v_add3_u32 v104, v138, v99, s31
	v_and_b32_sdwa v99, v141, v134 dst_sel:DWORD dst_unused:UNUSED_PAD src0_sel:WORD_1 src1_sel:DWORD
	v_and_b32_sdwa v105, v139, v134 dst_sel:DWORD dst_unused:UNUSED_PAD src0_sel:WORD_1 src1_sel:DWORD
	v_and_b32_sdwa v98, v140, v134 dst_sel:DWORD dst_unused:UNUSED_PAD src0_sel:WORD_1 src1_sel:DWORD
	v_add3_u32 v99, v141, v99, s31
	v_add3_u32 v105, v139, v105, s31
	v_add3_u32 v98, v140, v98, s31
	v_and_b32_e32 v99, 0xffff0000, v99
	v_and_b32_e32 v105, 0xffff0000, v105
	v_or_b32_sdwa v99, v99, v98 dst_sel:DWORD dst_unused:UNUSED_PAD src0_sel:DWORD src1_sel:WORD_1
	v_or_b32_sdwa v98, v105, v104 dst_sel:DWORD dst_unused:UNUSED_PAD src0_sel:DWORD src1_sel:WORD_1
	global_store_dwordx2 v[90:91], v[98:99], off offset:32
	v_and_b32_sdwa v99, v182, v134 dst_sel:DWORD dst_unused:UNUSED_PAD src0_sel:WORD_1 src1_sel:DWORD
	v_add3_u32 v104, v182, v99, s31
	v_and_b32_sdwa v99, v185, v134 dst_sel:DWORD dst_unused:UNUSED_PAD src0_sel:WORD_1 src1_sel:DWORD
	v_and_b32_sdwa v105, v183, v134 dst_sel:DWORD dst_unused:UNUSED_PAD src0_sel:WORD_1 src1_sel:DWORD
	v_and_b32_sdwa v98, v184, v134 dst_sel:DWORD dst_unused:UNUSED_PAD src0_sel:WORD_1 src1_sel:DWORD
	v_add3_u32 v99, v185, v99, s31
	v_add3_u32 v105, v183, v105, s31
	v_add3_u32 v98, v184, v98, s31
	v_and_b32_e32 v99, 0xffff0000, v99
	v_and_b32_e32 v105, 0xffff0000, v105
	v_or_b32_sdwa v99, v99, v98 dst_sel:DWORD dst_unused:UNUSED_PAD src0_sel:DWORD src1_sel:WORD_1
	v_or_b32_sdwa v98, v105, v104 dst_sel:DWORD dst_unused:UNUSED_PAD src0_sel:DWORD src1_sel:WORD_1
	global_store_dwordx2 v[102:103], v[98:99], off offset:64
	v_and_b32_sdwa v99, v186, v134 dst_sel:DWORD dst_unused:UNUSED_PAD src0_sel:WORD_1 src1_sel:DWORD
	v_add3_u32 v104, v186, v99, s31
	v_and_b32_sdwa v99, v189, v134 dst_sel:DWORD dst_unused:UNUSED_PAD src0_sel:WORD_1 src1_sel:DWORD
	v_and_b32_sdwa v105, v187, v134 dst_sel:DWORD dst_unused:UNUSED_PAD src0_sel:WORD_1 src1_sel:DWORD
	v_and_b32_sdwa v98, v188, v134 dst_sel:DWORD dst_unused:UNUSED_PAD src0_sel:WORD_1 src1_sel:DWORD
	v_add3_u32 v99, v189, v99, s31
	v_add3_u32 v105, v187, v105, s31
	v_add3_u32 v98, v188, v98, s31
	v_and_b32_e32 v99, 0xffff0000, v99
	v_and_b32_e32 v105, 0xffff0000, v105
	v_or_b32_sdwa v99, v99, v98 dst_sel:DWORD dst_unused:UNUSED_PAD src0_sel:DWORD src1_sel:WORD_1
	v_or_b32_sdwa v98, v105, v104 dst_sel:DWORD dst_unused:UNUSED_PAD src0_sel:DWORD src1_sel:WORD_1
	global_store_dwordx2 v[96:97], v[98:99], off offset:64
	v_and_b32_sdwa v99, v192, v134 dst_sel:DWORD dst_unused:UNUSED_PAD src0_sel:WORD_1 src1_sel:DWORD
	v_add3_u32 v104, v192, v99, s31
	v_and_b32_sdwa v99, v195, v134 dst_sel:DWORD dst_unused:UNUSED_PAD src0_sel:WORD_1 src1_sel:DWORD
	v_and_b32_sdwa v105, v193, v134 dst_sel:DWORD dst_unused:UNUSED_PAD src0_sel:WORD_1 src1_sel:DWORD
	v_and_b32_sdwa v98, v194, v134 dst_sel:DWORD dst_unused:UNUSED_PAD src0_sel:WORD_1 src1_sel:DWORD
	v_add3_u32 v99, v195, v99, s31
	v_add3_u32 v105, v193, v105, s31
	v_add3_u32 v98, v194, v98, s31
	v_and_b32_e32 v99, 0xffff0000, v99
	v_and_b32_e32 v105, 0xffff0000, v105
	v_or_b32_sdwa v99, v99, v98 dst_sel:DWORD dst_unused:UNUSED_PAD src0_sel:DWORD src1_sel:WORD_1
	v_or_b32_sdwa v98, v105, v104 dst_sel:DWORD dst_unused:UNUSED_PAD src0_sel:DWORD src1_sel:WORD_1
	global_store_dwordx2 v[94:95], v[98:99], off offset:64
	v_and_b32_sdwa v99, v142, v134 dst_sel:DWORD dst_unused:UNUSED_PAD src0_sel:WORD_1 src1_sel:DWORD
	v_add3_u32 v104, v142, v99, s31
	v_and_b32_sdwa v99, v145, v134 dst_sel:DWORD dst_unused:UNUSED_PAD src0_sel:WORD_1 src1_sel:DWORD
	v_and_b32_sdwa v105, v143, v134 dst_sel:DWORD dst_unused:UNUSED_PAD src0_sel:WORD_1 src1_sel:DWORD
	v_and_b32_sdwa v98, v144, v134 dst_sel:DWORD dst_unused:UNUSED_PAD src0_sel:WORD_1 src1_sel:DWORD
	v_add3_u32 v99, v145, v99, s31
	v_add3_u32 v105, v143, v105, s31
	v_add3_u32 v98, v144, v98, s31
	v_and_b32_e32 v99, 0xffff0000, v99
	v_and_b32_e32 v105, 0xffff0000, v105
	v_or_b32_sdwa v99, v99, v98 dst_sel:DWORD dst_unused:UNUSED_PAD src0_sel:DWORD src1_sel:WORD_1
	v_or_b32_sdwa v98, v105, v104 dst_sel:DWORD dst_unused:UNUSED_PAD src0_sel:DWORD src1_sel:WORD_1
	global_store_dwordx2 v[90:91], v[98:99], off offset:64
	v_and_b32_sdwa v99, v196, v134 dst_sel:DWORD dst_unused:UNUSED_PAD src0_sel:WORD_1 src1_sel:DWORD
	v_cmp_eq_u32_e32 vcc, 12, v101
	v_add3_u32 v101, v196, v99, s31
	v_and_b32_sdwa v99, v199, v134 dst_sel:DWORD dst_unused:UNUSED_PAD src0_sel:WORD_1 src1_sel:DWORD
	v_and_b32_sdwa v104, v197, v134 dst_sel:DWORD dst_unused:UNUSED_PAD src0_sel:WORD_1 src1_sel:DWORD
	v_and_b32_sdwa v98, v198, v134 dst_sel:DWORD dst_unused:UNUSED_PAD src0_sel:WORD_1 src1_sel:DWORD
	v_add3_u32 v99, v199, v99, s31
	v_add3_u32 v104, v197, v104, s31
	v_add3_u32 v98, v198, v98, s31
	v_and_b32_e32 v99, 0xffff0000, v99
	v_and_b32_e32 v104, 0xffff0000, v104
	v_or_b32_sdwa v99, v99, v98 dst_sel:DWORD dst_unused:UNUSED_PAD src0_sel:DWORD src1_sel:WORD_1
	v_or_b32_sdwa v98, v104, v101 dst_sel:DWORD dst_unused:UNUSED_PAD src0_sel:DWORD src1_sel:WORD_1
	global_store_dwordx2 v[102:103], v[98:99], off offset:96
	s_and_saveexec_b64 s[24:25], vcc
	s_cbranch_execz .LBB0_1325
	v_lshl_add_u64 v[92:93], v[92:93], 3, s[42:43]
	global_store_dwordx2 v[92:93], v[98:99], off

.LBB0_1342:
	s_add_i32 s37, s36, 2
	s_mul_hi_i32 s38, s37, 0x55555556
	s_lshr_b32 s44, s38, 31
	s_add_i32 s38, s38, s44
	s_mul_i32 s38, s38, 3
	s_sub_i32 s37, s37, s38
	s_mulk_i32 s37, 0x6000
	s_mul_i32 s54, s36, 0x6000
	v_readfirstlane_b32 s55, v141
	v_lshl_add_u64 v[232:233], v[132:133], 0, s[24:25]
	v_lshl_add_u64 v[234:235], v[130:131], 0, s[24:25]
	s_add_u32 s55, s55, s37
	s_waitcnt vmcnt(6) lgkmcnt(0)
	s_barrier
	s_setprio 1
	s_mov_b32 m0, s55
	v_lshl_add_u64 v[236:237], v[232:233], 0, s[12:13]
	global_load_lds_dwordx4 v[236:237], off
	s_add_u32 m0, s55, 0x1000
	v_lshl_add_u64 v[236:237], v[232:233], 0, s[14:15]
	global_load_lds_dwordx4 v[236:237], off
	s_add_u32 m0, s55, 0x2000
	v_lshl_add_u64 v[236:237], v[232:233], 0, s[16:17]
	global_load_lds_dwordx4 v[236:237], off
	s_add_u32 m0, s55, 0x3000
	v_lshl_add_u64 v[236:237], v[232:233], 0, s[18:19]
	global_load_lds_dwordx4 v[236:237], off
	s_add_u32 m0, s55, 0x4000
	v_lshl_add_u64 v[236:237], v[234:235], 0, s[20:21]
	global_load_lds_dwordx4 v[236:237], off
	s_add_u32 m0, s55, 0x5000
	v_lshl_add_u64 v[236:237], v[234:235], 0, s[22:23]
	global_load_lds_dwordx4 v[236:237], off
	v_or_b32_e32 v128, s54, v139
	v_add3_u32 v128, v128, v140, v138
	ds_read_b128 v[176:179], v128 offset:16384
	ds_read_b128 v[180:183], v128 offset:16640
	ds_read_b128 v[184:187], v128 offset:18432
	ds_read_b128 v[192:195], v128 offset:18688
	v_add3_u32 v128, s54, v142, v138
	ds_read_b128 v[144:147], v128
	ds_read_b128 v[148:151], v128 offset:1024
	ds_read_b128 v[152:155], v128 offset:2048
	ds_read_b128 v[156:159], v128 offset:3072
	ds_read_b128 v[160:163], v128 offset:4096
	ds_read_b128 v[164:167], v128 offset:5120
	ds_read_b128 v[168:171], v128 offset:6144
	ds_read_b128 v[172:175], v128 offset:7168
	s_setprio 0
	s_waitcnt lgkmcnt(7)
	v_mfma_f32_16x16x32_bf16 v[124:127], v[176:179], v[144:147], v[124:127]
	v_mfma_f32_16x16x32_bf16 v[120:123], v[180:183], v[144:147], v[120:123]
	v_mfma_f32_16x16x32_bf16 v[116:119], v[184:187], v[144:147], v[116:119]
	v_mfma_f32_16x16x32_bf16 v[112:115], v[192:195], v[144:147], v[112:115]
	s_waitcnt lgkmcnt(6)
	v_mfma_f32_16x16x32_bf16 v[108:111], v[176:179], v[148:151], v[108:111]
	v_mfma_f32_16x16x32_bf16 v[104:107], v[180:183], v[148:151], v[104:107]
	v_mfma_f32_16x16x32_bf16 v[100:103], v[184:187], v[148:151], v[100:103]
	v_mfma_f32_16x16x32_bf16 v[96:99], v[192:195], v[148:151], v[96:99]
	s_waitcnt lgkmcnt(5)
	v_mfma_f32_16x16x32_bf16 v[92:95], v[176:179], v[152:155], v[92:95]
	v_mfma_f32_16x16x32_bf16 v[88:91], v[180:183], v[152:155], v[88:91]
	v_mfma_f32_16x16x32_bf16 v[84:87], v[184:187], v[152:155], v[84:87]
	v_mfma_f32_16x16x32_bf16 v[80:83], v[192:195], v[152:155], v[80:83]
	s_waitcnt lgkmcnt(4)
	v_mfma_f32_16x16x32_bf16 v[76:79], v[176:179], v[156:159], v[76:79]
	v_mfma_f32_16x16x32_bf16 v[72:75], v[180:183], v[156:159], v[72:75]
	v_mfma_f32_16x16x32_bf16 v[68:71], v[184:187], v[156:159], v[68:71]
	v_mfma_f32_16x16x32_bf16 v[64:67], v[192:195], v[156:159], v[64:67]
	s_waitcnt lgkmcnt(3)
	v_mfma_f32_16x16x32_bf16 v[60:63], v[176:179], v[160:163], v[60:63]
	v_mfma_f32_16x16x32_bf16 v[56:59], v[180:183], v[160:163], v[56:59]
	v_mfma_f32_16x16x32_bf16 v[52:55], v[184:187], v[160:163], v[52:55]
	v_mfma_f32_16x16x32_bf16 v[48:51], v[192:195], v[160:163], v[48:51]
	s_waitcnt lgkmcnt(2)
	v_mfma_f32_16x16x32_bf16 v[44:47], v[176:179], v[164:167], v[44:47]
	v_mfma_f32_16x16x32_bf16 v[40:43], v[180:183], v[164:167], v[40:43]
	v_mfma_f32_16x16x32_bf16 v[36:39], v[184:187], v[164:167], v[36:39]
	v_mfma_f32_16x16x32_bf16 v[32:35], v[192:195], v[164:167], v[32:35]
	s_waitcnt lgkmcnt(1)
	v_mfma_f32_16x16x32_bf16 v[28:31], v[176:179], v[168:171], v[28:31]
	v_mfma_f32_16x16x32_bf16 v[24:27], v[180:183], v[168:171], v[24:27]
	v_mfma_f32_16x16x32_bf16 v[20:23], v[184:187], v[168:171], v[20:23]
	v_mfma_f32_16x16x32_bf16 v[16:19], v[192:195], v[168:171], v[16:19]
	s_waitcnt lgkmcnt(0)
	v_mfma_f32_16x16x32_bf16 v[12:15], v[176:179], v[172:175], v[12:15]
	v_mfma_f32_16x16x32_bf16 v[8:11], v[180:183], v[172:175], v[8:11]
	v_mfma_f32_16x16x32_bf16 v[4:7], v[184:187], v[172:175], v[4:7]
	v_mfma_f32_16x16x32_bf16 v[0:3], v[192:195], v[172:175], v[0:3]
	s_add_i32 s37, s36, 1
	s_cmp_lg_u32 s36, 2
	s_cselect_b32 s36, s37, 0
	s_add_u32 s24, s24, 0x80
	s_addc_u32 s25, s25, 0
	s_cmpk_lg_i32 s24, 0xf00
	s_cbranch_scc1 .LBB0_1342
	s_waitcnt vmcnt(6) lgkmcnt(0)
	s_barrier
	v_add_u32_e32 v128, v142, v138
	ds_read_b128 v[130:133], v128
	ds_read_b128 v[142:145], v128 offset:1024
	ds_read_b128 v[146:149], v128 offset:2048
	ds_read_b128 v[150:153], v128 offset:3072
	ds_read_b128 v[154:157], v128 offset:4096
	ds_read_b128 v[158:161], v128 offset:5120
	ds_read_b128 v[162:165], v128 offset:6144
	ds_read_b128 v[166:169], v128 offset:7168
	v_add3_u32 v182, v139, v140, v138
	ds_read_b128 v[138:141], v182 offset:16384
	ds_read_b128 v[170:173], v182 offset:16640
	ds_read_b128 v[174:177], v182 offset:18432
	ds_read_b128 v[178:181], v182 offset:18688
	s_setprio 1
	s_waitcnt lgkmcnt(0)
	v_mfma_f32_16x16x32_bf16 v[124:127], v[138:141], v[130:133], v[124:127]
	v_mfma_f32_16x16x32_bf16 v[120:123], v[170:173], v[130:133], v[120:123]
	v_mfma_f32_16x16x32_bf16 v[116:119], v[174:177], v[130:133], v[116:119]
	v_mfma_f32_16x16x32_bf16 v[112:115], v[178:181], v[130:133], v[112:115]
	v_mfma_f32_16x16x32_bf16 v[108:111], v[138:141], v[142:145], v[108:111]
	v_mfma_f32_16x16x32_bf16 v[104:107], v[170:173], v[142:145], v[104:107]
	v_mfma_f32_16x16x32_bf16 v[100:103], v[174:177], v[142:145], v[100:103]
	v_mfma_f32_16x16x32_bf16 v[96:99], v[178:181], v[142:145], v[96:99]
	v_mfma_f32_16x16x32_bf16 v[92:95], v[138:141], v[146:149], v[92:95]
	v_mfma_f32_16x16x32_bf16 v[88:91], v[170:173], v[146:149], v[88:91]
	v_mfma_f32_16x16x32_bf16 v[84:87], v[174:177], v[146:149], v[84:87]
	v_mfma_f32_16x16x32_bf16 v[80:83], v[178:181], v[146:149], v[80:83]
	v_mfma_f32_16x16x32_bf16 v[76:79], v[138:141], v[150:153], v[76:79]
	v_mfma_f32_16x16x32_bf16 v[72:75], v[170:173], v[150:153], v[72:75]
	v_mfma_f32_16x16x32_bf16 v[68:71], v[174:177], v[150:153], v[68:71]
	v_mfma_f32_16x16x32_bf16 v[64:67], v[178:181], v[150:153], v[64:67]
	v_mfma_f32_16x16x32_bf16 v[60:63], v[138:141], v[154:157], v[60:63]
	v_mfma_f32_16x16x32_bf16 v[56:59], v[170:173], v[154:157], v[56:59]
	v_mfma_f32_16x16x32_bf16 v[52:55], v[174:177], v[154:157], v[52:55]
	v_mfma_f32_16x16x32_bf16 v[48:51], v[178:181], v[154:157], v[48:51]
	v_mfma_f32_16x16x32_bf16 v[44:47], v[138:141], v[158:161], v[44:47]
	v_mfma_f32_16x16x32_bf16 v[40:43], v[170:173], v[158:161], v[40:43]
	v_mfma_f32_16x16x32_bf16 v[36:39], v[174:177], v[158:161], v[36:39]
	v_mfma_f32_16x16x32_bf16 v[32:35], v[178:181], v[158:161], v[32:35]
	v_mfma_f32_16x16x32_bf16 v[28:31], v[138:141], v[162:165], v[28:31]
	v_mfma_f32_16x16x32_bf16 v[24:27], v[170:173], v[162:165], v[24:27]
	v_mfma_f32_16x16x32_bf16 v[20:23], v[174:177], v[162:165], v[20:23]
	v_mfma_f32_16x16x32_bf16 v[16:19], v[178:181], v[162:165], v[16:19]
	v_mfma_f32_16x16x32_bf16 v[12:15], v[138:141], v[166:169], v[12:15]
	v_mfma_f32_16x16x32_bf16 v[8:11], v[170:173], v[166:169], v[8:11]
	v_mfma_f32_16x16x32_bf16 v[4:7], v[174:177], v[166:169], v[4:7]
	v_mfma_f32_16x16x32_bf16 v[0:3], v[178:181], v[166:169], v[0:3]
	s_setprio 0
	s_waitcnt vmcnt(0) lgkmcnt(0)
	s_barrier
	ds_read_b128 v[130:133], v128 offset:24576
	ds_read_b128 v[138:141], v128 offset:25600
	ds_read_b128 v[142:145], v128 offset:26624
	ds_read_b128 v[146:149], v128 offset:27648
	ds_read_b128 v[150:153], v128 offset:28672
	ds_read_b128 v[154:157], v128 offset:29696
	ds_read_b128 v[158:161], v128 offset:30720
	ds_read_b128 v[162:165], v128 offset:31744
	ds_read_b128 v[166:169], v182 offset:40960
	ds_read_b128 v[170:173], v182 offset:41216
	ds_read_b128 v[174:177], v182 offset:43008
	ds_read_b128 v[178:181], v182 offset:43264
	s_setprio 1
	s_waitcnt lgkmcnt(0)
	v_mfma_f32_16x16x32_bf16 v[124:127], v[166:169], v[130:133], v[124:127]
	v_mfma_f32_16x16x32_bf16 v[120:123], v[170:173], v[130:133], v[120:123]
	v_mfma_f32_16x16x32_bf16 v[116:119], v[174:177], v[130:133], v[116:119]
	v_mfma_f32_16x16x32_bf16 v[112:115], v[178:181], v[130:133], v[112:115]
	v_mfma_f32_16x16x32_bf16 v[108:111], v[166:169], v[138:141], v[108:111]
	v_mfma_f32_16x16x32_bf16 v[104:107], v[170:173], v[138:141], v[104:107]
	v_mfma_f32_16x16x32_bf16 v[100:103], v[174:177], v[138:141], v[100:103]
	v_mfma_f32_16x16x32_bf16 v[96:99], v[178:181], v[138:141], v[96:99]
	v_mfma_f32_16x16x32_bf16 v[92:95], v[166:169], v[142:145], v[92:95]
	v_mfma_f32_16x16x32_bf16 v[88:91], v[170:173], v[142:145], v[88:91]
	v_mfma_f32_16x16x32_bf16 v[84:87], v[174:177], v[142:145], v[84:87]
	v_mfma_f32_16x16x32_bf16 v[80:83], v[178:181], v[142:145], v[80:83]
	v_mfma_f32_16x16x32_bf16 v[130:133], v[166:169], v[146:149], v[76:79]
	v_mfma_f32_16x16x32_bf16 v[72:75], v[170:173], v[146:149], v[72:75]
	v_mfma_f32_16x16x32_bf16 v[68:71], v[174:177], v[146:149], v[68:71]
	v_mfma_f32_16x16x32_bf16 v[64:67], v[178:181], v[146:149], v[64:67]
	v_mfma_f32_16x16x32_bf16 v[60:63], v[166:169], v[150:153], v[60:63]
	v_mfma_f32_16x16x32_bf16 v[56:59], v[170:173], v[150:153], v[56:59]
	v_mfma_f32_16x16x32_bf16 v[52:55], v[174:177], v[150:153], v[52:55]
	v_mfma_f32_16x16x32_bf16 v[48:51], v[178:181], v[150:153], v[48:51]
	v_mfma_f32_16x16x32_bf16 v[44:47], v[166:169], v[154:157], v[44:47]
	v_mfma_f32_16x16x32_bf16 v[40:43], v[170:173], v[154:157], v[40:43]
	v_mfma_f32_16x16x32_bf16 v[36:39], v[174:177], v[154:157], v[36:39]
	v_mfma_f32_16x16x32_bf16 v[32:35], v[178:181], v[154:157], v[32:35]
	v_mfma_f32_16x16x32_bf16 v[28:31], v[166:169], v[158:161], v[28:31]
	v_mfma_f32_16x16x32_bf16 v[24:27], v[170:173], v[158:161], v[24:27]
	v_mfma_f32_16x16x32_bf16 v[20:23], v[174:177], v[158:161], v[20:23]
	v_mfma_f32_16x16x32_bf16 v[16:19], v[178:181], v[158:161], v[16:19]
	v_mfma_f32_16x16x32_bf16 v[12:15], v[166:169], v[162:165], v[12:15]
	v_mfma_f32_16x16x32_bf16 v[8:11], v[170:173], v[162:165], v[8:11]
	v_mfma_f32_16x16x32_bf16 v[4:7], v[174:177], v[162:165], v[4:7]
	v_mfma_f32_16x16x32_bf16 v[0:3], v[178:181], v[162:165], v[0:3]
	s_setprio 0
	v_and_b32_e32 v76, 0xffffff80, v135
	v_add_u32_e32 v76, s39, v76
	v_lshrrev_b32_e32 v78, 1, v135
	v_or_b32_e32 v76, v76, v136
	v_lshlrev_b32_e32 v77, 6, v137
	v_and_b32_e32 v78, 24, v78
	v_or3_b32 v78, v77, v78, s35
	v_ashrrev_i32_e32 v77, 31, v76
	v_lshlrev_b64 v[136:137], 12, v[76:77]
	v_bfe_u32 v77, v124, 16, 1
	v_add3_u32 v77, v124, v77, s31
	v_bfe_u32 v79, v125, 16, 1
	v_lshrrev_b32_e32 v77, 16, v77
	v_add3_u32 v79, v125, v79, s31
	v_and_or_b32 v124, v79, s33, v77
	v_bfe_u32 v77, v126, 16, 1
	v_add3_u32 v77, v126, v77, s31
	v_bfe_u32 v79, v127, 16, 1
	v_lshrrev_b32_e32 v77, 16, v77
	v_add3_u32 v79, v127, v79, s31
	v_and_or_b32 v125, v79, s33, v77
	v_bfe_u32 v77, v120, 16, 1
	v_add3_u32 v77, v120, v77, s31
	v_bfe_u32 v79, v121, 16, 1
	v_lshrrev_b32_e32 v77, 16, v77
	v_add3_u32 v79, v121, v79, s31
	v_and_or_b32 v126, v79, s33, v77
	v_bfe_u32 v77, v122, 16, 1
	v_add3_u32 v77, v122, v77, s31
	v_bfe_u32 v79, v123, 16, 1
	v_lshrrev_b32_e32 v77, 16, v77
	v_add3_u32 v79, v123, v79, s31
	v_and_or_b32 v127, v79, s33, v77
	v_bfe_u32 v77, v116, 16, 1
	v_add3_u32 v77, v116, v77, s31
	v_bfe_u32 v116, v117, 16, 1
	v_lshrrev_b32_e32 v77, 16, v77
	v_add3_u32 v116, v117, v116, s31
	v_and_or_b32 v116, v116, s33, v77
	v_bfe_u32 v77, v118, 16, 1
	v_add3_u32 v77, v118, v77, s31
	v_bfe_u32 v117, v119, 16, 1
	v_lshrrev_b32_e32 v77, 16, v77
	v_add3_u32 v117, v119, v117, s31
	v_and_or_b32 v117, v117, s33, v77
	v_bfe_u32 v77, v112, 16, 1
	v_add3_u32 v77, v112, v77, s31
	v_bfe_u32 v112, v113, 16, 1
	v_lshrrev_b32_e32 v77, 16, v77
	v_add3_u32 v112, v113, v112, s31
	v_and_or_b32 v118, v112, s33, v77
	v_bfe_u32 v77, v114, 16, 1
	v_add3_u32 v77, v114, v77, s31
	v_bfe_u32 v112, v115, 16, 1
	v_lshrrev_b32_e32 v77, 16, v77
	v_add3_u32 v112, v115, v112, s31
	v_and_or_b32 v119, v112, s33, v77
	v_bfe_u32 v77, v108, 16, 1
	v_add3_u32 v77, v108, v77, s31
	v_bfe_u32 v108, v109, 16, 1
	v_lshrrev_b32_e32 v77, 16, v77
	v_add3_u32 v108, v109, v108, s31
	v_and_or_b32 v108, v108, s33, v77
	v_bfe_u32 v77, v110, 16, 1
	v_add3_u32 v77, v110, v77, s31
	v_bfe_u32 v109, v111, 16, 1
	v_lshrrev_b32_e32 v77, 16, v77
	v_add3_u32 v109, v111, v109, s31
	v_and_or_b32 v109, v109, s33, v77
	v_bfe_u32 v77, v104, 16, 1
	v_add3_u32 v77, v104, v77, s31
	v_bfe_u32 v104, v105, 16, 1
	v_lshrrev_b32_e32 v77, 16, v77
	v_add3_u32 v104, v105, v104, s31
	v_and_or_b32 v110, v104, s33, v77
	v_bfe_u32 v77, v106, 16, 1
	v_add3_u32 v77, v106, v77, s31
	v_bfe_u32 v104, v107, 16, 1
	v_lshrrev_b32_e32 v77, 16, v77
	v_add3_u32 v104, v107, v104, s31
	v_and_or_b32 v111, v104, s33, v77
	v_bfe_u32 v77, v100, 16, 1
	v_add3_u32 v77, v100, v77, s31
	v_bfe_u32 v100, v101, 16, 1
	v_lshrrev_b32_e32 v77, 16, v77
	v_add3_u32 v100, v101, v100, s31
	v_and_or_b32 v100, v100, s33, v77
	v_bfe_u32 v77, v102, 16, 1
	v_add3_u32 v77, v102, v77, s31
	v_bfe_u32 v101, v103, 16, 1
	v_lshrrev_b32_e32 v77, 16, v77
	v_add3_u32 v101, v103, v101, s31
	v_and_or_b32 v101, v101, s33, v77
	v_bfe_u32 v77, v96, 16, 1
	v_add3_u32 v77, v96, v77, s31
	v_bfe_u32 v96, v97, 16, 1
	v_lshrrev_b32_e32 v77, 16, v77
	v_add3_u32 v96, v97, v96, s31
	v_and_or_b32 v102, v96, s33, v77
	v_bfe_u32 v77, v98, 16, 1
	v_add3_u32 v77, v98, v77, s31
	v_bfe_u32 v96, v99, 16, 1
	v_lshrrev_b32_e32 v77, 16, v77
	v_add3_u32 v96, v99, v96, s31
	v_and_or_b32 v103, v96, s33, v77
	v_bfe_u32 v77, v92, 16, 1
	v_add3_u32 v77, v92, v77, s31
	v_bfe_u32 v92, v93, 16, 1
	v_lshrrev_b32_e32 v77, 16, v77
	v_add3_u32 v92, v93, v92, s31
	v_and_or_b32 v92, v92, s33, v77
	v_bfe_u32 v77, v94, 16, 1
	v_add3_u32 v77, v94, v77, s31
	v_bfe_u32 v93, v95, 16, 1
	v_lshrrev_b32_e32 v77, 16, v77
	v_add3_u32 v93, v95, v93, s31
	v_and_or_b32 v93, v93, s33, v77
	v_bfe_u32 v77, v88, 16, 1
	v_add3_u32 v77, v88, v77, s31
	v_bfe_u32 v88, v89, 16, 1
	v_lshrrev_b32_e32 v77, 16, v77
	v_add3_u32 v88, v89, v88, s31
	v_and_or_b32 v94, v88, s33, v77
	v_bfe_u32 v77, v90, 16, 1
	v_add3_u32 v77, v90, v77, s31
	v_bfe_u32 v88, v91, 16, 1
	v_lshrrev_b32_e32 v77, 16, v77
	v_add3_u32 v88, v91, v88, s31
	v_and_or_b32 v95, v88, s33, v77
	v_bfe_u32 v77, v84, 16, 1
	v_add3_u32 v77, v84, v77, s31
	v_bfe_u32 v84, v85, 16, 1
	v_lshrrev_b32_e32 v77, 16, v77
	v_add3_u32 v84, v85, v84, s31
	v_and_or_b32 v84, v84, s33, v77
	v_bfe_u32 v77, v86, 16, 1
	v_add3_u32 v77, v86, v77, s31
	v_bfe_u32 v85, v87, 16, 1
	v_lshrrev_b32_e32 v77, 16, v77
	v_add3_u32 v85, v87, v85, s31
	v_and_or_b32 v85, v85, s33, v77
	v_bfe_u32 v77, v80, 16, 1
	v_add3_u32 v77, v80, v77, s31
	v_bfe_u32 v80, v81, 16, 1
	v_lshrrev_b32_e32 v77, 16, v77
	v_add3_u32 v80, v81, v80, s31
	v_and_or_b32 v86, v80, s33, v77
	v_bfe_u32 v77, v82, 16, 1
	v_or_b32_e32 v96, 32, v76
	v_add3_u32 v77, v82, v77, s31
	v_bfe_u32 v80, v83, 16, 1
	v_ashrrev_i32_e32 v97, 31, v96
	v_lshrrev_b32_e32 v77, 16, v77
	v_add3_u32 v80, v83, v80, s31
	v_ashrrev_i32_e32 v79, 31, v78
	v_lshlrev_b64 v[96:97], 12, v[96:97]
	v_and_or_b32 v87, v80, s33, v77
	v_or_b32_e32 v80, 48, v76
	v_lshlrev_b64 v[78:79], 1, v[78:79]
	v_lshl_add_u64 v[96:97], s[94:95], 0, v[96:97]
	v_ashrrev_i32_e32 v81, 31, v80
	v_lshl_add_u64 v[88:89], v[96:97], 0, v[78:79]
	v_lshlrev_b64 v[80:81], 12, v[80:81]
	v_bfe_u32 v77, v130, 16, 1
	global_store_dwordx4 v[88:89], v[84:87], off offset:64
	v_add3_u32 v77, v130, v77, s31
	v_lshrrev_b32_e32 v77, 16, v77
	v_lshl_add_u64 v[84:85], s[94:95], 0, v[80:81]
	v_bfe_u32 v80, v131, 16, 1
	v_add3_u32 v80, v131, v80, s31
	v_and_or_b32 v80, v80, s33, v77
	v_bfe_u32 v77, v132, 16, 1
	v_add3_u32 v77, v132, v77, s31
	v_bfe_u32 v81, v133, 16, 1
	v_lshrrev_b32_e32 v77, 16, v77
	v_add3_u32 v81, v133, v81, s31
	v_and_or_b32 v81, v81, s33, v77
	v_bfe_u32 v77, v72, 16, 1
	v_add3_u32 v72, v72, v77, s31
	v_bfe_u32 v77, v73, 16, 1
	v_lshrrev_b32_e32 v72, 16, v72
	v_add3_u32 v73, v73, v77, s31
	v_and_or_b32 v82, v73, s33, v72
	v_bfe_u32 v72, v74, 16, 1
	v_add3_u32 v72, v74, v72, s31
	v_bfe_u32 v74, v68, 16, 1
	v_add3_u32 v68, v68, v74, s31
	v_bfe_u32 v74, v69, 16, 1
	v_lshrrev_b32_e32 v68, 16, v68
	v_add3_u32 v69, v69, v74, s31
	v_and_or_b32 v68, v69, s33, v68
	v_bfe_u32 v69, v70, 16, 1
	v_add3_u32 v69, v70, v69, s31
	v_bfe_u32 v70, v71, 16, 1
	v_lshrrev_b32_e32 v69, 16, v69
	v_add3_u32 v70, v71, v70, s31
	v_and_or_b32 v69, v70, s33, v69
	v_bfe_u32 v70, v64, 16, 1
	v_add3_u32 v64, v64, v70, s31
	v_bfe_u32 v70, v65, 16, 1
	v_lshrrev_b32_e32 v64, 16, v64
	v_add3_u32 v65, v65, v70, s31
	v_and_or_b32 v70, v65, s33, v64
	v_bfe_u32 v64, v66, 16, 1
	v_add3_u32 v64, v66, v64, s31
	v_bfe_u32 v66, v60, 16, 1
	v_add3_u32 v60, v60, v66, s31
	v_bfe_u32 v66, v61, 16, 1
	v_lshrrev_b32_e32 v60, 16, v60
	v_add3_u32 v61, v61, v66, s31
	v_and_or_b32 v60, v61, s33, v60
	v_bfe_u32 v61, v62, 16, 1
	v_add3_u32 v61, v62, v61, s31
	v_bfe_u32 v62, v63, 16, 1
	v_lshrrev_b32_e32 v61, 16, v61
	v_add3_u32 v62, v63, v62, s31
	v_and_or_b32 v61, v62, s33, v61
	v_bfe_u32 v62, v56, 16, 1
	v_add3_u32 v56, v56, v62, s31
	v_bfe_u32 v62, v57, 16, 1
	v_lshrrev_b32_e32 v56, 16, v56
	v_add3_u32 v57, v57, v62, s31
	v_and_or_b32 v62, v57, s33, v56
	v_bfe_u32 v56, v58, 16, 1
	v_add3_u32 v56, v58, v56, s31
	v_bfe_u32 v58, v52, 16, 1
	v_add3_u32 v52, v52, v58, s31
	v_bfe_u32 v58, v53, 16, 1
	v_lshrrev_b32_e32 v52, 16, v52
	v_add3_u32 v53, v53, v58, s31
	v_and_or_b32 v52, v53, s33, v52
	v_bfe_u32 v53, v54, 16, 1
	v_add3_u32 v53, v54, v53, s31
	v_bfe_u32 v54, v55, 16, 1
	v_lshrrev_b32_e32 v53, 16, v53
	v_add3_u32 v54, v55, v54, s31
	v_and_or_b32 v53, v54, s33, v53
	v_bfe_u32 v54, v48, 16, 1
	v_add3_u32 v48, v48, v54, s31
	v_bfe_u32 v54, v49, 16, 1
	v_lshrrev_b32_e32 v48, 16, v48
	v_add3_u32 v49, v49, v54, s31
	v_and_or_b32 v54, v49, s33, v48
	v_bfe_u32 v48, v50, 16, 1
	v_add3_u32 v48, v50, v48, s31
	v_bfe_u32 v50, v44, 16, 1
	v_add3_u32 v44, v44, v50, s31
	v_bfe_u32 v50, v45, 16, 1
	v_lshrrev_b32_e32 v44, 16, v44
	v_add3_u32 v45, v45, v50, s31
	v_and_or_b32 v44, v45, s33, v44
	v_bfe_u32 v45, v46, 16, 1
	v_add3_u32 v45, v46, v45, s31
	v_bfe_u32 v46, v47, 16, 1
	v_lshrrev_b32_e32 v45, 16, v45
	v_add3_u32 v46, v47, v46, s31
	v_and_or_b32 v45, v46, s33, v45
	v_bfe_u32 v46, v40, 16, 1
	v_add3_u32 v40, v40, v46, s31
	v_bfe_u32 v46, v41, 16, 1
	v_lshrrev_b32_e32 v40, 16, v40
	v_add3_u32 v41, v41, v46, s31
	v_and_or_b32 v46, v41, s33, v40
	v_bfe_u32 v40, v42, 16, 1
	v_add3_u32 v40, v42, v40, s31
	v_bfe_u32 v42, v36, 16, 1
	v_add3_u32 v36, v36, v42, s31
	v_bfe_u32 v42, v37, 16, 1
	v_lshrrev_b32_e32 v36, 16, v36
	v_add3_u32 v37, v37, v42, s31
	v_and_or_b32 v36, v37, s33, v36
	v_bfe_u32 v37, v38, 16, 1
	v_add3_u32 v37, v38, v37, s31
	v_bfe_u32 v38, v39, 16, 1
	v_lshrrev_b32_e32 v37, 16, v37
	v_add3_u32 v38, v39, v38, s31
	v_and_or_b32 v37, v38, s33, v37
	v_bfe_u32 v38, v32, 16, 1
	v_add3_u32 v32, v32, v38, s31
	v_bfe_u32 v38, v33, 16, 1
	v_lshrrev_b32_e32 v32, 16, v32
	v_add3_u32 v33, v33, v38, s31
	v_and_or_b32 v38, v33, s33, v32
	v_bfe_u32 v32, v34, 16, 1
	v_add3_u32 v32, v34, v32, s31
	v_bfe_u32 v34, v28, 16, 1
	v_add3_u32 v28, v28, v34, s31
	v_bfe_u32 v34, v29, 16, 1
	v_lshrrev_b32_e32 v28, 16, v28
	v_add3_u32 v29, v29, v34, s31
	v_and_or_b32 v28, v29, s33, v28
	v_bfe_u32 v29, v30, 16, 1
	v_add3_u32 v29, v30, v29, s31
	v_bfe_u32 v30, v31, 16, 1
	v_lshrrev_b32_e32 v29, 16, v29
	v_add3_u32 v30, v31, v30, s31
	v_and_or_b32 v29, v30, s33, v29
	v_bfe_u32 v30, v24, 16, 1
	v_add3_u32 v24, v24, v30, s31
	v_bfe_u32 v30, v25, 16, 1
	v_lshrrev_b32_e32 v24, 16, v24
	v_add3_u32 v25, v25, v30, s31
	v_and_or_b32 v30, v25, s33, v24
	v_bfe_u32 v24, v26, 16, 1
	v_add3_u32 v24, v26, v24, s31
	v_bfe_u32 v26, v20, 16, 1
	v_add3_u32 v20, v20, v26, s31
	v_bfe_u32 v26, v21, 16, 1
	v_lshrrev_b32_e32 v20, 16, v20
	v_add3_u32 v21, v21, v26, s31
	v_and_or_b32 v20, v21, s33, v20
	v_bfe_u32 v21, v22, 16, 1
	v_add3_u32 v21, v22, v21, s31
	v_bfe_u32 v22, v23, 16, 1
	v_lshrrev_b32_e32 v21, 16, v21
	v_add3_u32 v22, v23, v22, s31
	v_and_or_b32 v21, v22, s33, v21
	v_bfe_u32 v22, v16, 16, 1
	v_add3_u32 v16, v16, v22, s31
	v_bfe_u32 v22, v17, 16, 1
	v_lshrrev_b32_e32 v16, 16, v16
	v_add3_u32 v17, v17, v22, s31
	v_and_or_b32 v22, v17, s33, v16
	v_bfe_u32 v16, v18, 16, 1
	v_add3_u32 v16, v18, v16, s31
	v_bfe_u32 v18, v12, 16, 1
	v_add3_u32 v12, v12, v18, s31
	v_bfe_u32 v18, v13, 16, 1
	v_lshrrev_b32_e32 v12, 16, v12
	v_add3_u32 v13, v13, v18, s31
	v_and_or_b32 v12, v13, s33, v12
	v_bfe_u32 v13, v14, 16, 1
	v_add3_u32 v13, v14, v13, s31
	v_bfe_u32 v14, v15, 16, 1
	v_lshrrev_b32_e32 v13, 16, v13
	v_add3_u32 v14, v15, v14, s31
	v_and_or_b32 v13, v14, s33, v13
	v_bfe_u32 v14, v8, 16, 1
	v_add3_u32 v8, v8, v14, s31
	v_bfe_u32 v14, v9, 16, 1
	v_lshrrev_b32_e32 v8, 16, v8
	v_add3_u32 v9, v9, v14, s31
	v_and_or_b32 v14, v9, s33, v8
	v_bfe_u32 v8, v10, 16, 1
	v_add3_u32 v8, v10, v8, s31
	v_bfe_u32 v10, v4, 16, 1
	v_add3_u32 v4, v4, v10, s31
	v_bfe_u32 v10, v5, 16, 1
	v_lshrrev_b32_e32 v4, 16, v4
	v_add3_u32 v5, v5, v10, s31
	v_and_or_b32 v4, v5, s33, v4
	v_bfe_u32 v5, v6, 16, 1
	v_add3_u32 v5, v6, v5, s31
	v_bfe_u32 v6, v7, 16, 1
	v_lshrrev_b32_e32 v5, 16, v5
	v_add3_u32 v6, v7, v6, s31
	v_bfe_u32 v65, v67, 16, 1
	v_bfe_u32 v49, v51, 16, 1
	v_bfe_u32 v33, v35, 16, 1
	v_bfe_u32 v17, v19, 16, 1
	v_and_or_b32 v5, v6, s33, v5
	v_bfe_u32 v6, v0, 16, 1
	v_lshrrev_b32_e32 v64, 16, v64
	v_add3_u32 v65, v67, v65, s31
	v_lshrrev_b32_e32 v48, 16, v48
	v_add3_u32 v49, v51, v49, s31
	v_lshrrev_b32_e32 v32, 16, v32
	v_add3_u32 v33, v35, v33, s31
	v_lshrrev_b32_e32 v16, 16, v16
	v_add3_u32 v17, v19, v17, s31
	v_add3_u32 v0, v0, v6, s31
	v_bfe_u32 v6, v1, 16, 1
	v_or_b32_e32 v112, 16, v76
	v_and_or_b32 v71, v65, s33, v64
	v_or_b32_e32 v64, 64, v76
	v_and_or_b32 v55, v49, s33, v48
	v_or_b32_e32 v48, 0x50, v76
	v_and_or_b32 v39, v33, s33, v32
	v_or_b32_e32 v32, 0x60, v76
	v_and_or_b32 v23, v17, s33, v16
	v_or_b32_e32 v16, 0x70, v76
	v_lshrrev_b32_e32 v0, 16, v0
	v_add3_u32 v1, v1, v6, s31
	v_ashrrev_i32_e32 v113, 31, v112
	v_ashrrev_i32_e32 v65, 31, v64
	v_ashrrev_i32_e32 v49, 31, v48
	v_ashrrev_i32_e32 v33, 31, v32
	v_ashrrev_i32_e32 v17, 31, v16
	v_and_or_b32 v6, v1, s33, v0
	v_bfe_u32 v0, v2, 16, 1
	v_lshlrev_b64 v[112:113], 12, v[112:113]
	v_bfe_u32 v73, v75, 16, 1
	v_lshlrev_b64 v[64:65], 12, v[64:65]
	v_bfe_u32 v57, v59, 16, 1
	v_lshlrev_b64 v[48:49], 12, v[48:49]
	v_bfe_u32 v41, v43, 16, 1
	v_lshlrev_b64 v[32:33], 12, v[32:33]
	v_bfe_u32 v25, v27, 16, 1
	v_lshlrev_b64 v[16:17], 12, v[16:17]
	v_bfe_u32 v9, v11, 16, 1
	v_add3_u32 v0, v2, v0, s31
	v_bfe_u32 v1, v3, 16, 1
	v_lshl_add_u64 v[136:137], s[94:95], 0, v[136:137]
	v_lshl_add_u64 v[112:113], s[94:95], 0, v[112:113]
	v_lshrrev_b32_e32 v72, 16, v72
	v_add3_u32 v73, v75, v73, s31
	v_lshl_add_u64 v[64:65], s[94:95], 0, v[64:65]
	v_lshrrev_b32_e32 v56, 16, v56
	v_add3_u32 v57, v59, v57, s31
	v_lshl_add_u64 v[48:49], s[94:95], 0, v[48:49]
	v_lshrrev_b32_e32 v40, 16, v40
	v_add3_u32 v41, v43, v41, s31
	v_lshl_add_u64 v[32:33], s[94:95], 0, v[32:33]
	v_lshrrev_b32_e32 v24, 16, v24
	v_add3_u32 v25, v27, v25, s31
	v_lshl_add_u64 v[16:17], s[94:95], 0, v[16:17]
	v_lshrrev_b32_e32 v8, 16, v8
	v_add3_u32 v9, v11, v9, s31
	v_lshrrev_b32_e32 v0, 16, v0
	v_add3_u32 v1, v3, v1, s31
	v_lshl_add_u64 v[120:121], v[136:137], 0, v[78:79]
	v_lshl_add_u64 v[104:105], v[112:113], 0, v[78:79]
	v_and_or_b32 v83, v73, s33, v72
	v_lshl_add_u64 v[72:73], v[84:85], 0, v[78:79]
	v_and_or_b32 v63, v57, s33, v56
	v_lshl_add_u64 v[56:57], v[64:65], 0, v[78:79]
	v_and_or_b32 v47, v41, s33, v40
	v_lshl_add_u64 v[40:41], v[48:49], 0, v[78:79]
	v_and_or_b32 v31, v25, s33, v24
	v_lshl_add_u64 v[24:25], v[32:33], 0, v[78:79]
	v_and_or_b32 v15, v9, s33, v8
	v_lshl_add_u64 v[8:9], v[16:17], 0, v[78:79]
	v_and_or_b32 v7, v1, s33, v0
	global_store_dwordx4 v[120:121], v[124:127], off
	global_store_dwordx4 v[120:121], v[116:119], off offset:64
	global_store_dwordx4 v[104:105], v[108:111], off
	global_store_dwordx4 v[104:105], v[100:103], off offset:64
	global_store_dwordx4 v[88:89], v[92:95], off
	global_store_dwordx4 v[72:73], v[80:83], off
	global_store_dwordx4 v[72:73], v[68:71], off offset:64
	global_store_dwordx4 v[56:57], v[60:63], off
	global_store_dwordx4 v[56:57], v[52:55], off offset:64
	global_store_dwordx4 v[40:41], v[44:47], off
	global_store_dwordx4 v[40:41], v[36:39], off offset:64
	global_store_dwordx4 v[24:25], v[28:31], off
	global_store_dwordx4 v[24:25], v[20:23], off offset:64
	global_store_dwordx4 v[8:9], v[12:15], off
	global_store_dwordx4 v[8:9], v[4:7], off offset:64
	s_branch .LBB0_1319

.LBB0_1874:
	s_add_i32 s29, s28, 2
	s_mul_hi_i32 s30, s29, 0x55555556
	s_lshr_b32 s31, s30, 31
	s_add_i32 s30, s30, s31
	s_mul_i32 s30, s30, 3
	s_sub_i32 s29, s29, s30
	s_mulk_i32 s29, 0x6000
	s_mul_i32 s54, s28, 0x6000
	v_readfirstlane_b32 s55, v142
	v_lshl_add_u64 v[232:233], v[132:133], 0, s[4:5]
	v_lshl_add_u64 v[234:235], v[130:131], 0, s[4:5]
	s_add_u32 s55, s55, s29
	s_waitcnt vmcnt(6) lgkmcnt(0)
	s_barrier
	s_setprio 1
	s_mov_b32 m0, s55
	v_lshl_add_u64 v[236:237], v[232:233], 0, s[6:7]
	global_load_lds_dwordx4 v[236:237], off
	s_add_u32 m0, s55, 0x1000
	v_lshl_add_u64 v[236:237], v[232:233], 0, s[8:9]
	global_load_lds_dwordx4 v[236:237], off
	s_add_u32 m0, s55, 0x2000
	v_lshl_add_u64 v[236:237], v[232:233], 0, s[10:11]
	global_load_lds_dwordx4 v[236:237], off
	s_add_u32 m0, s55, 0x3000
	v_lshl_add_u64 v[236:237], v[232:233], 0, s[12:13]
	global_load_lds_dwordx4 v[236:237], off
	s_add_u32 m0, s55, 0x4000
	v_lshl_add_u64 v[236:237], v[234:235], 0, s[14:15]
	global_load_lds_dwordx4 v[236:237], off
	s_add_u32 m0, s55, 0x5000
	v_lshl_add_u64 v[236:237], v[234:235], 0, s[16:17]
	global_load_lds_dwordx4 v[236:237], off
	v_or_b32_e32 v128, s54, v140
	v_add3_u32 v128, v128, v141, v139
	ds_read_b128 v[176:179], v128 offset:16384
	ds_read_b128 v[180:183], v128 offset:16640
	ds_read_b128 v[184:187], v128 offset:18432
	ds_read_b128 v[192:195], v128 offset:18688
	v_add3_u32 v128, s54, v143, v139
	ds_read_b128 v[144:147], v128
	ds_read_b128 v[148:151], v128 offset:1024
	ds_read_b128 v[152:155], v128 offset:2048
	ds_read_b128 v[156:159], v128 offset:3072
	ds_read_b128 v[160:163], v128 offset:4096
	ds_read_b128 v[164:167], v128 offset:5120
	ds_read_b128 v[168:171], v128 offset:6144
	ds_read_b128 v[172:175], v128 offset:7168
	s_setprio 0
	s_waitcnt lgkmcnt(7)
	v_mfma_f32_16x16x32_bf16 v[124:127], v[176:179], v[144:147], v[124:127]
	v_mfma_f32_16x16x32_bf16 v[120:123], v[180:183], v[144:147], v[120:123]
	v_mfma_f32_16x16x32_bf16 v[116:119], v[184:187], v[144:147], v[116:119]
	v_mfma_f32_16x16x32_bf16 v[112:115], v[192:195], v[144:147], v[112:115]
	s_waitcnt lgkmcnt(6)
	v_mfma_f32_16x16x32_bf16 v[108:111], v[176:179], v[148:151], v[108:111]
	v_mfma_f32_16x16x32_bf16 v[104:107], v[180:183], v[148:151], v[104:107]
	v_mfma_f32_16x16x32_bf16 v[100:103], v[184:187], v[148:151], v[100:103]
	v_mfma_f32_16x16x32_bf16 v[96:99], v[192:195], v[148:151], v[96:99]
	s_waitcnt lgkmcnt(5)
	v_mfma_f32_16x16x32_bf16 v[92:95], v[176:179], v[152:155], v[92:95]
	v_mfma_f32_16x16x32_bf16 v[88:91], v[180:183], v[152:155], v[88:91]
	v_mfma_f32_16x16x32_bf16 v[84:87], v[184:187], v[152:155], v[84:87]
	v_mfma_f32_16x16x32_bf16 v[80:83], v[192:195], v[152:155], v[80:83]
	s_waitcnt lgkmcnt(4)
	v_mfma_f32_16x16x32_bf16 v[76:79], v[176:179], v[156:159], v[76:79]
	v_mfma_f32_16x16x32_bf16 v[72:75], v[180:183], v[156:159], v[72:75]
	v_mfma_f32_16x16x32_bf16 v[68:71], v[184:187], v[156:159], v[68:71]
	v_mfma_f32_16x16x32_bf16 v[64:67], v[192:195], v[156:159], v[64:67]
	s_waitcnt lgkmcnt(3)
	v_mfma_f32_16x16x32_bf16 v[60:63], v[176:179], v[160:163], v[60:63]
	v_mfma_f32_16x16x32_bf16 v[56:59], v[180:183], v[160:163], v[56:59]
	v_mfma_f32_16x16x32_bf16 v[52:55], v[184:187], v[160:163], v[52:55]
	v_mfma_f32_16x16x32_bf16 v[48:51], v[192:195], v[160:163], v[48:51]
	s_waitcnt lgkmcnt(2)
	v_mfma_f32_16x16x32_bf16 v[44:47], v[176:179], v[164:167], v[44:47]
	v_mfma_f32_16x16x32_bf16 v[40:43], v[180:183], v[164:167], v[40:43]
	v_mfma_f32_16x16x32_bf16 v[36:39], v[184:187], v[164:167], v[36:39]
	v_mfma_f32_16x16x32_bf16 v[32:35], v[192:195], v[164:167], v[32:35]
	s_waitcnt lgkmcnt(1)
	v_mfma_f32_16x16x32_bf16 v[28:31], v[176:179], v[168:171], v[28:31]
	v_mfma_f32_16x16x32_bf16 v[24:27], v[180:183], v[168:171], v[24:27]
	v_mfma_f32_16x16x32_bf16 v[20:23], v[184:187], v[168:171], v[20:23]
	v_mfma_f32_16x16x32_bf16 v[16:19], v[192:195], v[168:171], v[16:19]
	s_waitcnt lgkmcnt(0)
	v_mfma_f32_16x16x32_bf16 v[12:15], v[176:179], v[172:175], v[12:15]
	v_mfma_f32_16x16x32_bf16 v[8:11], v[180:183], v[172:175], v[8:11]
	v_mfma_f32_16x16x32_bf16 v[4:7], v[184:187], v[172:175], v[4:7]
	v_mfma_f32_16x16x32_bf16 v[0:3], v[192:195], v[172:175], v[0:3]
	s_add_i32 s29, s28, 1
	s_cmp_lg_u32 s28, 2
	s_cselect_b32 s28, s29, 0
	s_add_u32 s4, s4, 64
	s_addc_u32 s5, s5, 0
	s_cmpk_eq_i32 s4, 0xf80
	s_cbranch_scc0 .LBB0_1874
	s_waitcnt vmcnt(6) lgkmcnt(0)
	s_barrier
	v_add_u32_e32 v128, v143, v139
	ds_read_b128 v[130:133], v128 offset:49152
	ds_read_b128 v[142:145], v128 offset:50176
	ds_read_b128 v[146:149], v128 offset:51200
	ds_read_b128 v[150:153], v128 offset:52224
	ds_read_b128 v[154:157], v128 offset:53248
	ds_read_b128 v[158:161], v128 offset:54272
	ds_read_b128 v[162:165], v128 offset:55296
	ds_read_b128 v[166:169], v128 offset:56320
	v_add3_u32 v139, v140, v141, v139
	v_add_u32_e32 v140, 0xc000, v139
	ds_read_b128 v[170:173], v140 offset:16384
	ds_read_b128 v[174:177], v140 offset:16640
	ds_read_b128 v[178:181], v140 offset:18432
	ds_read_b128 v[182:185], v140 offset:18688
	s_setprio 1
	s_waitcnt lgkmcnt(0)
	v_mfma_f32_16x16x32_bf16 v[124:127], v[170:173], v[130:133], v[124:127]
	v_mfma_f32_16x16x32_bf16 v[120:123], v[174:177], v[130:133], v[120:123]
	v_mfma_f32_16x16x32_bf16 v[116:119], v[178:181], v[130:133], v[116:119]
	v_mfma_f32_16x16x32_bf16 v[112:115], v[182:185], v[130:133], v[112:115]
	v_mfma_f32_16x16x32_bf16 v[108:111], v[170:173], v[142:145], v[108:111]
	v_mfma_f32_16x16x32_bf16 v[104:107], v[174:177], v[142:145], v[104:107]
	v_mfma_f32_16x16x32_bf16 v[100:103], v[178:181], v[142:145], v[100:103]
	v_mfma_f32_16x16x32_bf16 v[96:99], v[182:185], v[142:145], v[96:99]
	v_mfma_f32_16x16x32_bf16 v[92:95], v[170:173], v[146:149], v[92:95]
	v_mfma_f32_16x16x32_bf16 v[88:91], v[174:177], v[146:149], v[88:91]
	v_mfma_f32_16x16x32_bf16 v[84:87], v[178:181], v[146:149], v[84:87]
	v_mfma_f32_16x16x32_bf16 v[80:83], v[182:185], v[146:149], v[80:83]
	v_mfma_f32_16x16x32_bf16 v[76:79], v[170:173], v[150:153], v[76:79]
	v_mfma_f32_16x16x32_bf16 v[72:75], v[174:177], v[150:153], v[72:75]
	v_mfma_f32_16x16x32_bf16 v[68:71], v[178:181], v[150:153], v[68:71]
	v_mfma_f32_16x16x32_bf16 v[64:67], v[182:185], v[150:153], v[64:67]
	v_mfma_f32_16x16x32_bf16 v[60:63], v[170:173], v[154:157], v[60:63]
	v_mfma_f32_16x16x32_bf16 v[56:59], v[174:177], v[154:157], v[56:59]
	v_mfma_f32_16x16x32_bf16 v[52:55], v[178:181], v[154:157], v[52:55]
	v_mfma_f32_16x16x32_bf16 v[48:51], v[182:185], v[154:157], v[48:51]
	v_mfma_f32_16x16x32_bf16 v[44:47], v[170:173], v[158:161], v[44:47]
	v_mfma_f32_16x16x32_bf16 v[40:43], v[174:177], v[158:161], v[40:43]
	v_mfma_f32_16x16x32_bf16 v[36:39], v[178:181], v[158:161], v[36:39]
	v_mfma_f32_16x16x32_bf16 v[32:35], v[182:185], v[158:161], v[32:35]
	v_mfma_f32_16x16x32_bf16 v[28:31], v[170:173], v[162:165], v[28:31]
	v_mfma_f32_16x16x32_bf16 v[24:27], v[174:177], v[162:165], v[24:27]
	v_mfma_f32_16x16x32_bf16 v[20:23], v[178:181], v[162:165], v[20:23]
	v_mfma_f32_16x16x32_bf16 v[16:19], v[182:185], v[162:165], v[16:19]
	v_mfma_f32_16x16x32_bf16 v[12:15], v[170:173], v[166:169], v[12:15]
	v_mfma_f32_16x16x32_bf16 v[8:11], v[174:177], v[166:169], v[8:11]
	v_mfma_f32_16x16x32_bf16 v[4:7], v[178:181], v[166:169], v[4:7]
	v_mfma_f32_16x16x32_bf16 v[0:3], v[182:185], v[166:169], v[0:3]
	s_setprio 0
	s_waitcnt vmcnt(0) lgkmcnt(0)
	s_barrier
	ds_read_b128 v[130:133], v128
	ds_read_b128 v[140:143], v128 offset:1024
	ds_read_b128 v[144:147], v128 offset:2048
	ds_read_b128 v[148:151], v128 offset:3072
	ds_read_b128 v[152:155], v128 offset:4096
	ds_read_b128 v[156:159], v128 offset:5120
	ds_read_b128 v[160:163], v128 offset:6144
	ds_read_b128 v[164:167], v128 offset:7168
	ds_read_b128 v[168:171], v139 offset:16384
	ds_read_b128 v[172:175], v139 offset:16640
	ds_read_b128 v[176:179], v139 offset:18432
	ds_read_b128 v[180:183], v139 offset:18688
	s_setprio 1
	s_waitcnt lgkmcnt(0)
	v_mfma_f32_16x16x32_bf16 v[124:127], v[168:171], v[130:133], v[124:127]
	v_mfma_f32_16x16x32_bf16 v[120:123], v[172:175], v[130:133], v[120:123]
	v_mfma_f32_16x16x32_bf16 v[116:119], v[176:179], v[130:133], v[116:119]
	v_mfma_f32_16x16x32_bf16 v[112:115], v[180:183], v[130:133], v[112:115]
	v_mfma_f32_16x16x32_bf16 v[108:111], v[168:171], v[140:143], v[108:111]
	v_mfma_f32_16x16x32_bf16 v[104:107], v[172:175], v[140:143], v[104:107]
	v_mfma_f32_16x16x32_bf16 v[100:103], v[176:179], v[140:143], v[100:103]
	v_mfma_f32_16x16x32_bf16 v[96:99], v[180:183], v[140:143], v[96:99]
	v_mfma_f32_16x16x32_bf16 v[92:95], v[168:171], v[144:147], v[92:95]
	v_mfma_f32_16x16x32_bf16 v[88:91], v[172:175], v[144:147], v[88:91]
	v_mfma_f32_16x16x32_bf16 v[84:87], v[176:179], v[144:147], v[84:87]
	v_mfma_f32_16x16x32_bf16 v[80:83], v[180:183], v[144:147], v[80:83]
	v_mfma_f32_16x16x32_bf16 v[76:79], v[168:171], v[148:151], v[76:79]
	v_mfma_f32_16x16x32_bf16 v[72:75], v[172:175], v[148:151], v[72:75]
	v_mfma_f32_16x16x32_bf16 v[68:71], v[176:179], v[148:151], v[68:71]
	v_mfma_f32_16x16x32_bf16 v[64:67], v[180:183], v[148:151], v[64:67]
	v_mfma_f32_16x16x32_bf16 v[60:63], v[168:171], v[152:155], v[60:63]
	v_mfma_f32_16x16x32_bf16 v[56:59], v[172:175], v[152:155], v[56:59]
	v_mfma_f32_16x16x32_bf16 v[52:55], v[176:179], v[152:155], v[52:55]
	v_mfma_f32_16x16x32_bf16 v[48:51], v[180:183], v[152:155], v[48:51]
	v_mfma_f32_16x16x32_bf16 v[44:47], v[168:171], v[156:159], v[44:47]
	v_mfma_f32_16x16x32_bf16 v[40:43], v[172:175], v[156:159], v[40:43]
	v_mfma_f32_16x16x32_bf16 v[36:39], v[176:179], v[156:159], v[36:39]
	v_mfma_f32_16x16x32_bf16 v[32:35], v[180:183], v[156:159], v[32:35]
	v_mfma_f32_16x16x32_bf16 v[28:31], v[168:171], v[160:163], v[28:31]
	v_mfma_f32_16x16x32_bf16 v[24:27], v[172:175], v[160:163], v[24:27]
	v_mfma_f32_16x16x32_bf16 v[20:23], v[176:179], v[160:163], v[20:23]
	v_mfma_f32_16x16x32_bf16 v[16:19], v[180:183], v[160:163], v[16:19]
	v_mfma_f32_16x16x32_bf16 v[12:15], v[168:171], v[164:167], v[12:15]
	v_mfma_f32_16x16x32_bf16 v[8:11], v[172:175], v[164:167], v[8:11]
	v_mfma_f32_16x16x32_bf16 v[4:7], v[176:179], v[164:167], v[4:7]
	v_mfma_f32_16x16x32_bf16 v[0:3], v[180:183], v[164:167], v[0:3]
	s_setprio 0
	v_and_b32_e32 v128, 0xffffff80, v137
	v_add_u32_e32 v139, s27, v128
	v_and_or_b32 v130, v137, 63, v139
	v_cmp_gt_i32_e32 vcc, s23, v130
	v_mov_b32_e32 v140, 0x358637bd
	v_mov_b32_e32 v141, 0x358637bd
	s_and_saveexec_b64 s[4:5], vcc
	s_cbranch_execz .LBB0_1877
	v_ashrrev_i32_e32 v131, 31, v130
	v_readlane_b32 s28, v254, 18
	v_lshlrev_b64 v[132:133], 7, v[130:131]
	v_readlane_b32 s29, v254, 19
	s_nop 1
	v_lshl_add_u64 v[132:133], s[28:29], 0, v[132:133]
	global_load_dwordx4 v[142:145], v[132:133], off
	global_load_dwordx4 v[146:149], v[132:133], off offset:16
	global_load_dwordx4 v[150:153], v[132:133], off offset:32
	global_load_dwordx4 v[154:157], v[132:133], off offset:48
	global_load_dwordx4 v[158:161], v[132:133], off offset:64
	global_load_dwordx4 v[162:165], v[132:133], off offset:80
	global_load_dwordx4 v[166:169], v[132:133], off offset:96
	global_load_dwordx4 v[170:173], v[132:133], off offset:112
	s_waitcnt vmcnt(0)
	v_mov_b32_e32 v132, v142
	v_mov_b32_e32 v133, v146
	v_mov_b32_e32 v146, v143
	v_mov_b32_e32 v142, v144
	v_mov_b32_e32 v143, v148
	v_pk_add_f32 v[132:133], v[132:133], v[146:147]
	v_mov_b32_e32 v148, v145
	v_mov_b32_e32 v144, v150
	v_mov_b32_e32 v145, v154
	v_mov_b32_e32 v154, v151
	v_pk_add_f32 v[132:133], v[132:133], v[142:143]
	v_mov_b32_e32 v150, v152
	v_mov_b32_e32 v151, v156
	v_pk_add_f32 v[144:145], v[144:145], v[154:155]
	v_pk_add_f32 v[132:133], v[132:133], v[148:149]
	v_mov_b32_e32 v156, v153
	v_mov_b32_e32 v152, v158
	v_mov_b32_e32 v153, v162
	v_mov_b32_e32 v162, v159
	v_pk_add_f32 v[142:143], v[144:145], v[150:151]
	v_add_f32_e32 v128, 0, v132
	v_mov_b32_e32 v158, v160
	v_mov_b32_e32 v159, v164
	v_pk_add_f32 v[146:147], v[152:153], v[162:163]
	v_pk_add_f32 v[142:143], v[142:143], v[156:157]
	v_add_f32_e32 v128, v128, v133
	v_mov_b32_e32 v164, v161
	v_mov_b32_e32 v160, v166
	v_mov_b32_e32 v161, v170
	v_mov_b32_e32 v170, v167
	v_pk_add_f32 v[144:145], v[146:147], v[158:159]
	v_add_f32_e32 v128, v128, v142
	v_mov_b32_e32 v166, v168
	v_mov_b32_e32 v167, v172
	v_pk_add_f32 v[152:153], v[160:161], v[170:171]
	v_pk_add_f32 v[144:145], v[144:145], v[164:165]
	v_add_f32_e32 v128, v128, v143
	v_mov_b32_e32 v172, v169
	v_pk_add_f32 v[146:147], v[152:153], v[166:167]
	v_add_f32_e32 v128, v128, v144
	v_add_f32_e32 v128, v128, v145
	v_pk_add_f32 v[132:133], v[146:147], v[172:173]
	s_nop 0
	v_add_f32_e32 v128, v128, v132
	v_add_f32_e32 v128, v128, v133
	v_fmamk_f32 v141, v128, 0x3a000000, v134

.LBB0_1945:
	s_add_i32 s51, s50, 2
	s_mul_hi_i32 s52, s51, 0x55555556
	s_lshr_b32 s53, s52, 31
	s_add_i32 s52, s52, s53
	s_mul_i32 s52, s52, 3
	s_sub_i32 s51, s51, s52
	s_mulk_i32 s51, 0x6000
	s_mul_i32 s54, s50, 0x6000
	v_readfirstlane_b32 s55, v140
	v_lshl_add_u64 v[232:233], v[132:133], 0, s[0:1]
	v_lshl_add_u64 v[234:235], v[130:131], 0, s[0:1]
	s_add_u32 s55, s55, s51
	s_waitcnt vmcnt(6) lgkmcnt(0)
	s_barrier
	s_setprio 1
	s_mov_b32 m0, s55
	v_lshl_add_u64 v[236:237], v[232:233], 0, s[20:21]
	global_load_lds_dwordx4 v[236:237], off
	s_add_u32 m0, s55, 0x1000
	v_lshl_add_u64 v[236:237], v[232:233], 0, s[22:23]
	global_load_lds_dwordx4 v[236:237], off
	s_add_u32 m0, s55, 0x2000
	v_lshl_add_u64 v[236:237], v[232:233], 0, s[24:25]
	global_load_lds_dwordx4 v[236:237], off
	s_add_u32 m0, s55, 0x3000
	v_lshl_add_u64 v[236:237], v[232:233], 0, s[26:27]
	global_load_lds_dwordx4 v[236:237], off
	s_add_u32 m0, s55, 0x4000
	v_lshl_add_u64 v[236:237], v[234:235], 0, s[28:29]
	global_load_lds_dwordx4 v[236:237], off
	s_add_u32 m0, s55, 0x5000
	v_lshl_add_u64 v[236:237], v[234:235], 0, s[30:31]
	global_load_lds_dwordx4 v[236:237], off
	v_or_b32_e32 v128, s54, v139
	v_add3_u32 v128, v128, v137, v138
	ds_read_b128 v[176:179], v128 offset:16384
	ds_read_b128 v[180:183], v128 offset:17408
	ds_read_b128 v[184:187], v128 offset:18432
	ds_read_b128 v[192:195], v128 offset:19456
	v_add_u32_e32 v128, s54, v141
	v_add3_u32 v128, v128, v137, v138
	ds_read_b128 v[144:147], v128
	ds_read_b128 v[148:151], v128 offset:1024
	ds_read_b128 v[152:155], v128 offset:2048
	ds_read_b128 v[156:159], v128 offset:3072
	ds_read_b128 v[160:163], v128 offset:4096
	ds_read_b128 v[164:167], v128 offset:5120
	ds_read_b128 v[168:171], v128 offset:6144
	ds_read_b128 v[172:175], v128 offset:7168
	s_setprio 0
	s_waitcnt lgkmcnt(7)
	v_mfma_f32_16x16x32_bf16 v[124:127], v[144:147], v[176:179], v[124:127]
	v_mfma_f32_16x16x32_bf16 v[120:123], v[144:147], v[180:183], v[120:123]
	v_mfma_f32_16x16x32_bf16 v[116:119], v[144:147], v[184:187], v[116:119]
	v_mfma_f32_16x16x32_bf16 v[112:115], v[144:147], v[192:195], v[112:115]
	s_waitcnt lgkmcnt(6)
	v_mfma_f32_16x16x32_bf16 v[108:111], v[148:151], v[176:179], v[108:111]
	v_mfma_f32_16x16x32_bf16 v[104:107], v[148:151], v[180:183], v[104:107]
	v_mfma_f32_16x16x32_bf16 v[100:103], v[148:151], v[184:187], v[100:103]
	v_mfma_f32_16x16x32_bf16 v[96:99], v[148:151], v[192:195], v[96:99]
	s_waitcnt lgkmcnt(5)
	v_mfma_f32_16x16x32_bf16 v[92:95], v[152:155], v[176:179], v[92:95]
	v_mfma_f32_16x16x32_bf16 v[88:91], v[152:155], v[180:183], v[88:91]
	v_mfma_f32_16x16x32_bf16 v[84:87], v[152:155], v[184:187], v[84:87]
	v_mfma_f32_16x16x32_bf16 v[80:83], v[152:155], v[192:195], v[80:83]
	s_waitcnt lgkmcnt(4)
	v_mfma_f32_16x16x32_bf16 v[76:79], v[156:159], v[176:179], v[76:79]
	v_mfma_f32_16x16x32_bf16 v[72:75], v[156:159], v[180:183], v[72:75]
	v_mfma_f32_16x16x32_bf16 v[68:71], v[156:159], v[184:187], v[68:71]
	v_mfma_f32_16x16x32_bf16 v[64:67], v[156:159], v[192:195], v[64:67]
	s_waitcnt lgkmcnt(3)
	v_mfma_f32_16x16x32_bf16 v[60:63], v[160:163], v[176:179], v[60:63]
	v_mfma_f32_16x16x32_bf16 v[56:59], v[160:163], v[180:183], v[56:59]
	v_mfma_f32_16x16x32_bf16 v[52:55], v[160:163], v[184:187], v[52:55]
	v_mfma_f32_16x16x32_bf16 v[48:51], v[160:163], v[192:195], v[48:51]
	s_waitcnt lgkmcnt(2)
	v_mfma_f32_16x16x32_bf16 v[44:47], v[164:167], v[176:179], v[44:47]
	v_mfma_f32_16x16x32_bf16 v[40:43], v[164:167], v[180:183], v[40:43]
	v_mfma_f32_16x16x32_bf16 v[36:39], v[164:167], v[184:187], v[36:39]
	v_mfma_f32_16x16x32_bf16 v[32:35], v[164:167], v[192:195], v[32:35]
	s_waitcnt lgkmcnt(1)
	v_mfma_f32_16x16x32_bf16 v[28:31], v[168:171], v[176:179], v[28:31]
	v_mfma_f32_16x16x32_bf16 v[24:27], v[168:171], v[180:183], v[24:27]
	v_mfma_f32_16x16x32_bf16 v[20:23], v[168:171], v[184:187], v[20:23]
	v_mfma_f32_16x16x32_bf16 v[16:19], v[168:171], v[192:195], v[16:19]
	s_waitcnt lgkmcnt(0)
	v_mfma_f32_16x16x32_bf16 v[12:15], v[172:175], v[176:179], v[12:15]
	v_mfma_f32_16x16x32_bf16 v[8:11], v[172:175], v[180:183], v[8:11]
	v_mfma_f32_16x16x32_bf16 v[4:7], v[172:175], v[184:187], v[4:7]
	v_mfma_f32_16x16x32_bf16 v[0:3], v[172:175], v[192:195], v[0:3]
	s_add_i32 s51, s50, 1
	s_cmp_lg_u32 s50, 2
	s_cselect_b32 s50, s51, 0
	s_add_u32 s0, s0, 0x80
	s_addc_u32 s1, s1, 0
	s_cmpk_lg_i32 s0, 0xf00
	s_cbranch_scc1 .LBB0_1945
	s_waitcnt vmcnt(6) lgkmcnt(0)
	s_barrier
	v_add3_u32 v128, v141, v137, v138
	ds_read_b128 v[130:133], v128
	ds_read_b128 v[144:147], v128 offset:1024
	ds_read_b128 v[148:151], v128 offset:2048
	ds_read_b128 v[152:155], v128 offset:3072
	ds_read_b128 v[156:159], v128 offset:4096
	ds_read_b128 v[160:163], v128 offset:5120
	ds_read_b128 v[164:167], v128 offset:6144
	ds_read_b128 v[168:171], v128 offset:7168
	v_add3_u32 v137, v139, v137, v138
	ds_read_b128 v[138:141], v137 offset:16384
	ds_read_b128 v[172:175], v137 offset:17408
	ds_read_b128 v[176:179], v137 offset:18432
	ds_read_b128 v[180:183], v137 offset:19456
	s_setprio 1
	s_waitcnt lgkmcnt(0)
	v_mfma_f32_16x16x32_bf16 v[124:127], v[130:133], v[138:141], v[124:127]
	v_mfma_f32_16x16x32_bf16 v[120:123], v[130:133], v[172:175], v[120:123]
	v_mfma_f32_16x16x32_bf16 v[116:119], v[130:133], v[176:179], v[116:119]
	v_mfma_f32_16x16x32_bf16 v[112:115], v[130:133], v[180:183], v[112:115]
	v_mfma_f32_16x16x32_bf16 v[108:111], v[144:147], v[138:141], v[108:111]
	v_mfma_f32_16x16x32_bf16 v[104:107], v[144:147], v[172:175], v[104:107]
	v_mfma_f32_16x16x32_bf16 v[100:103], v[144:147], v[176:179], v[100:103]
	v_mfma_f32_16x16x32_bf16 v[96:99], v[144:147], v[180:183], v[96:99]
	v_mfma_f32_16x16x32_bf16 v[92:95], v[148:151], v[138:141], v[92:95]
	v_mfma_f32_16x16x32_bf16 v[88:91], v[148:151], v[172:175], v[88:91]
	v_mfma_f32_16x16x32_bf16 v[84:87], v[148:151], v[176:179], v[84:87]
	v_mfma_f32_16x16x32_bf16 v[80:83], v[148:151], v[180:183], v[80:83]
	v_mfma_f32_16x16x32_bf16 v[76:79], v[152:155], v[138:141], v[76:79]
	v_mfma_f32_16x16x32_bf16 v[72:75], v[152:155], v[172:175], v[72:75]
	v_mfma_f32_16x16x32_bf16 v[68:71], v[152:155], v[176:179], v[68:71]
	v_mfma_f32_16x16x32_bf16 v[64:67], v[152:155], v[180:183], v[64:67]
	v_mfma_f32_16x16x32_bf16 v[60:63], v[156:159], v[138:141], v[60:63]
	v_mfma_f32_16x16x32_bf16 v[56:59], v[156:159], v[172:175], v[56:59]
	v_mfma_f32_16x16x32_bf16 v[52:55], v[156:159], v[176:179], v[52:55]
	v_mfma_f32_16x16x32_bf16 v[48:51], v[156:159], v[180:183], v[48:51]
	v_mfma_f32_16x16x32_bf16 v[44:47], v[160:163], v[138:141], v[44:47]
	v_mfma_f32_16x16x32_bf16 v[40:43], v[160:163], v[172:175], v[40:43]
	v_mfma_f32_16x16x32_bf16 v[36:39], v[160:163], v[176:179], v[36:39]
	v_mfma_f32_16x16x32_bf16 v[32:35], v[160:163], v[180:183], v[32:35]
	v_mfma_f32_16x16x32_bf16 v[28:31], v[164:167], v[138:141], v[28:31]
	v_mfma_f32_16x16x32_bf16 v[24:27], v[164:167], v[172:175], v[24:27]
	v_mfma_f32_16x16x32_bf16 v[20:23], v[164:167], v[176:179], v[20:23]
	v_mfma_f32_16x16x32_bf16 v[16:19], v[164:167], v[180:183], v[16:19]
	v_mfma_f32_16x16x32_bf16 v[12:15], v[168:171], v[138:141], v[12:15]
	v_mfma_f32_16x16x32_bf16 v[8:11], v[168:171], v[172:175], v[8:11]
	v_mfma_f32_16x16x32_bf16 v[4:7], v[168:171], v[176:179], v[4:7]
	v_mfma_f32_16x16x32_bf16 v[0:3], v[168:171], v[180:183], v[0:3]
	s_setprio 0
	s_waitcnt vmcnt(0) lgkmcnt(0)
	s_barrier
	ds_read_b128 v[130:133], v128 offset:24576
	ds_read_b128 v[138:141], v128 offset:25600
	ds_read_b128 v[144:147], v128 offset:26624
	ds_read_b128 v[148:151], v128 offset:27648
	ds_read_b128 v[152:155], v128 offset:28672
	ds_read_b128 v[156:159], v128 offset:29696
	ds_read_b128 v[160:163], v128 offset:30720
	ds_read_b128 v[164:167], v128 offset:31744
	ds_read_b128 v[168:171], v137 offset:40960
	ds_read_b128 v[172:175], v137 offset:41984
	ds_read_b128 v[176:179], v137 offset:43008
	ds_read_b128 v[180:183], v137 offset:44032
	s_setprio 1
	s_waitcnt lgkmcnt(0)
	v_mfma_f32_16x16x32_bf16 v[124:127], v[130:133], v[168:171], v[124:127]
	v_mfma_f32_16x16x32_bf16 v[120:123], v[130:133], v[172:175], v[120:123]
	v_mfma_f32_16x16x32_bf16 v[116:119], v[130:133], v[176:179], v[116:119]
	v_mfma_f32_16x16x32_bf16 v[112:115], v[130:133], v[180:183], v[112:115]
	v_mfma_f32_16x16x32_bf16 v[108:111], v[138:141], v[168:171], v[108:111]
	v_mfma_f32_16x16x32_bf16 v[104:107], v[138:141], v[172:175], v[104:107]
	v_mfma_f32_16x16x32_bf16 v[100:103], v[138:141], v[176:179], v[100:103]
	v_mfma_f32_16x16x32_bf16 v[96:99], v[138:141], v[180:183], v[96:99]
	v_mfma_f32_16x16x32_bf16 v[92:95], v[144:147], v[168:171], v[92:95]
	v_mfma_f32_16x16x32_bf16 v[88:91], v[144:147], v[172:175], v[88:91]
	v_mfma_f32_16x16x32_bf16 v[84:87], v[144:147], v[176:179], v[84:87]
	v_mfma_f32_16x16x32_bf16 v[130:133], v[144:147], v[180:183], v[80:83]
	v_mfma_f32_16x16x32_bf16 v[138:141], v[148:151], v[168:171], v[76:79]
	v_mfma_f32_16x16x32_bf16 v[72:75], v[148:151], v[172:175], v[72:75]
	v_mfma_f32_16x16x32_bf16 v[68:71], v[148:151], v[176:179], v[68:71]
	v_mfma_f32_16x16x32_bf16 v[64:67], v[148:151], v[180:183], v[64:67]
	v_mfma_f32_16x16x32_bf16 v[60:63], v[152:155], v[168:171], v[60:63]
	v_mfma_f32_16x16x32_bf16 v[56:59], v[152:155], v[172:175], v[56:59]
	v_mfma_f32_16x16x32_bf16 v[52:55], v[152:155], v[176:179], v[52:55]
	v_mfma_f32_16x16x32_bf16 v[48:51], v[152:155], v[180:183], v[48:51]
	v_mfma_f32_16x16x32_bf16 v[44:47], v[156:159], v[168:171], v[44:47]
	v_mfma_f32_16x16x32_bf16 v[40:43], v[156:159], v[172:175], v[40:43]
	v_mfma_f32_16x16x32_bf16 v[36:39], v[156:159], v[176:179], v[36:39]
	v_mfma_f32_16x16x32_bf16 v[32:35], v[156:159], v[180:183], v[32:35]
	v_mfma_f32_16x16x32_bf16 v[28:31], v[160:163], v[168:171], v[28:31]
	v_mfma_f32_16x16x32_bf16 v[24:27], v[160:163], v[172:175], v[24:27]
	v_mfma_f32_16x16x32_bf16 v[20:23], v[160:163], v[176:179], v[20:23]
	v_mfma_f32_16x16x32_bf16 v[16:19], v[160:163], v[180:183], v[16:19]
	v_mfma_f32_16x16x32_bf16 v[12:15], v[164:167], v[168:171], v[12:15]
	v_mfma_f32_16x16x32_bf16 v[8:11], v[164:167], v[172:175], v[8:11]
	v_mfma_f32_16x16x32_bf16 v[4:7], v[164:167], v[176:179], v[4:7]
	v_mfma_f32_16x16x32_bf16 v[0:3], v[164:167], v[180:183], v[0:3]
	s_setprio 0
	v_and_b32_e32 v76, 0xffffff80, v134
	v_add_u32_e32 v76, s41, v76
	v_lshlrev_b32_e32 v77, 6, v136
	s_add_i32 s0, s4, 0xfffffc00
	v_ashrrev_i32_e32 v76, 6, v76
	v_or3_b32 v136, v77, s0, v135
	v_ashrrev_i32_e32 v77, 31, v76
	v_lshlrev_b64 v[78:79], 17, v[76:77]
	v_readlane_b32 s0, v254, 60
	v_lshrrev_b32_e32 v77, 1, v134
	v_and_b32_sdwa v81, v127, v142 dst_sel:DWORD dst_unused:UNUSED_PAD src0_sel:WORD_1 src1_sel:DWORD
	v_and_b32_sdwa v82, v125, v142 dst_sel:DWORD dst_unused:UNUSED_PAD src0_sel:WORD_1 src1_sel:DWORD
	v_readlane_b32 s1, v254, 61
	v_and_b32_e32 v128, 24, v77
	v_and_b32_sdwa v77, v126, v142 dst_sel:DWORD dst_unused:UNUSED_PAD src0_sel:WORD_1 src1_sel:DWORD
	v_and_b32_sdwa v80, v124, v142 dst_sel:DWORD dst_unused:UNUSED_PAD src0_sel:WORD_1 src1_sel:DWORD
	v_add3_u32 v81, v127, v81, s46
	v_add3_u32 v82, v125, v82, s46
	v_lshl_add_u64 v[78:79], s[0:1], 0, v[78:79]
	v_mov_b32_e32 v137, v129
	v_add3_u32 v80, v124, v80, s46
	v_add3_u32 v77, v126, v77, s46
	v_and_b32_e32 v81, 0xffff0000, v81
	v_and_b32_e32 v82, 0xffff0000, v82
	v_and_b32_sdwa v83, v123, v142 dst_sel:DWORD dst_unused:UNUSED_PAD src0_sel:WORD_1 src1_sel:DWORD
	v_lshl_add_u64 v[134:135], v[78:79], 0, v[128:129]
	v_lshlrev_b64 v[78:79], 7, v[136:137]
	v_or_b32_sdwa v81, v81, v77 dst_sel:DWORD dst_unused:UNUSED_PAD src0_sel:DWORD src1_sel:WORD_1
	v_or_b32_sdwa v80, v82, v80 dst_sel:DWORD dst_unused:UNUSED_PAD src0_sel:DWORD src1_sel:WORD_1
	v_and_b32_sdwa v77, v122, v142 dst_sel:DWORD dst_unused:UNUSED_PAD src0_sel:WORD_1 src1_sel:DWORD
	v_and_b32_sdwa v82, v120, v142 dst_sel:DWORD dst_unused:UNUSED_PAD src0_sel:WORD_1 src1_sel:DWORD
	v_add3_u32 v83, v123, v83, s46
	v_lshl_add_u64 v[144:145], v[134:135], 0, v[78:79]
	v_add3_u32 v82, v120, v82, s46
	v_add3_u32 v77, v122, v77, s46
	v_and_b32_sdwa v120, v121, v142 dst_sel:DWORD dst_unused:UNUSED_PAD src0_sel:WORD_1 src1_sel:DWORD
	v_and_b32_e32 v83, 0xffff0000, v83
	global_store_dwordx2 v[144:145], v[80:81], off
	v_or_b32_e32 v80, 16, v136
	v_mov_b32_e32 v81, v129
	v_add3_u32 v120, v121, v120, s46
	v_or_b32_sdwa v83, v83, v77 dst_sel:DWORD dst_unused:UNUSED_PAD src0_sel:DWORD src1_sel:WORD_1
	v_and_b32_sdwa v77, v118, v142 dst_sel:DWORD dst_unused:UNUSED_PAD src0_sel:WORD_1 src1_sel:DWORD
	v_lshlrev_b64 v[80:81], 7, v[80:81]
	v_and_b32_e32 v120, 0xffff0000, v120
	v_and_b32_sdwa v122, v116, v142 dst_sel:DWORD dst_unused:UNUSED_PAD src0_sel:WORD_1 src1_sel:DWORD
	v_add3_u32 v77, v118, v77, s46
	v_and_b32_sdwa v118, v119, v142 dst_sel:DWORD dst_unused:UNUSED_PAD src0_sel:WORD_1 src1_sel:DWORD
	v_lshl_add_u64 v[124:125], v[134:135], 0, v[80:81]
	v_or_b32_sdwa v82, v120, v82 dst_sel:DWORD dst_unused:UNUSED_PAD src0_sel:DWORD src1_sel:WORD_1
	v_add3_u32 v116, v116, v122, s46
	v_and_b32_sdwa v122, v117, v142 dst_sel:DWORD dst_unused:UNUSED_PAD src0_sel:WORD_1 src1_sel:DWORD
	v_add3_u32 v118, v119, v118, s46
	global_store_dwordx2 v[124:125], v[82:83], off
	v_or_b32_e32 v82, 32, v136
	v_mov_b32_e32 v83, v129
	v_add3_u32 v117, v117, v122, s46
	v_and_b32_e32 v118, 0xffff0000, v118
	v_lshlrev_b64 v[82:83], 7, v[82:83]
	v_and_b32_e32 v119, 0xffff0000, v117
	v_or_b32_sdwa v117, v118, v77 dst_sel:DWORD dst_unused:UNUSED_PAD src0_sel:DWORD src1_sel:WORD_1
	v_and_b32_sdwa v77, v114, v142 dst_sel:DWORD dst_unused:UNUSED_PAD src0_sel:WORD_1 src1_sel:DWORD
	v_and_b32_sdwa v122, v112, v142 dst_sel:DWORD dst_unused:UNUSED_PAD src0_sel:WORD_1 src1_sel:DWORD
	v_lshl_add_u64 v[120:121], v[134:135], 0, v[82:83]
	v_or_b32_sdwa v116, v119, v116 dst_sel:DWORD dst_unused:UNUSED_PAD src0_sel:DWORD src1_sel:WORD_1
	v_add3_u32 v112, v112, v122, s46
	v_add3_u32 v77, v114, v77, s46
	v_and_b32_sdwa v114, v115, v142 dst_sel:DWORD dst_unused:UNUSED_PAD src0_sel:WORD_1 src1_sel:DWORD
	v_and_b32_sdwa v122, v113, v142 dst_sel:DWORD dst_unused:UNUSED_PAD src0_sel:WORD_1 src1_sel:DWORD
	global_store_dwordx2 v[120:121], v[116:117], off
	v_or_b32_e32 v116, 48, v136
	v_mov_b32_e32 v117, v129
	v_add3_u32 v114, v115, v114, s46
	v_add3_u32 v113, v113, v122, s46
	v_lshlrev_b64 v[116:117], 7, v[116:117]
	v_and_b32_e32 v114, 0xffff0000, v114
	v_and_b32_e32 v115, 0xffff0000, v113
	v_lshl_add_u64 v[118:119], v[134:135], 0, v[116:117]
	v_or_b32_sdwa v113, v114, v77 dst_sel:DWORD dst_unused:UNUSED_PAD src0_sel:DWORD src1_sel:WORD_1
	v_or_b32_sdwa v112, v115, v112 dst_sel:DWORD dst_unused:UNUSED_PAD src0_sel:DWORD src1_sel:WORD_1
	global_store_dwordx2 v[118:119], v[112:113], off
	v_and_b32_sdwa v77, v110, v142 dst_sel:DWORD dst_unused:UNUSED_PAD src0_sel:WORD_1 src1_sel:DWORD
	v_and_b32_sdwa v112, v108, v142 dst_sel:DWORD dst_unused:UNUSED_PAD src0_sel:WORD_1 src1_sel:DWORD
	v_add3_u32 v108, v108, v112, s46
	v_add3_u32 v77, v110, v77, s46
	v_and_b32_sdwa v110, v111, v142 dst_sel:DWORD dst_unused:UNUSED_PAD src0_sel:WORD_1 src1_sel:DWORD
	v_and_b32_sdwa v112, v109, v142 dst_sel:DWORD dst_unused:UNUSED_PAD src0_sel:WORD_1 src1_sel:DWORD
	v_add3_u32 v110, v111, v110, s46
	v_add3_u32 v109, v109, v112, s46
	v_and_b32_e32 v110, 0xffff0000, v110
	v_and_b32_e32 v111, 0xffff0000, v109
	v_or_b32_sdwa v109, v110, v77 dst_sel:DWORD dst_unused:UNUSED_PAD src0_sel:DWORD src1_sel:WORD_1
	v_or_b32_sdwa v108, v111, v108 dst_sel:DWORD dst_unused:UNUSED_PAD src0_sel:DWORD src1_sel:WORD_1
	global_store_dwordx2 v[144:145], v[108:109], off offset:32
	v_and_b32_sdwa v77, v106, v142 dst_sel:DWORD dst_unused:UNUSED_PAD src0_sel:WORD_1 src1_sel:DWORD
	v_and_b32_sdwa v108, v104, v142 dst_sel:DWORD dst_unused:UNUSED_PAD src0_sel:WORD_1 src1_sel:DWORD
	v_add3_u32 v104, v104, v108, s46
	v_add3_u32 v77, v106, v77, s46
	v_and_b32_sdwa v106, v107, v142 dst_sel:DWORD dst_unused:UNUSED_PAD src0_sel:WORD_1 src1_sel:DWORD
	v_and_b32_sdwa v108, v105, v142 dst_sel:DWORD dst_unused:UNUSED_PAD src0_sel:WORD_1 src1_sel:DWORD
	v_add3_u32 v106, v107, v106, s46
	v_add3_u32 v105, v105, v108, s46
	v_and_b32_e32 v106, 0xffff0000, v106
	v_and_b32_e32 v107, 0xffff0000, v105
	v_or_b32_sdwa v105, v106, v77 dst_sel:DWORD dst_unused:UNUSED_PAD src0_sel:DWORD src1_sel:WORD_1
	v_or_b32_sdwa v104, v107, v104 dst_sel:DWORD dst_unused:UNUSED_PAD src0_sel:DWORD src1_sel:WORD_1
	global_store_dwordx2 v[124:125], v[104:105], off offset:32
	v_and_b32_sdwa v77, v102, v142 dst_sel:DWORD dst_unused:UNUSED_PAD src0_sel:WORD_1 src1_sel:DWORD
	v_and_b32_sdwa v104, v100, v142 dst_sel:DWORD dst_unused:UNUSED_PAD src0_sel:WORD_1 src1_sel:DWORD
	v_add3_u32 v100, v100, v104, s46
	v_add3_u32 v77, v102, v77, s46
	v_and_b32_sdwa v102, v103, v142 dst_sel:DWORD dst_unused:UNUSED_PAD src0_sel:WORD_1 src1_sel:DWORD
	v_and_b32_sdwa v104, v101, v142 dst_sel:DWORD dst_unused:UNUSED_PAD src0_sel:WORD_1 src1_sel:DWORD
	v_add3_u32 v102, v103, v102, s46
	v_add3_u32 v101, v101, v104, s46
	v_and_b32_e32 v102, 0xffff0000, v102
	v_and_b32_e32 v103, 0xffff0000, v101
	v_or_b32_sdwa v101, v102, v77 dst_sel:DWORD dst_unused:UNUSED_PAD src0_sel:DWORD src1_sel:WORD_1
	v_or_b32_sdwa v100, v103, v100 dst_sel:DWORD dst_unused:UNUSED_PAD src0_sel:DWORD src1_sel:WORD_1
	global_store_dwordx2 v[120:121], v[100:101], off offset:32
	v_and_b32_sdwa v77, v98, v142 dst_sel:DWORD dst_unused:UNUSED_PAD src0_sel:WORD_1 src1_sel:DWORD
	v_and_b32_sdwa v100, v96, v142 dst_sel:DWORD dst_unused:UNUSED_PAD src0_sel:WORD_1 src1_sel:DWORD
	v_add3_u32 v96, v96, v100, s46
	v_add3_u32 v77, v98, v77, s46
	v_and_b32_sdwa v98, v99, v142 dst_sel:DWORD dst_unused:UNUSED_PAD src0_sel:WORD_1 src1_sel:DWORD
	v_and_b32_sdwa v100, v97, v142 dst_sel:DWORD dst_unused:UNUSED_PAD src0_sel:WORD_1 src1_sel:DWORD
	v_add3_u32 v98, v99, v98, s46
	v_add3_u32 v97, v97, v100, s46
	v_and_b32_e32 v98, 0xffff0000, v98
	v_and_b32_e32 v99, 0xffff0000, v97
	v_or_b32_sdwa v97, v98, v77 dst_sel:DWORD dst_unused:UNUSED_PAD src0_sel:DWORD src1_sel:WORD_1
	v_or_b32_sdwa v96, v99, v96 dst_sel:DWORD dst_unused:UNUSED_PAD src0_sel:DWORD src1_sel:WORD_1
	global_store_dwordx2 v[118:119], v[96:97], off offset:32
	v_and_b32_sdwa v77, v94, v142 dst_sel:DWORD dst_unused:UNUSED_PAD src0_sel:WORD_1 src1_sel:DWORD
	v_and_b32_sdwa v96, v92, v142 dst_sel:DWORD dst_unused:UNUSED_PAD src0_sel:WORD_1 src1_sel:DWORD
	v_add3_u32 v92, v92, v96, s46
	v_add3_u32 v77, v94, v77, s46
	v_and_b32_sdwa v94, v95, v142 dst_sel:DWORD dst_unused:UNUSED_PAD src0_sel:WORD_1 src1_sel:DWORD
	v_and_b32_sdwa v96, v93, v142 dst_sel:DWORD dst_unused:UNUSED_PAD src0_sel:WORD_1 src1_sel:DWORD
	v_add3_u32 v94, v95, v94, s46
	v_add3_u32 v93, v93, v96, s46
	v_and_b32_e32 v94, 0xffff0000, v94
	v_and_b32_e32 v95, 0xffff0000, v93
	v_or_b32_sdwa v93, v94, v77 dst_sel:DWORD dst_unused:UNUSED_PAD src0_sel:DWORD src1_sel:WORD_1
	v_or_b32_sdwa v92, v95, v92 dst_sel:DWORD dst_unused:UNUSED_PAD src0_sel:DWORD src1_sel:WORD_1
	global_store_dwordx2 v[144:145], v[92:93], off offset:64
	v_and_b32_sdwa v77, v90, v142 dst_sel:DWORD dst_unused:UNUSED_PAD src0_sel:WORD_1 src1_sel:DWORD
	v_and_b32_sdwa v92, v88, v142 dst_sel:DWORD dst_unused:UNUSED_PAD src0_sel:WORD_1 src1_sel:DWORD
	v_add3_u32 v88, v88, v92, s46
	v_add3_u32 v77, v90, v77, s46
	v_and_b32_sdwa v90, v91, v142 dst_sel:DWORD dst_unused:UNUSED_PAD src0_sel:WORD_1 src1_sel:DWORD
	v_and_b32_sdwa v92, v89, v142 dst_sel:DWORD dst_unused:UNUSED_PAD src0_sel:WORD_1 src1_sel:DWORD
	v_add3_u32 v90, v91, v90, s46
	v_add3_u32 v89, v89, v92, s46
	v_and_b32_e32 v90, 0xffff0000, v90
	v_and_b32_e32 v91, 0xffff0000, v89
	v_or_b32_sdwa v89, v90, v77 dst_sel:DWORD dst_unused:UNUSED_PAD src0_sel:DWORD src1_sel:WORD_1
	v_or_b32_sdwa v88, v91, v88 dst_sel:DWORD dst_unused:UNUSED_PAD src0_sel:DWORD src1_sel:WORD_1
	global_store_dwordx2 v[124:125], v[88:89], off offset:64
	v_and_b32_sdwa v77, v86, v142 dst_sel:DWORD dst_unused:UNUSED_PAD src0_sel:WORD_1 src1_sel:DWORD
	v_and_b32_sdwa v88, v84, v142 dst_sel:DWORD dst_unused:UNUSED_PAD src0_sel:WORD_1 src1_sel:DWORD
	v_add3_u32 v84, v84, v88, s46
	v_add3_u32 v77, v86, v77, s46
	v_and_b32_sdwa v86, v87, v142 dst_sel:DWORD dst_unused:UNUSED_PAD src0_sel:WORD_1 src1_sel:DWORD
	v_and_b32_sdwa v88, v85, v142 dst_sel:DWORD dst_unused:UNUSED_PAD src0_sel:WORD_1 src1_sel:DWORD
	v_add3_u32 v86, v87, v86, s46
	v_add3_u32 v85, v85, v88, s46
	v_and_b32_e32 v86, 0xffff0000, v86
	v_and_b32_e32 v87, 0xffff0000, v85
	v_or_b32_sdwa v85, v86, v77 dst_sel:DWORD dst_unused:UNUSED_PAD src0_sel:DWORD src1_sel:WORD_1
	v_or_b32_sdwa v84, v87, v84 dst_sel:DWORD dst_unused:UNUSED_PAD src0_sel:DWORD src1_sel:WORD_1
	global_store_dwordx2 v[120:121], v[84:85], off offset:64
	v_and_b32_sdwa v85, v133, v142 dst_sel:DWORD dst_unused:UNUSED_PAD src0_sel:WORD_1 src1_sel:DWORD
	v_and_b32_sdwa v86, v131, v142 dst_sel:DWORD dst_unused:UNUSED_PAD src0_sel:WORD_1 src1_sel:DWORD
	v_and_b32_sdwa v77, v132, v142 dst_sel:DWORD dst_unused:UNUSED_PAD src0_sel:WORD_1 src1_sel:DWORD
	v_and_b32_sdwa v84, v130, v142 dst_sel:DWORD dst_unused:UNUSED_PAD src0_sel:WORD_1 src1_sel:DWORD
	v_add3_u32 v85, v133, v85, s46
	v_add3_u32 v86, v131, v86, s46
	v_add3_u32 v84, v130, v84, s46
	v_add3_u32 v77, v132, v77, s46
	v_and_b32_e32 v85, 0xffff0000, v85
	v_and_b32_e32 v86, 0xffff0000, v86
	v_or_b32_sdwa v85, v85, v77 dst_sel:DWORD dst_unused:UNUSED_PAD src0_sel:DWORD src1_sel:WORD_1
	v_or_b32_sdwa v84, v86, v84 dst_sel:DWORD dst_unused:UNUSED_PAD src0_sel:DWORD src1_sel:WORD_1
	global_store_dwordx2 v[118:119], v[84:85], off offset:64
	v_and_b32_sdwa v85, v141, v142 dst_sel:DWORD dst_unused:UNUSED_PAD src0_sel:WORD_1 src1_sel:DWORD
	v_and_b32_sdwa v86, v139, v142 dst_sel:DWORD dst_unused:UNUSED_PAD src0_sel:WORD_1 src1_sel:DWORD
	v_and_b32_sdwa v77, v140, v142 dst_sel:DWORD dst_unused:UNUSED_PAD src0_sel:WORD_1 src1_sel:DWORD
	v_and_b32_sdwa v84, v138, v142 dst_sel:DWORD dst_unused:UNUSED_PAD src0_sel:WORD_1 src1_sel:DWORD
	v_add3_u32 v85, v141, v85, s46
	v_add3_u32 v86, v139, v86, s46
	v_add3_u32 v84, v138, v84, s46
	v_add3_u32 v77, v140, v77, s46
	v_and_b32_e32 v85, 0xffff0000, v85
	v_and_b32_e32 v86, 0xffff0000, v86
	v_or_b32_sdwa v85, v85, v77 dst_sel:DWORD dst_unused:UNUSED_PAD src0_sel:DWORD src1_sel:WORD_1
	v_or_b32_sdwa v84, v86, v84 dst_sel:DWORD dst_unused:UNUSED_PAD src0_sel:DWORD src1_sel:WORD_1
	global_store_dwordx2 v[144:145], v[84:85], off offset:96
	v_and_b32_sdwa v77, v74, v142 dst_sel:DWORD dst_unused:UNUSED_PAD src0_sel:WORD_1 src1_sel:DWORD
	v_and_b32_sdwa v84, v72, v142 dst_sel:DWORD dst_unused:UNUSED_PAD src0_sel:WORD_1 src1_sel:DWORD
	v_add3_u32 v72, v72, v84, s46
	v_add3_u32 v74, v74, v77, s46
	v_and_b32_sdwa v77, v75, v142 dst_sel:DWORD dst_unused:UNUSED_PAD src0_sel:WORD_1 src1_sel:DWORD
	v_and_b32_sdwa v84, v73, v142 dst_sel:DWORD dst_unused:UNUSED_PAD src0_sel:WORD_1 src1_sel:DWORD
	v_add3_u32 v75, v75, v77, s46
	v_add3_u32 v73, v73, v84, s46
	v_and_b32_e32 v75, 0xffff0000, v75
	v_and_b32_e32 v77, 0xffff0000, v73
	v_or_b32_sdwa v73, v75, v74 dst_sel:DWORD dst_unused:UNUSED_PAD src0_sel:DWORD src1_sel:WORD_1
	v_or_b32_sdwa v72, v77, v72 dst_sel:DWORD dst_unused:UNUSED_PAD src0_sel:DWORD src1_sel:WORD_1
	global_store_dwordx2 v[124:125], v[72:73], off offset:96
	v_and_b32_sdwa v72, v70, v142 dst_sel:DWORD dst_unused:UNUSED_PAD src0_sel:WORD_1 src1_sel:DWORD
	v_and_b32_sdwa v73, v68, v142 dst_sel:DWORD dst_unused:UNUSED_PAD src0_sel:WORD_1 src1_sel:DWORD
	v_add3_u32 v68, v68, v73, s46
	v_add3_u32 v70, v70, v72, s46
	v_and_b32_sdwa v72, v71, v142 dst_sel:DWORD dst_unused:UNUSED_PAD src0_sel:WORD_1 src1_sel:DWORD
	v_and_b32_sdwa v73, v69, v142 dst_sel:DWORD dst_unused:UNUSED_PAD src0_sel:WORD_1 src1_sel:DWORD
	v_add3_u32 v71, v71, v72, s46
	v_add3_u32 v69, v69, v73, s46
	v_and_b32_e32 v71, 0xffff0000, v71
	v_and_b32_e32 v72, 0xffff0000, v69
	v_or_b32_sdwa v69, v71, v70 dst_sel:DWORD dst_unused:UNUSED_PAD src0_sel:DWORD src1_sel:WORD_1
	v_or_b32_sdwa v68, v72, v68 dst_sel:DWORD dst_unused:UNUSED_PAD src0_sel:DWORD src1_sel:WORD_1
	global_store_dwordx2 v[120:121], v[68:69], off offset:96
	v_and_b32_sdwa v69, v64, v142 dst_sel:DWORD dst_unused:UNUSED_PAD src0_sel:WORD_1 src1_sel:DWORD
	v_and_b32_sdwa v68, v66, v142 dst_sel:DWORD dst_unused:UNUSED_PAD src0_sel:WORD_1 src1_sel:DWORD
	v_add3_u32 v64, v64, v69, s46
	v_and_b32_sdwa v69, v65, v142 dst_sel:DWORD dst_unused:UNUSED_PAD src0_sel:WORD_1 src1_sel:DWORD
	v_add3_u32 v66, v66, v68, s46
	v_and_b32_sdwa v68, v67, v142 dst_sel:DWORD dst_unused:UNUSED_PAD src0_sel:WORD_1 src1_sel:DWORD
	v_add3_u32 v65, v65, v69, s46
	v_add3_u32 v67, v67, v68, s46
	v_and_b32_e32 v68, 0xffff0000, v65
	v_or_b32_sdwa v64, v68, v64 dst_sel:DWORD dst_unused:UNUSED_PAD src0_sel:DWORD src1_sel:WORD_1
	v_and_b32_sdwa v68, v62, v142 dst_sel:DWORD dst_unused:UNUSED_PAD src0_sel:WORD_1 src1_sel:DWORD
	v_and_b32_sdwa v69, v60, v142 dst_sel:DWORD dst_unused:UNUSED_PAD src0_sel:WORD_1 src1_sel:DWORD
	v_add3_u32 v62, v62, v68, s46
	v_and_b32_sdwa v68, v63, v142 dst_sel:DWORD dst_unused:UNUSED_PAD src0_sel:WORD_1 src1_sel:DWORD
	v_add3_u32 v60, v60, v69, s46
	v_and_b32_sdwa v69, v61, v142 dst_sel:DWORD dst_unused:UNUSED_PAD src0_sel:WORD_1 src1_sel:DWORD
	v_add3_u32 v63, v63, v68, s46
	v_add3_u32 v61, v61, v69, s46
	v_and_b32_e32 v63, 0xffff0000, v63
	v_and_b32_e32 v68, 0xffff0000, v61
	v_or_b32_sdwa v61, v63, v62 dst_sel:DWORD dst_unused:UNUSED_PAD src0_sel:DWORD src1_sel:WORD_1
	v_and_b32_sdwa v62, v58, v142 dst_sel:DWORD dst_unused:UNUSED_PAD src0_sel:WORD_1 src1_sel:DWORD
	v_and_b32_sdwa v63, v56, v142 dst_sel:DWORD dst_unused:UNUSED_PAD src0_sel:WORD_1 src1_sel:DWORD
	v_add3_u32 v58, v58, v62, s46
	v_and_b32_sdwa v62, v59, v142 dst_sel:DWORD dst_unused:UNUSED_PAD src0_sel:WORD_1 src1_sel:DWORD
	v_and_b32_e32 v67, 0xffff0000, v67
	v_add3_u32 v56, v56, v63, s46
	v_and_b32_sdwa v63, v57, v142 dst_sel:DWORD dst_unused:UNUSED_PAD src0_sel:WORD_1 src1_sel:DWORD
	v_add3_u32 v59, v59, v62, s46
	v_or_b32_sdwa v65, v67, v66 dst_sel:DWORD dst_unused:UNUSED_PAD src0_sel:DWORD src1_sel:WORD_1
	v_add3_u32 v57, v57, v63, s46
	v_and_b32_e32 v59, 0xffff0000, v59
	global_store_dwordx2 v[118:119], v[64:65], off offset:96
	v_or_b32_e32 v64, 1, v76
	v_and_b32_e32 v62, 0xffff0000, v57
	v_or_b32_sdwa v57, v59, v58 dst_sel:DWORD dst_unused:UNUSED_PAD src0_sel:DWORD src1_sel:WORD_1
	v_and_b32_sdwa v58, v54, v142 dst_sel:DWORD dst_unused:UNUSED_PAD src0_sel:WORD_1 src1_sel:DWORD
	v_ashrrev_i32_e32 v65, 31, v64
	v_and_b32_sdwa v59, v52, v142 dst_sel:DWORD dst_unused:UNUSED_PAD src0_sel:WORD_1 src1_sel:DWORD
	v_add3_u32 v54, v54, v58, s46
	v_and_b32_sdwa v58, v55, v142 dst_sel:DWORD dst_unused:UNUSED_PAD src0_sel:WORD_1 src1_sel:DWORD
	v_lshlrev_b64 v[64:65], 17, v[64:65]
	v_add3_u32 v52, v52, v59, s46
	v_and_b32_sdwa v59, v53, v142 dst_sel:DWORD dst_unused:UNUSED_PAD src0_sel:WORD_1 src1_sel:DWORD
	v_add3_u32 v55, v55, v58, s46
	v_lshl_add_u64 v[64:65], s[0:1], 0, v[64:65]
	v_add3_u32 v53, v53, v59, s46
	v_and_b32_e32 v55, 0xffff0000, v55
	v_lshl_add_u64 v[64:65], v[64:65], 0, v[128:129]
	v_and_b32_e32 v58, 0xffff0000, v53
	v_or_b32_sdwa v53, v55, v54 dst_sel:DWORD dst_unused:UNUSED_PAD src0_sel:DWORD src1_sel:WORD_1
	v_and_b32_sdwa v54, v50, v142 dst_sel:DWORD dst_unused:UNUSED_PAD src0_sel:WORD_1 src1_sel:DWORD
	v_and_b32_sdwa v55, v48, v142 dst_sel:DWORD dst_unused:UNUSED_PAD src0_sel:WORD_1 src1_sel:DWORD
	v_lshl_add_u64 v[66:67], v[64:65], 0, v[78:79]
	v_or_b32_sdwa v60, v68, v60 dst_sel:DWORD dst_unused:UNUSED_PAD src0_sel:DWORD src1_sel:WORD_1
	v_add3_u32 v48, v48, v55, s46
	v_add3_u32 v50, v50, v54, s46
	v_and_b32_sdwa v54, v51, v142 dst_sel:DWORD dst_unused:UNUSED_PAD src0_sel:WORD_1 src1_sel:DWORD
	v_and_b32_sdwa v55, v49, v142 dst_sel:DWORD dst_unused:UNUSED_PAD src0_sel:WORD_1 src1_sel:DWORD
	global_store_dwordx2 v[66:67], v[60:61], off
	v_lshl_add_u64 v[60:61], v[64:65], 0, v[80:81]
	v_or_b32_sdwa v56, v62, v56 dst_sel:DWORD dst_unused:UNUSED_PAD src0_sel:DWORD src1_sel:WORD_1
	v_add3_u32 v51, v51, v54, s46
	v_add3_u32 v49, v49, v55, s46
	global_store_dwordx2 v[60:61], v[56:57], off
	v_lshl_add_u64 v[56:57], v[64:65], 0, v[82:83]
	v_or_b32_sdwa v52, v58, v52 dst_sel:DWORD dst_unused:UNUSED_PAD src0_sel:DWORD src1_sel:WORD_1
	v_and_b32_e32 v51, 0xffff0000, v51
	v_and_b32_e32 v54, 0xffff0000, v49
	global_store_dwordx2 v[56:57], v[52:53], off
	v_lshl_add_u64 v[52:53], v[64:65], 0, v[116:117]
	v_or_b32_sdwa v49, v51, v50 dst_sel:DWORD dst_unused:UNUSED_PAD src0_sel:DWORD src1_sel:WORD_1
	v_or_b32_sdwa v48, v54, v48 dst_sel:DWORD dst_unused:UNUSED_PAD src0_sel:DWORD src1_sel:WORD_1
	global_store_dwordx2 v[52:53], v[48:49], off
	v_and_b32_sdwa v48, v46, v142 dst_sel:DWORD dst_unused:UNUSED_PAD src0_sel:WORD_1 src1_sel:DWORD
	v_and_b32_sdwa v49, v44, v142 dst_sel:DWORD dst_unused:UNUSED_PAD src0_sel:WORD_1 src1_sel:DWORD
	v_add3_u32 v44, v44, v49, s46
	v_add3_u32 v46, v46, v48, s46
	v_and_b32_sdwa v48, v47, v142 dst_sel:DWORD dst_unused:UNUSED_PAD src0_sel:WORD_1 src1_sel:DWORD
	v_and_b32_sdwa v49, v45, v142 dst_sel:DWORD dst_unused:UNUSED_PAD src0_sel:WORD_1 src1_sel:DWORD
	v_add3_u32 v47, v47, v48, s46
	v_add3_u32 v45, v45, v49, s46
	v_and_b32_e32 v47, 0xffff0000, v47
	v_and_b32_e32 v48, 0xffff0000, v45
	v_or_b32_sdwa v45, v47, v46 dst_sel:DWORD dst_unused:UNUSED_PAD src0_sel:DWORD src1_sel:WORD_1
	v_or_b32_sdwa v44, v48, v44 dst_sel:DWORD dst_unused:UNUSED_PAD src0_sel:DWORD src1_sel:WORD_1
	global_store_dwordx2 v[66:67], v[44:45], off offset:32
	v_and_b32_sdwa v44, v42, v142 dst_sel:DWORD dst_unused:UNUSED_PAD src0_sel:WORD_1 src1_sel:DWORD
	v_and_b32_sdwa v45, v40, v142 dst_sel:DWORD dst_unused:UNUSED_PAD src0_sel:WORD_1 src1_sel:DWORD
	v_add3_u32 v40, v40, v45, s46
	v_add3_u32 v42, v42, v44, s46
	v_and_b32_sdwa v44, v43, v142 dst_sel:DWORD dst_unused:UNUSED_PAD src0_sel:WORD_1 src1_sel:DWORD
	v_and_b32_sdwa v45, v41, v142 dst_sel:DWORD dst_unused:UNUSED_PAD src0_sel:WORD_1 src1_sel:DWORD
	v_add3_u32 v43, v43, v44, s46
	v_add3_u32 v41, v41, v45, s46
	v_and_b32_e32 v43, 0xffff0000, v43
	v_and_b32_e32 v44, 0xffff0000, v41
	v_or_b32_sdwa v41, v43, v42 dst_sel:DWORD dst_unused:UNUSED_PAD src0_sel:DWORD src1_sel:WORD_1
	v_or_b32_sdwa v40, v44, v40 dst_sel:DWORD dst_unused:UNUSED_PAD src0_sel:DWORD src1_sel:WORD_1
	global_store_dwordx2 v[60:61], v[40:41], off offset:32
	v_and_b32_sdwa v40, v38, v142 dst_sel:DWORD dst_unused:UNUSED_PAD src0_sel:WORD_1 src1_sel:DWORD
	v_and_b32_sdwa v41, v36, v142 dst_sel:DWORD dst_unused:UNUSED_PAD src0_sel:WORD_1 src1_sel:DWORD
	v_add3_u32 v36, v36, v41, s46
	v_add3_u32 v38, v38, v40, s46
	v_and_b32_sdwa v40, v39, v142 dst_sel:DWORD dst_unused:UNUSED_PAD src0_sel:WORD_1 src1_sel:DWORD
	v_and_b32_sdwa v41, v37, v142 dst_sel:DWORD dst_unused:UNUSED_PAD src0_sel:WORD_1 src1_sel:DWORD
	v_add3_u32 v39, v39, v40, s46
	v_add3_u32 v37, v37, v41, s46
	v_and_b32_e32 v39, 0xffff0000, v39
	v_and_b32_e32 v40, 0xffff0000, v37
	v_or_b32_sdwa v37, v39, v38 dst_sel:DWORD dst_unused:UNUSED_PAD src0_sel:DWORD src1_sel:WORD_1
	v_or_b32_sdwa v36, v40, v36 dst_sel:DWORD dst_unused:UNUSED_PAD src0_sel:DWORD src1_sel:WORD_1
	global_store_dwordx2 v[56:57], v[36:37], off offset:32
	v_and_b32_sdwa v36, v34, v142 dst_sel:DWORD dst_unused:UNUSED_PAD src0_sel:WORD_1 src1_sel:DWORD
	v_and_b32_sdwa v37, v32, v142 dst_sel:DWORD dst_unused:UNUSED_PAD src0_sel:WORD_1 src1_sel:DWORD
	v_add3_u32 v32, v32, v37, s46
	v_add3_u32 v34, v34, v36, s46
	v_and_b32_sdwa v36, v35, v142 dst_sel:DWORD dst_unused:UNUSED_PAD src0_sel:WORD_1 src1_sel:DWORD
	v_and_b32_sdwa v37, v33, v142 dst_sel:DWORD dst_unused:UNUSED_PAD src0_sel:WORD_1 src1_sel:DWORD
	v_add3_u32 v35, v35, v36, s46
	v_add3_u32 v33, v33, v37, s46
	v_and_b32_e32 v35, 0xffff0000, v35
	v_and_b32_e32 v36, 0xffff0000, v33
	v_or_b32_sdwa v33, v35, v34 dst_sel:DWORD dst_unused:UNUSED_PAD src0_sel:DWORD src1_sel:WORD_1
	v_or_b32_sdwa v32, v36, v32 dst_sel:DWORD dst_unused:UNUSED_PAD src0_sel:DWORD src1_sel:WORD_1
	global_store_dwordx2 v[52:53], v[32:33], off offset:32
	v_and_b32_sdwa v32, v30, v142 dst_sel:DWORD dst_unused:UNUSED_PAD src0_sel:WORD_1 src1_sel:DWORD
	v_and_b32_sdwa v33, v28, v142 dst_sel:DWORD dst_unused:UNUSED_PAD src0_sel:WORD_1 src1_sel:DWORD
	v_add3_u32 v28, v28, v33, s46
	v_add3_u32 v30, v30, v32, s46
	v_and_b32_sdwa v32, v31, v142 dst_sel:DWORD dst_unused:UNUSED_PAD src0_sel:WORD_1 src1_sel:DWORD
	v_and_b32_sdwa v33, v29, v142 dst_sel:DWORD dst_unused:UNUSED_PAD src0_sel:WORD_1 src1_sel:DWORD
	v_add3_u32 v31, v31, v32, s46
	v_add3_u32 v29, v29, v33, s46
	v_and_b32_e32 v31, 0xffff0000, v31
	v_and_b32_e32 v32, 0xffff0000, v29
	v_or_b32_sdwa v29, v31, v30 dst_sel:DWORD dst_unused:UNUSED_PAD src0_sel:DWORD src1_sel:WORD_1
	v_or_b32_sdwa v28, v32, v28 dst_sel:DWORD dst_unused:UNUSED_PAD src0_sel:DWORD src1_sel:WORD_1
	global_store_dwordx2 v[66:67], v[28:29], off offset:64
	v_and_b32_sdwa v28, v26, v142 dst_sel:DWORD dst_unused:UNUSED_PAD src0_sel:WORD_1 src1_sel:DWORD
	v_and_b32_sdwa v29, v24, v142 dst_sel:DWORD dst_unused:UNUSED_PAD src0_sel:WORD_1 src1_sel:DWORD
	v_add3_u32 v24, v24, v29, s46
	v_add3_u32 v26, v26, v28, s46
	v_and_b32_sdwa v28, v27, v142 dst_sel:DWORD dst_unused:UNUSED_PAD src0_sel:WORD_1 src1_sel:DWORD
	v_and_b32_sdwa v29, v25, v142 dst_sel:DWORD dst_unused:UNUSED_PAD src0_sel:WORD_1 src1_sel:DWORD
	v_add3_u32 v27, v27, v28, s46
	v_add3_u32 v25, v25, v29, s46
	v_and_b32_e32 v27, 0xffff0000, v27
	v_and_b32_e32 v28, 0xffff0000, v25
	v_or_b32_sdwa v25, v27, v26 dst_sel:DWORD dst_unused:UNUSED_PAD src0_sel:DWORD src1_sel:WORD_1
	v_or_b32_sdwa v24, v28, v24 dst_sel:DWORD dst_unused:UNUSED_PAD src0_sel:DWORD src1_sel:WORD_1
	global_store_dwordx2 v[60:61], v[24:25], off offset:64
	v_and_b32_sdwa v24, v22, v142 dst_sel:DWORD dst_unused:UNUSED_PAD src0_sel:WORD_1 src1_sel:DWORD
	v_and_b32_sdwa v25, v20, v142 dst_sel:DWORD dst_unused:UNUSED_PAD src0_sel:WORD_1 src1_sel:DWORD
	v_add3_u32 v20, v20, v25, s46
	v_add3_u32 v22, v22, v24, s46
	v_and_b32_sdwa v24, v23, v142 dst_sel:DWORD dst_unused:UNUSED_PAD src0_sel:WORD_1 src1_sel:DWORD
	v_and_b32_sdwa v25, v21, v142 dst_sel:DWORD dst_unused:UNUSED_PAD src0_sel:WORD_1 src1_sel:DWORD
	v_add3_u32 v23, v23, v24, s46
	v_add3_u32 v21, v21, v25, s46
	v_and_b32_e32 v23, 0xffff0000, v23
	v_and_b32_e32 v24, 0xffff0000, v21
	v_or_b32_sdwa v21, v23, v22 dst_sel:DWORD dst_unused:UNUSED_PAD src0_sel:DWORD src1_sel:WORD_1
	v_or_b32_sdwa v20, v24, v20 dst_sel:DWORD dst_unused:UNUSED_PAD src0_sel:DWORD src1_sel:WORD_1
	global_store_dwordx2 v[56:57], v[20:21], off offset:64
	v_and_b32_sdwa v20, v18, v142 dst_sel:DWORD dst_unused:UNUSED_PAD src0_sel:WORD_1 src1_sel:DWORD
	v_and_b32_sdwa v21, v16, v142 dst_sel:DWORD dst_unused:UNUSED_PAD src0_sel:WORD_1 src1_sel:DWORD
	v_add3_u32 v16, v16, v21, s46
	v_add3_u32 v18, v18, v20, s46
	v_and_b32_sdwa v20, v19, v142 dst_sel:DWORD dst_unused:UNUSED_PAD src0_sel:WORD_1 src1_sel:DWORD
	v_and_b32_sdwa v21, v17, v142 dst_sel:DWORD dst_unused:UNUSED_PAD src0_sel:WORD_1 src1_sel:DWORD
	v_add3_u32 v19, v19, v20, s46
	v_add3_u32 v17, v17, v21, s46
	v_and_b32_e32 v19, 0xffff0000, v19
	v_and_b32_e32 v20, 0xffff0000, v17
	v_or_b32_sdwa v17, v19, v18 dst_sel:DWORD dst_unused:UNUSED_PAD src0_sel:DWORD src1_sel:WORD_1
	v_or_b32_sdwa v16, v20, v16 dst_sel:DWORD dst_unused:UNUSED_PAD src0_sel:DWORD src1_sel:WORD_1
	global_store_dwordx2 v[52:53], v[16:17], off offset:64
	v_and_b32_sdwa v16, v14, v142 dst_sel:DWORD dst_unused:UNUSED_PAD src0_sel:WORD_1 src1_sel:DWORD
	v_and_b32_sdwa v17, v12, v142 dst_sel:DWORD dst_unused:UNUSED_PAD src0_sel:WORD_1 src1_sel:DWORD
	v_add3_u32 v12, v12, v17, s46
	v_add3_u32 v14, v14, v16, s46
	v_and_b32_sdwa v16, v15, v142 dst_sel:DWORD dst_unused:UNUSED_PAD src0_sel:WORD_1 src1_sel:DWORD
	v_and_b32_sdwa v17, v13, v142 dst_sel:DWORD dst_unused:UNUSED_PAD src0_sel:WORD_1 src1_sel:DWORD
	v_add3_u32 v15, v15, v16, s46
	v_add3_u32 v13, v13, v17, s46
	v_and_b32_e32 v15, 0xffff0000, v15
	v_and_b32_e32 v16, 0xffff0000, v13
	v_or_b32_sdwa v13, v15, v14 dst_sel:DWORD dst_unused:UNUSED_PAD src0_sel:DWORD src1_sel:WORD_1
	v_or_b32_sdwa v12, v16, v12 dst_sel:DWORD dst_unused:UNUSED_PAD src0_sel:DWORD src1_sel:WORD_1
	global_store_dwordx2 v[66:67], v[12:13], off offset:96
	v_and_b32_sdwa v12, v10, v142 dst_sel:DWORD dst_unused:UNUSED_PAD src0_sel:WORD_1 src1_sel:DWORD
	v_and_b32_sdwa v13, v8, v142 dst_sel:DWORD dst_unused:UNUSED_PAD src0_sel:WORD_1 src1_sel:DWORD
	v_add3_u32 v8, v8, v13, s46
	v_add3_u32 v10, v10, v12, s46
	v_and_b32_sdwa v12, v11, v142 dst_sel:DWORD dst_unused:UNUSED_PAD src0_sel:WORD_1 src1_sel:DWORD
	v_and_b32_sdwa v13, v9, v142 dst_sel:DWORD dst_unused:UNUSED_PAD src0_sel:WORD_1 src1_sel:DWORD
	v_add3_u32 v11, v11, v12, s46
	v_add3_u32 v9, v9, v13, s46
	v_and_b32_e32 v11, 0xffff0000, v11
	v_and_b32_e32 v12, 0xffff0000, v9
	v_or_b32_sdwa v9, v11, v10 dst_sel:DWORD dst_unused:UNUSED_PAD src0_sel:DWORD src1_sel:WORD_1
	v_or_b32_sdwa v8, v12, v8 dst_sel:DWORD dst_unused:UNUSED_PAD src0_sel:DWORD src1_sel:WORD_1
	global_store_dwordx2 v[60:61], v[8:9], off offset:96
	v_and_b32_sdwa v8, v6, v142 dst_sel:DWORD dst_unused:UNUSED_PAD src0_sel:WORD_1 src1_sel:DWORD
	v_and_b32_sdwa v9, v4, v142 dst_sel:DWORD dst_unused:UNUSED_PAD src0_sel:WORD_1 src1_sel:DWORD
	v_add3_u32 v4, v4, v9, s46
	v_add3_u32 v6, v6, v8, s46
	v_and_b32_sdwa v8, v7, v142 dst_sel:DWORD dst_unused:UNUSED_PAD src0_sel:WORD_1 src1_sel:DWORD
	v_and_b32_sdwa v9, v5, v142 dst_sel:DWORD dst_unused:UNUSED_PAD src0_sel:WORD_1 src1_sel:DWORD
	v_add3_u32 v7, v7, v8, s46
	v_add3_u32 v5, v5, v9, s46
	v_and_b32_e32 v7, 0xffff0000, v7
	v_and_b32_e32 v8, 0xffff0000, v5
	v_or_b32_sdwa v5, v7, v6 dst_sel:DWORD dst_unused:UNUSED_PAD src0_sel:DWORD src1_sel:WORD_1
	v_or_b32_sdwa v4, v8, v4 dst_sel:DWORD dst_unused:UNUSED_PAD src0_sel:DWORD src1_sel:WORD_1
	global_store_dwordx2 v[56:57], v[4:5], off offset:96
	v_and_b32_sdwa v4, v2, v142 dst_sel:DWORD dst_unused:UNUSED_PAD src0_sel:WORD_1 src1_sel:DWORD
	v_and_b32_sdwa v5, v0, v142 dst_sel:DWORD dst_unused:UNUSED_PAD src0_sel:WORD_1 src1_sel:DWORD
	v_add3_u32 v0, v0, v5, s46
	v_add3_u32 v2, v2, v4, s46
	v_and_b32_sdwa v4, v3, v142 dst_sel:DWORD dst_unused:UNUSED_PAD src0_sel:WORD_1 src1_sel:DWORD
	v_and_b32_sdwa v5, v1, v142 dst_sel:DWORD dst_unused:UNUSED_PAD src0_sel:WORD_1 src1_sel:DWORD
	v_add3_u32 v3, v3, v4, s46
	v_add3_u32 v1, v1, v5, s46
	v_and_b32_e32 v3, 0xffff0000, v3
	v_and_b32_e32 v4, 0xffff0000, v1
	v_readlane_b32 s52, v254, 58
	v_or_b32_sdwa v1, v3, v2 dst_sel:DWORD dst_unused:UNUSED_PAD src0_sel:DWORD src1_sel:WORD_1
	v_or_b32_sdwa v0, v4, v0 dst_sel:DWORD dst_unused:UNUSED_PAD src0_sel:DWORD src1_sel:WORD_1
	s_mov_b64 s[0:1], 0
	v_readlane_b32 s53, v254, 59
	global_store_dwordx2 v[52:53], v[0:1], off offset:96

.LBB0_1949:
	s_add_i32 s6, s5, 2
	s_mul_hi_i32 s7, s6, 0x55555556
	s_lshr_b32 s41, s7, 31
	s_add_i32 s7, s7, s41
	s_mul_i32 s7, s7, 3
	s_sub_i32 s6, s6, s7
	s_mulk_i32 s6, 0x6000
	s_mul_i32 s54, s5, 0x6000
	v_readfirstlane_b32 s55, v140
	v_lshl_add_u64 v[232:233], v[132:133], 0, s[0:1]
	v_lshl_add_u64 v[234:235], v[130:131], 0, s[0:1]
	s_add_u32 s55, s55, s6
	s_waitcnt vmcnt(6) lgkmcnt(0)
	s_barrier
	s_setprio 1
	s_mov_b32 m0, s55
	v_lshl_add_u64 v[236:237], v[232:233], 0, s[20:21]
	global_load_lds_dwordx4 v[236:237], off
	s_add_u32 m0, s55, 0x1000
	v_lshl_add_u64 v[236:237], v[232:233], 0, s[22:23]
	global_load_lds_dwordx4 v[236:237], off
	s_add_u32 m0, s55, 0x2000
	v_lshl_add_u64 v[236:237], v[232:233], 0, s[24:25]
	global_load_lds_dwordx4 v[236:237], off
	s_add_u32 m0, s55, 0x3000
	v_lshl_add_u64 v[236:237], v[232:233], 0, s[26:27]
	global_load_lds_dwordx4 v[236:237], off
	s_add_u32 m0, s55, 0x4000
	v_lshl_add_u64 v[236:237], v[234:235], 0, s[28:29]
	global_load_lds_dwordx4 v[236:237], off
	s_add_u32 m0, s55, 0x5000
	v_lshl_add_u64 v[236:237], v[234:235], 0, s[30:31]
	global_load_lds_dwordx4 v[236:237], off
	v_or_b32_e32 v128, s54, v138
	v_add3_u32 v128, v128, v139, v137
	ds_read_b128 v[176:179], v128 offset:16384
	ds_read_b128 v[180:183], v128 offset:16640
	ds_read_b128 v[184:187], v128 offset:18432
	ds_read_b128 v[192:195], v128 offset:18688
	v_add3_u32 v128, s54, v141, v137
	ds_read_b128 v[144:147], v128
	ds_read_b128 v[148:151], v128 offset:1024
	ds_read_b128 v[152:155], v128 offset:2048
	ds_read_b128 v[156:159], v128 offset:3072
	ds_read_b128 v[160:163], v128 offset:4096
	ds_read_b128 v[164:167], v128 offset:5120
	ds_read_b128 v[168:171], v128 offset:6144
	ds_read_b128 v[172:175], v128 offset:7168
	s_setprio 0
	s_waitcnt lgkmcnt(7)
	v_mfma_f32_16x16x32_bf16 v[124:127], v[176:179], v[144:147], v[124:127]
	v_mfma_f32_16x16x32_bf16 v[120:123], v[180:183], v[144:147], v[120:123]
	v_mfma_f32_16x16x32_bf16 v[116:119], v[184:187], v[144:147], v[116:119]
	v_mfma_f32_16x16x32_bf16 v[112:115], v[192:195], v[144:147], v[112:115]
	s_waitcnt lgkmcnt(6)
	v_mfma_f32_16x16x32_bf16 v[108:111], v[176:179], v[148:151], v[108:111]
	v_mfma_f32_16x16x32_bf16 v[104:107], v[180:183], v[148:151], v[104:107]
	v_mfma_f32_16x16x32_bf16 v[100:103], v[184:187], v[148:151], v[100:103]
	v_mfma_f32_16x16x32_bf16 v[96:99], v[192:195], v[148:151], v[96:99]
	s_waitcnt lgkmcnt(5)
	v_mfma_f32_16x16x32_bf16 v[92:95], v[176:179], v[152:155], v[92:95]
	v_mfma_f32_16x16x32_bf16 v[88:91], v[180:183], v[152:155], v[88:91]
	v_mfma_f32_16x16x32_bf16 v[84:87], v[184:187], v[152:155], v[84:87]
	v_mfma_f32_16x16x32_bf16 v[80:83], v[192:195], v[152:155], v[80:83]
	s_waitcnt lgkmcnt(4)
	v_mfma_f32_16x16x32_bf16 v[76:79], v[176:179], v[156:159], v[76:79]
	v_mfma_f32_16x16x32_bf16 v[72:75], v[180:183], v[156:159], v[72:75]
	v_mfma_f32_16x16x32_bf16 v[68:71], v[184:187], v[156:159], v[68:71]
	v_mfma_f32_16x16x32_bf16 v[64:67], v[192:195], v[156:159], v[64:67]
	s_waitcnt lgkmcnt(3)
	v_mfma_f32_16x16x32_bf16 v[60:63], v[176:179], v[160:163], v[60:63]
	v_mfma_f32_16x16x32_bf16 v[56:59], v[180:183], v[160:163], v[56:59]
	v_mfma_f32_16x16x32_bf16 v[52:55], v[184:187], v[160:163], v[52:55]
	v_mfma_f32_16x16x32_bf16 v[48:51], v[192:195], v[160:163], v[48:51]
	s_waitcnt lgkmcnt(2)
	v_mfma_f32_16x16x32_bf16 v[44:47], v[176:179], v[164:167], v[44:47]
	v_mfma_f32_16x16x32_bf16 v[40:43], v[180:183], v[164:167], v[40:43]
	v_mfma_f32_16x16x32_bf16 v[36:39], v[184:187], v[164:167], v[36:39]
	v_mfma_f32_16x16x32_bf16 v[32:35], v[192:195], v[164:167], v[32:35]
	s_waitcnt lgkmcnt(1)
	v_mfma_f32_16x16x32_bf16 v[28:31], v[176:179], v[168:171], v[28:31]
	v_mfma_f32_16x16x32_bf16 v[24:27], v[180:183], v[168:171], v[24:27]
	v_mfma_f32_16x16x32_bf16 v[20:23], v[184:187], v[168:171], v[20:23]
	v_mfma_f32_16x16x32_bf16 v[16:19], v[192:195], v[168:171], v[16:19]
	s_waitcnt lgkmcnt(0)
	v_mfma_f32_16x16x32_bf16 v[12:15], v[176:179], v[172:175], v[12:15]
	v_mfma_f32_16x16x32_bf16 v[8:11], v[180:183], v[172:175], v[8:11]
	v_mfma_f32_16x16x32_bf16 v[4:7], v[184:187], v[172:175], v[4:7]
	v_mfma_f32_16x16x32_bf16 v[0:3], v[192:195], v[172:175], v[0:3]
	s_add_i32 s6, s5, 1
	s_cmp_lg_u32 s5, 2
	s_cselect_b32 s5, s6, 0
	s_add_u32 s0, s0, 0x80
	s_addc_u32 s1, s1, 0
	s_cmpk_eq_i32 s0, 0xf00
	s_cbranch_scc0 .LBB0_1949
	s_waitcnt vmcnt(6) lgkmcnt(0)
	s_barrier
	v_add_u32_e32 v128, v141, v137
	ds_read_b128 v[130:133], v128
	ds_read_b128 v[144:147], v128 offset:1024
	ds_read_b128 v[148:151], v128 offset:2048
	ds_read_b128 v[152:155], v128 offset:3072
	ds_read_b128 v[156:159], v128 offset:4096
	ds_read_b128 v[160:163], v128 offset:5120
	ds_read_b128 v[164:167], v128 offset:6144
	ds_read_b128 v[168:171], v128 offset:7168
	v_add3_u32 v137, v138, v139, v137
	ds_read_b128 v[138:141], v137 offset:16384
	ds_read_b128 v[172:175], v137 offset:16640
	ds_read_b128 v[176:179], v137 offset:18432
	ds_read_b128 v[180:183], v137 offset:18688
	s_setprio 1
	s_waitcnt lgkmcnt(0)
	v_mfma_f32_16x16x32_bf16 v[124:127], v[138:141], v[130:133], v[124:127]
	v_mfma_f32_16x16x32_bf16 v[184:187], v[172:175], v[130:133], v[120:123]
	v_mfma_f32_16x16x32_bf16 v[116:119], v[176:179], v[130:133], v[116:119]
	v_mfma_f32_16x16x32_bf16 v[130:133], v[180:183], v[130:133], v[112:115]
	v_mfma_f32_16x16x32_bf16 v[108:111], v[138:141], v[144:147], v[108:111]
	v_mfma_f32_16x16x32_bf16 v[100:103], v[176:179], v[144:147], v[100:103]
	v_mfma_f32_16x16x32_bf16 v[92:95], v[138:141], v[148:151], v[92:95]
	v_mfma_f32_16x16x32_bf16 v[84:87], v[176:179], v[148:151], v[84:87]
	v_mfma_f32_16x16x32_bf16 v[76:79], v[138:141], v[152:155], v[76:79]
	v_mfma_f32_16x16x32_bf16 v[68:71], v[176:179], v[152:155], v[68:71]
	v_mfma_f32_16x16x32_bf16 v[60:63], v[138:141], v[156:159], v[60:63]
	v_mfma_f32_16x16x32_bf16 v[52:55], v[176:179], v[156:159], v[52:55]
	v_mfma_f32_16x16x32_bf16 v[44:47], v[138:141], v[160:163], v[44:47]
	v_mfma_f32_16x16x32_bf16 v[36:39], v[176:179], v[160:163], v[36:39]
	v_mfma_f32_16x16x32_bf16 v[28:31], v[138:141], v[164:167], v[28:31]
	v_mfma_f32_16x16x32_bf16 v[20:23], v[176:179], v[164:167], v[20:23]
	v_mfma_f32_16x16x32_bf16 v[12:15], v[138:141], v[168:171], v[12:15]
	v_mfma_f32_16x16x32_bf16 v[138:141], v[172:175], v[168:171], v[8:11]
	v_mfma_f32_16x16x32_bf16 v[4:7], v[176:179], v[168:171], v[4:7]
	v_mfma_f32_16x16x32_bf16 v[192:195], v[172:175], v[144:147], v[104:107]
	v_mfma_f32_16x16x32_bf16 v[144:147], v[180:183], v[144:147], v[96:99]
	v_mfma_f32_16x16x32_bf16 v[196:199], v[172:175], v[148:151], v[88:91]
	v_mfma_f32_16x16x32_bf16 v[148:151], v[180:183], v[148:151], v[80:83]
	v_mfma_f32_16x16x32_bf16 v[200:203], v[172:175], v[152:155], v[72:75]
	v_mfma_f32_16x16x32_bf16 v[152:155], v[180:183], v[152:155], v[64:67]
	v_mfma_f32_16x16x32_bf16 v[204:207], v[172:175], v[156:159], v[56:59]
	v_mfma_f32_16x16x32_bf16 v[156:159], v[180:183], v[156:159], v[48:51]
	v_mfma_f32_16x16x32_bf16 v[208:211], v[172:175], v[160:163], v[40:43]
	v_mfma_f32_16x16x32_bf16 v[160:163], v[180:183], v[160:163], v[32:35]
	v_mfma_f32_16x16x32_bf16 v[212:215], v[172:175], v[164:167], v[24:27]
	v_mfma_f32_16x16x32_bf16 v[164:167], v[180:183], v[164:167], v[16:19]
	v_mfma_f32_16x16x32_bf16 v[168:171], v[180:183], v[168:171], v[0:3]
	s_setprio 0
	s_waitcnt vmcnt(0) lgkmcnt(0)
	s_barrier
	s_nop 1
	ds_read_b128 v[0:3], v128 offset:24576
	ds_read_b128 v[8:11], v128 offset:25600
	ds_read_b128 v[16:19], v128 offset:26624
	ds_read_b128 v[24:27], v128 offset:27648
	ds_read_b128 v[32:35], v128 offset:28672
	ds_read_b128 v[172:175], v128 offset:29696
	ds_read_b128 v[176:179], v128 offset:30720
	ds_read_b128 v[180:183], v128 offset:31744
	ds_read_b128 v[216:219], v137 offset:40960
	ds_read_b128 v[220:223], v137 offset:41216
	ds_read_b128 v[224:227], v137 offset:43008
	ds_read_b128 v[228:231], v137 offset:43264
	s_setprio 1
	s_waitcnt lgkmcnt(0)
	v_mfma_f32_16x16x32_bf16 v[120:123], v[216:219], v[0:3], v[124:127]
	v_mfma_f32_16x16x32_bf16 v[124:127], v[220:223], v[0:3], v[184:187]
	v_mfma_f32_16x16x32_bf16 v[112:115], v[224:227], v[0:3], v[116:119]
	v_mfma_f32_16x16x32_bf16 v[116:119], v[228:231], v[0:3], v[130:133]
	v_mfma_f32_16x16x32_bf16 v[104:107], v[216:219], v[8:11], v[108:111]
	v_mfma_f32_16x16x32_bf16 v[108:111], v[220:223], v[8:11], v[192:195]
	v_mfma_f32_16x16x32_bf16 v[96:99], v[224:227], v[8:11], v[100:103]
	v_mfma_f32_16x16x32_bf16 v[100:103], v[228:231], v[8:11], v[144:147]
	v_mfma_f32_16x16x32_bf16 v[88:91], v[216:219], v[16:19], v[92:95]
	v_mfma_f32_16x16x32_bf16 v[92:95], v[220:223], v[16:19], v[196:199]
	v_mfma_f32_16x16x32_bf16 v[80:83], v[224:227], v[16:19], v[84:87]
	v_mfma_f32_16x16x32_bf16 v[84:87], v[228:231], v[16:19], v[148:151]
	v_mfma_f32_16x16x32_bf16 v[72:75], v[216:219], v[24:27], v[76:79]
	v_mfma_f32_16x16x32_bf16 v[76:79], v[220:223], v[24:27], v[200:203]
	v_mfma_f32_16x16x32_bf16 v[64:67], v[224:227], v[24:27], v[68:71]
	v_mfma_f32_16x16x32_bf16 v[68:71], v[228:231], v[24:27], v[152:155]
	v_mfma_f32_16x16x32_bf16 v[56:59], v[216:219], v[32:35], v[60:63]
	v_mfma_f32_16x16x32_bf16 v[60:63], v[220:223], v[32:35], v[204:207]
	v_mfma_f32_16x16x32_bf16 v[48:51], v[224:227], v[32:35], v[52:55]
	v_mfma_f32_16x16x32_bf16 v[52:55], v[228:231], v[32:35], v[156:159]
	v_mfma_f32_16x16x32_bf16 v[40:43], v[216:219], v[172:175], v[44:47]
	v_mfma_f32_16x16x32_bf16 v[44:47], v[220:223], v[172:175], v[208:211]
	v_mfma_f32_16x16x32_bf16 v[32:35], v[224:227], v[172:175], v[36:39]
	v_mfma_f32_16x16x32_bf16 v[36:39], v[228:231], v[172:175], v[160:163]
	v_mfma_f32_16x16x32_bf16 v[24:27], v[216:219], v[176:179], v[28:31]
	v_mfma_f32_16x16x32_bf16 v[28:31], v[220:223], v[176:179], v[212:215]
	v_mfma_f32_16x16x32_bf16 v[16:19], v[224:227], v[176:179], v[20:23]
	v_mfma_f32_16x16x32_bf16 v[20:23], v[228:231], v[176:179], v[164:167]
	v_mfma_f32_16x16x32_bf16 v[8:11], v[216:219], v[180:183], v[12:15]
	v_mfma_f32_16x16x32_bf16 v[12:15], v[220:223], v[180:183], v[138:141]
	v_mfma_f32_16x16x32_bf16 v[0:3], v[224:227], v[180:183], v[4:7]
	v_mfma_f32_16x16x32_bf16 v[4:7], v[228:231], v[180:183], v[168:171]
	s_setprio 0
	v_and_b32_e32 v128, 0xffffff80, v134
	v_add_u32_e32 v128, s40, v128
	v_or_b32_e32 v132, v128, v135
	v_lshrrev_b32_e32 v130, 1, v134
	v_lshlrev_b32_e32 v128, 6, v136
	v_and_b32_e32 v130, 24, v130
	v_ashrrev_i32_e32 v133, 31, v132
	v_readlane_b32 s0, v254, 62
	v_or3_b32 v128, v128, v130, s4
	v_lshlrev_b64 v[130:131], 11, v[132:133]
	v_readlane_b32 s1, v254, 63
	v_cmp_lt_i32_e64 s[4:5], s48, v128
	s_nop 0
	v_lshl_add_u64 v[136:137], s[0:1], 0, v[130:131]
	v_lshlrev_b64 v[130:131], 10, v[132:133]
	v_lshl_add_u64 v[134:135], s[96:97], 0, v[130:131]
	s_and_saveexec_b64 s[0:1], s[4:5]
	s_xor_b64 s[0:1], exec, s[0:1]
	s_cbranch_execz .LBB0_1955
	s_cmpk_gt_u32 s33, 0x3ff
	s_mov_b64 s[6:7], -1
	s_cbranch_scc0 .LBB0_1953
	v_lshl_add_u64 v[138:139], v[128:129], 1, v[136:137]
	v_lshl_add_u64 v[138:139], v[138:139], 0, s[2:3]
	s_mov_b64 s[6:7], 0

.LBB0_2563:
	s_add_i32 s36, s35, 2
	s_mul_hi_i32 s37, s36, 0x55555556
	s_lshr_b32 s38, s37, 31
	s_add_i32 s37, s37, s38
	s_mul_i32 s37, s37, 3
	s_sub_i32 s36, s36, s37
	s_mulk_i32 s36, 0x6000
	s_mul_i32 s54, s35, 0x6000
	v_readfirstlane_b32 s55, v140
	v_lshl_add_u64 v[232:233], v[132:133], 0, s[24:25]
	v_lshl_add_u64 v[234:235], v[130:131], 0, s[24:25]
	s_add_u32 s55, s55, s36
	s_waitcnt vmcnt(6) lgkmcnt(0)
	s_barrier
	s_setprio 1
	s_mov_b32 m0, s55
	v_lshl_add_u64 v[236:237], v[232:233], 0, s[12:13]
	global_load_lds_dwordx4 v[236:237], off
	s_add_u32 m0, s55, 0x1000
	v_lshl_add_u64 v[236:237], v[232:233], 0, s[14:15]
	global_load_lds_dwordx4 v[236:237], off
	s_add_u32 m0, s55, 0x2000
	v_lshl_add_u64 v[236:237], v[232:233], 0, s[16:17]
	global_load_lds_dwordx4 v[236:237], off
	s_add_u32 m0, s55, 0x3000
	v_lshl_add_u64 v[236:237], v[232:233], 0, s[18:19]
	global_load_lds_dwordx4 v[236:237], off
	s_add_u32 m0, s55, 0x4000
	v_lshl_add_u64 v[236:237], v[234:235], 0, s[20:21]
	global_load_lds_dwordx4 v[236:237], off
	s_add_u32 m0, s55, 0x5000
	v_lshl_add_u64 v[236:237], v[234:235], 0, s[22:23]
	global_load_lds_dwordx4 v[236:237], off
	v_or_b32_e32 v128, s54, v138
	v_add3_u32 v128, v128, v139, v137
	ds_read_b128 v[174:177], v128 offset:16384
	ds_read_b128 v[178:181], v128 offset:16640
	ds_read_b128 v[182:185], v128 offset:18432
	ds_read_b128 v[186:189], v128 offset:18688
	v_add3_u32 v128, s54, v141, v137
	ds_read_b128 v[142:145], v128
	ds_read_b128 v[146:149], v128 offset:1024
	ds_read_b128 v[150:153], v128 offset:2048
	ds_read_b128 v[154:157], v128 offset:3072
	ds_read_b128 v[158:161], v128 offset:4096
	ds_read_b128 v[162:165], v128 offset:5120
	ds_read_b128 v[166:169], v128 offset:6144
	ds_read_b128 v[170:173], v128 offset:7168
	s_setprio 0
	s_waitcnt lgkmcnt(7)
	v_mfma_f32_16x16x32_bf16 v[124:127], v[174:177], v[142:145], v[124:127]
	v_mfma_f32_16x16x32_bf16 v[120:123], v[178:181], v[142:145], v[120:123]
	v_mfma_f32_16x16x32_bf16 v[116:119], v[182:185], v[142:145], v[116:119]
	v_mfma_f32_16x16x32_bf16 v[112:115], v[186:189], v[142:145], v[112:115]
	s_waitcnt lgkmcnt(6)
	v_mfma_f32_16x16x32_bf16 v[108:111], v[174:177], v[146:149], v[108:111]
	v_mfma_f32_16x16x32_bf16 v[104:107], v[178:181], v[146:149], v[104:107]
	v_mfma_f32_16x16x32_bf16 v[100:103], v[182:185], v[146:149], v[100:103]
	v_mfma_f32_16x16x32_bf16 v[96:99], v[186:189], v[146:149], v[96:99]
	s_waitcnt lgkmcnt(5)
	v_mfma_f32_16x16x32_bf16 v[92:95], v[174:177], v[150:153], v[92:95]
	v_mfma_f32_16x16x32_bf16 v[88:91], v[178:181], v[150:153], v[88:91]
	v_mfma_f32_16x16x32_bf16 v[84:87], v[182:185], v[150:153], v[84:87]
	v_mfma_f32_16x16x32_bf16 v[80:83], v[186:189], v[150:153], v[80:83]
	s_waitcnt lgkmcnt(4)
	v_mfma_f32_16x16x32_bf16 v[76:79], v[174:177], v[154:157], v[76:79]
	v_mfma_f32_16x16x32_bf16 v[72:75], v[178:181], v[154:157], v[72:75]
	v_mfma_f32_16x16x32_bf16 v[68:71], v[182:185], v[154:157], v[68:71]
	v_mfma_f32_16x16x32_bf16 v[64:67], v[186:189], v[154:157], v[64:67]
	s_waitcnt lgkmcnt(3)
	v_mfma_f32_16x16x32_bf16 v[60:63], v[174:177], v[158:161], v[60:63]
	v_mfma_f32_16x16x32_bf16 v[56:59], v[178:181], v[158:161], v[56:59]
	v_mfma_f32_16x16x32_bf16 v[52:55], v[182:185], v[158:161], v[52:55]
	v_mfma_f32_16x16x32_bf16 v[48:51], v[186:189], v[158:161], v[48:51]
	s_waitcnt lgkmcnt(2)
	v_mfma_f32_16x16x32_bf16 v[44:47], v[174:177], v[162:165], v[44:47]
	v_mfma_f32_16x16x32_bf16 v[40:43], v[178:181], v[162:165], v[40:43]
	v_mfma_f32_16x16x32_bf16 v[36:39], v[182:185], v[162:165], v[36:39]
	v_mfma_f32_16x16x32_bf16 v[32:35], v[186:189], v[162:165], v[32:35]
	s_waitcnt lgkmcnt(1)
	v_mfma_f32_16x16x32_bf16 v[28:31], v[174:177], v[166:169], v[28:31]
	v_mfma_f32_16x16x32_bf16 v[24:27], v[178:181], v[166:169], v[24:27]
	v_mfma_f32_16x16x32_bf16 v[20:23], v[182:185], v[166:169], v[20:23]
	v_mfma_f32_16x16x32_bf16 v[16:19], v[186:189], v[166:169], v[16:19]
	s_waitcnt lgkmcnt(0)
	v_mfma_f32_16x16x32_bf16 v[12:15], v[174:177], v[170:173], v[12:15]
	v_mfma_f32_16x16x32_bf16 v[8:11], v[178:181], v[170:173], v[8:11]
	v_mfma_f32_16x16x32_bf16 v[4:7], v[182:185], v[170:173], v[4:7]
	v_mfma_f32_16x16x32_bf16 v[0:3], v[186:189], v[170:173], v[0:3]
	s_add_i32 s36, s35, 1
	s_cmp_lg_u32 s35, 2
	s_cselect_b32 s35, s36, 0
	s_add_u32 s24, s24, 64
	s_addc_u32 s25, s25, 0
	s_cmpk_eq_i32 s24, 0x780
	s_cbranch_scc0 .LBB0_2563
	s_waitcnt vmcnt(6) lgkmcnt(0)
	s_barrier
	v_add_u32_e32 v128, v141, v137
	ds_read_b128 v[130:133], v128
	ds_read_b128 v[140:143], v128 offset:1024
	ds_read_b128 v[144:147], v128 offset:2048
	ds_read_b128 v[148:151], v128 offset:3072
	ds_read_b128 v[152:155], v128 offset:4096
	ds_read_b128 v[156:159], v128 offset:5120
	ds_read_b128 v[160:163], v128 offset:6144
	ds_read_b128 v[164:167], v128 offset:7168
	v_add3_u32 v137, v138, v139, v137
	ds_read_b128 v[168:171], v137 offset:16384
	ds_read_b128 v[172:175], v137 offset:16640
	ds_read_b128 v[176:179], v137 offset:18432
	ds_read_b128 v[180:183], v137 offset:18688
	s_setprio 1
	s_waitcnt lgkmcnt(0)
	v_mfma_f32_16x16x32_bf16 v[124:127], v[168:171], v[130:133], v[124:127]
	v_mfma_f32_16x16x32_bf16 v[120:123], v[172:175], v[130:133], v[120:123]
	v_mfma_f32_16x16x32_bf16 v[116:119], v[176:179], v[130:133], v[116:119]
	v_mfma_f32_16x16x32_bf16 v[112:115], v[180:183], v[130:133], v[112:115]
	v_mfma_f32_16x16x32_bf16 v[108:111], v[168:171], v[140:143], v[108:111]
	v_mfma_f32_16x16x32_bf16 v[104:107], v[172:175], v[140:143], v[104:107]
	v_mfma_f32_16x16x32_bf16 v[100:103], v[176:179], v[140:143], v[100:103]
	v_mfma_f32_16x16x32_bf16 v[96:99], v[180:183], v[140:143], v[96:99]
	v_mfma_f32_16x16x32_bf16 v[92:95], v[168:171], v[144:147], v[92:95]
	v_mfma_f32_16x16x32_bf16 v[88:91], v[172:175], v[144:147], v[88:91]
	v_mfma_f32_16x16x32_bf16 v[84:87], v[176:179], v[144:147], v[84:87]
	v_mfma_f32_16x16x32_bf16 v[80:83], v[180:183], v[144:147], v[80:83]
	v_mfma_f32_16x16x32_bf16 v[76:79], v[168:171], v[148:151], v[76:79]
	v_mfma_f32_16x16x32_bf16 v[72:75], v[172:175], v[148:151], v[72:75]
	v_mfma_f32_16x16x32_bf16 v[68:71], v[176:179], v[148:151], v[68:71]
	v_mfma_f32_16x16x32_bf16 v[64:67], v[180:183], v[148:151], v[64:67]
	v_mfma_f32_16x16x32_bf16 v[60:63], v[168:171], v[152:155], v[60:63]
	v_mfma_f32_16x16x32_bf16 v[56:59], v[172:175], v[152:155], v[56:59]
	v_mfma_f32_16x16x32_bf16 v[52:55], v[176:179], v[152:155], v[52:55]
	v_mfma_f32_16x16x32_bf16 v[48:51], v[180:183], v[152:155], v[48:51]
	v_mfma_f32_16x16x32_bf16 v[44:47], v[168:171], v[156:159], v[44:47]
	v_mfma_f32_16x16x32_bf16 v[40:43], v[172:175], v[156:159], v[40:43]
	v_mfma_f32_16x16x32_bf16 v[36:39], v[176:179], v[156:159], v[36:39]
	v_mfma_f32_16x16x32_bf16 v[32:35], v[180:183], v[156:159], v[32:35]
	v_mfma_f32_16x16x32_bf16 v[28:31], v[168:171], v[160:163], v[28:31]
	v_mfma_f32_16x16x32_bf16 v[24:27], v[172:175], v[160:163], v[24:27]
	v_mfma_f32_16x16x32_bf16 v[20:23], v[176:179], v[160:163], v[20:23]
	v_mfma_f32_16x16x32_bf16 v[16:19], v[180:183], v[160:163], v[16:19]
	v_mfma_f32_16x16x32_bf16 v[12:15], v[168:171], v[164:167], v[12:15]
	v_mfma_f32_16x16x32_bf16 v[8:11], v[172:175], v[164:167], v[8:11]
	v_mfma_f32_16x16x32_bf16 v[4:7], v[176:179], v[164:167], v[4:7]
	v_mfma_f32_16x16x32_bf16 v[0:3], v[180:183], v[164:167], v[0:3]
	s_setprio 0
	s_waitcnt vmcnt(0) lgkmcnt(0)
	s_barrier
	ds_read_b128 v[130:133], v128 offset:24576
	ds_read_b128 v[138:141], v128 offset:25600
	ds_read_b128 v[142:145], v128 offset:26624
	ds_read_b128 v[146:149], v128 offset:27648
	ds_read_b128 v[150:153], v128 offset:28672
	ds_read_b128 v[154:157], v128 offset:29696
	ds_read_b128 v[158:161], v128 offset:30720
	ds_read_b128 v[162:165], v128 offset:31744
	ds_read_b128 v[166:169], v137 offset:40960
	ds_read_b128 v[170:173], v137 offset:41216
	ds_read_b128 v[174:177], v137 offset:43008
	ds_read_b128 v[178:181], v137 offset:43264
	s_setprio 1
	s_waitcnt lgkmcnt(0)
	v_mfma_f32_16x16x32_bf16 v[124:127], v[166:169], v[130:133], v[124:127]
	v_mfma_f32_16x16x32_bf16 v[120:123], v[170:173], v[130:133], v[120:123]
	v_mfma_f32_16x16x32_bf16 v[116:119], v[174:177], v[130:133], v[116:119]
	v_mfma_f32_16x16x32_bf16 v[112:115], v[178:181], v[130:133], v[112:115]
	v_mfma_f32_16x16x32_bf16 v[108:111], v[166:169], v[138:141], v[108:111]
	v_mfma_f32_16x16x32_bf16 v[104:107], v[170:173], v[138:141], v[104:107]
	v_mfma_f32_16x16x32_bf16 v[100:103], v[174:177], v[138:141], v[100:103]
	v_mfma_f32_16x16x32_bf16 v[130:133], v[178:181], v[138:141], v[96:99]
	v_mfma_f32_16x16x32_bf16 v[92:95], v[166:169], v[142:145], v[92:95]
	v_mfma_f32_16x16x32_bf16 v[88:91], v[170:173], v[142:145], v[88:91]
	v_mfma_f32_16x16x32_bf16 v[84:87], v[174:177], v[142:145], v[84:87]
	v_mfma_f32_16x16x32_bf16 v[80:83], v[178:181], v[142:145], v[80:83]
	v_mfma_f32_16x16x32_bf16 v[76:79], v[166:169], v[146:149], v[76:79]
	v_mfma_f32_16x16x32_bf16 v[72:75], v[170:173], v[146:149], v[72:75]
	v_mfma_f32_16x16x32_bf16 v[68:71], v[174:177], v[146:149], v[68:71]
	v_mfma_f32_16x16x32_bf16 v[64:67], v[178:181], v[146:149], v[64:67]
	v_mfma_f32_16x16x32_bf16 v[60:63], v[166:169], v[150:153], v[60:63]
	v_mfma_f32_16x16x32_bf16 v[56:59], v[170:173], v[150:153], v[56:59]
	v_mfma_f32_16x16x32_bf16 v[52:55], v[174:177], v[150:153], v[52:55]
	v_mfma_f32_16x16x32_bf16 v[48:51], v[178:181], v[150:153], v[48:51]
	v_mfma_f32_16x16x32_bf16 v[44:47], v[166:169], v[154:157], v[44:47]
	v_mfma_f32_16x16x32_bf16 v[40:43], v[170:173], v[154:157], v[40:43]
	v_mfma_f32_16x16x32_bf16 v[36:39], v[174:177], v[154:157], v[36:39]
	v_mfma_f32_16x16x32_bf16 v[32:35], v[178:181], v[154:157], v[32:35]
	v_mfma_f32_16x16x32_bf16 v[28:31], v[166:169], v[158:161], v[28:31]
	v_mfma_f32_16x16x32_bf16 v[24:27], v[170:173], v[158:161], v[24:27]
	v_mfma_f32_16x16x32_bf16 v[20:23], v[174:177], v[158:161], v[20:23]
	v_mfma_f32_16x16x32_bf16 v[16:19], v[178:181], v[158:161], v[16:19]
	v_mfma_f32_16x16x32_bf16 v[12:15], v[166:169], v[162:165], v[12:15]
	v_mfma_f32_16x16x32_bf16 v[8:11], v[170:173], v[162:165], v[8:11]
	v_mfma_f32_16x16x32_bf16 v[4:7], v[174:177], v[162:165], v[4:7]
	v_mfma_f32_16x16x32_bf16 v[0:3], v[178:181], v[162:165], v[0:3]
	s_setprio 0
	v_and_b32_e32 v96, 0xffffff80, v134
	v_lshrrev_b32_e32 v98, 1, v134
	v_add_u32_e32 v96, s33, v96
	v_lshlrev_b32_e32 v97, 6, v136
	v_and_b32_e32 v98, 24, v98
	v_or_b32_e32 v96, v96, v135
	v_or3_b32 v98, v97, v98, s34
	v_mov_b32_e32 v97, v129
	v_add_u32_e32 v128, 0xffffc000, v96
	v_readlane_b32 s24, v255, 39
	v_lshlrev_b64 v[138:139], 12, v[96:97]
	v_ashrrev_i32_e32 v97, 31, v96
	v_readlane_b32 s36, v254, 34
	v_lshlrev_b64 v[134:135], 12, v[128:129]
	v_readlane_b32 s25, v255, 40
	v_lshlrev_b64 v[140:141], 12, v[96:97]
	v_readlane_b32 s50, v254, 48
	v_readlane_b32 s51, v254, 49
	v_lshl_add_u64 v[134:135], s[24:25], 0, v[134:135]
	v_cmp_gt_i32_e32 vcc, s30, v96
	v_lshl_add_u64 v[136:137], s[50:51], 0, v[140:141]
	v_ashrrev_i32_e32 v99, 31, v98
	v_cndmask_b32_e32 v135, v135, v137, vcc
	v_cndmask_b32_e32 v134, v134, v136, vcc
	v_lshlrev_b64 v[98:99], 2, v[98:99]
	v_lshl_add_u64 v[142:143], v[134:135], 0, v[98:99]
	global_load_dwordx4 v[134:137], v[142:143], off
	v_cndmask_b32_e32 v139, v139, v141, vcc
	v_cndmask_b32_e32 v138, v138, v140, vcc
	v_lshl_add_u64 v[138:139], s[50:51], 0, v[138:139]
	v_lshl_add_u64 v[138:139], v[138:139], 0, v[98:99]
	v_add_u32_e32 v128, 0xffffc010, v96
	s_add_i32 s31, s31, s86
	s_add_i32 s26, s26, s27
	s_add_i32 s28, s28, s29
	s_cmpk_gt_i32 s31, 0x1ff
	v_readlane_b32 s37, v254, 35
	v_readlane_b32 s38, v254, 36
	v_readlane_b32 s39, v254, 37
	v_readlane_b32 s40, v254, 38
	v_readlane_b32 s41, v254, 39
	v_readlane_b32 s42, v254, 40
	v_readlane_b32 s43, v254, 41
	v_readlane_b32 s44, v254, 42
	v_readlane_b32 s45, v254, 43
	v_readlane_b32 s46, v254, 44
	v_readlane_b32 s47, v254, 45
	v_readlane_b32 s48, v254, 46
	v_readlane_b32 s49, v254, 47
	s_waitcnt vmcnt(0)
	v_pk_add_f32 v[124:125], v[124:125], v[134:135]
	v_pk_add_f32 v[126:127], v[126:127], v[136:137]
	global_store_dwordx4 v[138:139], v[124:127], off
	global_load_dwordx4 v[124:127], v[142:143], off offset:16
	s_waitcnt vmcnt(0)
	v_pk_add_f32 v[120:121], v[120:121], v[124:125]
	v_pk_add_f32 v[122:123], v[122:123], v[126:127]
	global_store_dwordx4 v[138:139], v[120:123], off offset:16
	global_load_dwordx4 v[120:123], v[142:143], off offset:128
	v_lshlrev_b64 v[124:125], 12, v[128:129]
	v_lshl_add_u64 v[124:125], s[24:25], 0, v[124:125]
	v_add_u32_e32 v128, 0xffffc020, v96
	s_waitcnt vmcnt(0)
	v_pk_add_f32 v[116:117], v[116:117], v[120:121]
	v_pk_add_f32 v[118:119], v[118:119], v[122:123]
	global_store_dwordx4 v[138:139], v[116:119], off offset:128
	global_load_dwordx4 v[116:119], v[142:143], off offset:144
	v_mov_b32_e32 v121, v129
	v_or_b32_e32 v120, 16, v96
	v_lshlrev_b64 v[122:123], 12, v[120:121]
	v_ashrrev_i32_e32 v121, 31, v120
	v_lshlrev_b64 v[126:127], 12, v[120:121]
	v_lshl_add_u64 v[134:135], s[50:51], 0, v[126:127]
	v_cmp_gt_i32_e32 vcc, s30, v120
	s_waitcnt vmcnt(0)
	v_pk_add_f32 v[112:113], v[112:113], v[116:117]
	v_cndmask_b32_e32 v125, v125, v135, vcc
	v_cndmask_b32_e32 v124, v124, v134, vcc
	v_pk_add_f32 v[114:115], v[114:115], v[118:119]
	v_lshl_add_u64 v[124:125], v[124:125], 0, v[98:99]
	global_store_dwordx4 v[138:139], v[112:115], off offset:144
	global_load_dwordx4 v[112:115], v[124:125], off
	v_cndmask_b32_e32 v121, v123, v127, vcc
	v_cndmask_b32_e32 v120, v122, v126, vcc
	v_lshl_add_u64 v[116:117], s[50:51], 0, v[120:121]
	v_lshl_add_u64 v[116:117], v[116:117], 0, v[98:99]
	s_waitcnt vmcnt(0)
	v_pk_add_f32 v[108:109], v[108:109], v[112:113]
	v_pk_add_f32 v[110:111], v[110:111], v[114:115]
	global_store_dwordx4 v[116:117], v[108:111], off
	global_load_dwordx4 v[108:111], v[124:125], off offset:16
	s_waitcnt vmcnt(0)
	v_pk_add_f32 v[104:105], v[104:105], v[108:109]
	v_pk_add_f32 v[106:107], v[106:107], v[110:111]
	global_store_dwordx4 v[116:117], v[104:107], off offset:16
	global_load_dwordx4 v[104:107], v[124:125], off offset:128
	v_lshlrev_b64 v[110:111], 12, v[128:129]
	v_lshl_add_u64 v[110:111], s[24:25], 0, v[110:111]
	v_add_u32_e32 v128, 0xffffc030, v96
	s_waitcnt vmcnt(0)
	v_pk_add_f32 v[100:101], v[100:101], v[104:105]
	v_pk_add_f32 v[102:103], v[102:103], v[106:107]
	global_store_dwordx4 v[116:117], v[100:103], off offset:128
	global_load_dwordx4 v[100:103], v[124:125], off offset:144
	v_mov_b32_e32 v105, v129
	v_or_b32_e32 v104, 32, v96
	v_lshlrev_b64 v[106:107], 12, v[104:105]
	v_ashrrev_i32_e32 v105, 31, v104
	v_lshlrev_b64 v[108:109], 12, v[104:105]
	v_lshl_add_u64 v[112:113], s[50:51], 0, v[108:109]
	v_cmp_gt_i32_e32 vcc, s30, v104
	s_waitcnt vmcnt(0)
	v_pk_add_f32 v[100:101], v[130:131], v[100:101]
	v_cndmask_b32_e32 v111, v111, v113, vcc
	v_cndmask_b32_e32 v110, v110, v112, vcc
	v_pk_add_f32 v[102:103], v[132:133], v[102:103]
	v_lshl_add_u64 v[110:111], v[110:111], 0, v[98:99]
	global_store_dwordx4 v[116:117], v[100:103], off offset:144
	global_load_dwordx4 v[100:103], v[110:111], off
	v_cndmask_b32_e32 v105, v107, v109, vcc
	v_cndmask_b32_e32 v104, v106, v108, vcc
	v_lshl_add_u64 v[104:105], s[50:51], 0, v[104:105]
	v_lshl_add_u64 v[104:105], v[104:105], 0, v[98:99]
	s_waitcnt vmcnt(0)
	v_pk_add_f32 v[92:93], v[92:93], v[100:101]
	v_pk_add_f32 v[94:95], v[94:95], v[102:103]
	global_store_dwordx4 v[104:105], v[92:95], off
	global_load_dwordx4 v[92:95], v[110:111], off offset:16
	v_lshlrev_b64 v[100:101], 12, v[128:129]
	v_lshl_add_u64 v[100:101], s[24:25], 0, v[100:101]
	v_add_u32_e32 v128, 0xffffc040, v96
	s_waitcnt vmcnt(0)
	v_pk_add_f32 v[88:89], v[88:89], v[92:93]
	v_pk_add_f32 v[90:91], v[90:91], v[94:95]
	global_store_dwordx4 v[104:105], v[88:91], off offset:16
	global_load_dwordx4 v[88:91], v[110:111], off offset:128
	s_waitcnt vmcnt(0)
	v_pk_add_f32 v[84:85], v[84:85], v[88:89]
	v_pk_add_f32 v[86:87], v[86:87], v[90:91]
	global_store_dwordx4 v[104:105], v[84:87], off offset:128
	global_load_dwordx4 v[84:87], v[110:111], off offset:144
	v_mov_b32_e32 v89, v129
	v_or_b32_e32 v88, 48, v96
	v_lshlrev_b64 v[90:91], 12, v[88:89]
	v_ashrrev_i32_e32 v89, 31, v88
	v_lshlrev_b64 v[92:93], 12, v[88:89]
	v_lshl_add_u64 v[94:95], s[50:51], 0, v[92:93]
	v_cmp_gt_i32_e32 vcc, s30, v88
	s_waitcnt vmcnt(0)
	v_pk_add_f32 v[80:81], v[80:81], v[84:85]
	v_cndmask_b32_e32 v95, v101, v95, vcc
	v_cndmask_b32_e32 v94, v100, v94, vcc
	v_pk_add_f32 v[82:83], v[82:83], v[86:87]
	v_lshl_add_u64 v[94:95], v[94:95], 0, v[98:99]
	global_store_dwordx4 v[104:105], v[80:83], off offset:144
	global_load_dwordx4 v[80:83], v[94:95], off
	v_cndmask_b32_e32 v89, v91, v93, vcc
	v_cndmask_b32_e32 v88, v90, v92, vcc
	v_lshl_add_u64 v[84:85], s[50:51], 0, v[88:89]
	v_lshl_add_u64 v[84:85], v[84:85], 0, v[98:99]
	s_waitcnt vmcnt(0)
	v_pk_add_f32 v[76:77], v[76:77], v[80:81]
	v_pk_add_f32 v[78:79], v[78:79], v[82:83]
	global_store_dwordx4 v[84:85], v[76:79], off
	global_load_dwordx4 v[76:79], v[94:95], off offset:16
	v_lshlrev_b64 v[80:81], 12, v[128:129]
	v_lshl_add_u64 v[80:81], s[24:25], 0, v[80:81]
	v_add_u32_e32 v128, 0xffffc050, v96
	s_waitcnt vmcnt(0)
	v_pk_add_f32 v[72:73], v[72:73], v[76:77]
	v_pk_add_f32 v[74:75], v[74:75], v[78:79]
	global_store_dwordx4 v[84:85], v[72:75], off offset:16
	global_load_dwordx4 v[72:75], v[94:95], off offset:128
	s_waitcnt vmcnt(0)
	v_pk_add_f32 v[68:69], v[68:69], v[72:73]
	v_pk_add_f32 v[70:71], v[70:71], v[74:75]
	global_store_dwordx4 v[84:85], v[68:71], off offset:128
	global_load_dwordx4 v[68:71], v[94:95], off offset:144
	v_mov_b32_e32 v73, v129
	v_or_b32_e32 v72, 64, v96
	v_lshlrev_b64 v[74:75], 12, v[72:73]
	v_ashrrev_i32_e32 v73, 31, v72
	v_lshlrev_b64 v[76:77], 12, v[72:73]
	v_lshl_add_u64 v[78:79], s[50:51], 0, v[76:77]
	v_cmp_gt_i32_e32 vcc, s30, v72
	s_waitcnt vmcnt(0)
	v_pk_add_f32 v[64:65], v[64:65], v[68:69]
	v_cndmask_b32_e32 v79, v81, v79, vcc
	v_cndmask_b32_e32 v78, v80, v78, vcc
	v_pk_add_f32 v[66:67], v[66:67], v[70:71]
	v_lshl_add_u64 v[78:79], v[78:79], 0, v[98:99]
	global_store_dwordx4 v[84:85], v[64:67], off offset:144
	global_load_dwordx4 v[64:67], v[78:79], off
	v_cndmask_b32_e32 v73, v75, v77, vcc
	v_cndmask_b32_e32 v72, v74, v76, vcc
	v_lshl_add_u64 v[68:69], s[50:51], 0, v[72:73]
	v_lshl_add_u64 v[68:69], v[68:69], 0, v[98:99]
	s_waitcnt vmcnt(0)
	v_pk_add_f32 v[60:61], v[60:61], v[64:65]
	v_pk_add_f32 v[62:63], v[62:63], v[66:67]
	global_store_dwordx4 v[68:69], v[60:63], off
	global_load_dwordx4 v[60:63], v[78:79], off offset:16
	v_lshlrev_b64 v[64:65], 12, v[128:129]
	v_lshl_add_u64 v[64:65], s[24:25], 0, v[64:65]
	v_add_u32_e32 v128, 0xffffc060, v96
	s_waitcnt vmcnt(0)
	v_pk_add_f32 v[56:57], v[56:57], v[60:61]
	v_pk_add_f32 v[58:59], v[58:59], v[62:63]
	global_store_dwordx4 v[68:69], v[56:59], off offset:16
	global_load_dwordx4 v[56:59], v[78:79], off offset:128
	s_waitcnt vmcnt(0)
	v_pk_add_f32 v[52:53], v[52:53], v[56:57]
	v_pk_add_f32 v[54:55], v[54:55], v[58:59]
	global_store_dwordx4 v[68:69], v[52:55], off offset:128
	global_load_dwordx4 v[52:55], v[78:79], off offset:144
	v_mov_b32_e32 v57, v129
	v_or_b32_e32 v56, 0x50, v96
	v_lshlrev_b64 v[58:59], 12, v[56:57]
	v_ashrrev_i32_e32 v57, 31, v56
	v_lshlrev_b64 v[60:61], 12, v[56:57]
	v_lshl_add_u64 v[62:63], s[50:51], 0, v[60:61]
	v_cmp_gt_i32_e32 vcc, s30, v56
	s_waitcnt vmcnt(0)
	v_pk_add_f32 v[48:49], v[48:49], v[52:53]
	v_cndmask_b32_e32 v63, v65, v63, vcc
	v_cndmask_b32_e32 v62, v64, v62, vcc
	v_pk_add_f32 v[50:51], v[50:51], v[54:55]
	v_lshl_add_u64 v[62:63], v[62:63], 0, v[98:99]
	global_store_dwordx4 v[68:69], v[48:51], off offset:144
	global_load_dwordx4 v[48:51], v[62:63], off
	v_cndmask_b32_e32 v57, v59, v61, vcc
	v_cndmask_b32_e32 v56, v58, v60, vcc
	v_lshl_add_u64 v[52:53], s[50:51], 0, v[56:57]
	v_lshl_add_u64 v[52:53], v[52:53], 0, v[98:99]
	s_waitcnt vmcnt(0)
	v_pk_add_f32 v[44:45], v[44:45], v[48:49]
	v_pk_add_f32 v[46:47], v[46:47], v[50:51]
	global_store_dwordx4 v[52:53], v[44:47], off
	global_load_dwordx4 v[44:47], v[62:63], off offset:16
	v_lshlrev_b64 v[48:49], 12, v[128:129]
	v_lshl_add_u64 v[48:49], s[24:25], 0, v[48:49]
	v_add_u32_e32 v128, 0xffffc070, v96
	s_waitcnt vmcnt(0)
	v_pk_add_f32 v[40:41], v[40:41], v[44:45]
	v_pk_add_f32 v[42:43], v[42:43], v[46:47]
	global_store_dwordx4 v[52:53], v[40:43], off offset:16
	global_load_dwordx4 v[40:43], v[62:63], off offset:128
	s_waitcnt vmcnt(0)
	v_pk_add_f32 v[36:37], v[36:37], v[40:41]
	v_pk_add_f32 v[38:39], v[38:39], v[42:43]
	global_store_dwordx4 v[52:53], v[36:39], off offset:128
	global_load_dwordx4 v[36:39], v[62:63], off offset:144
	v_mov_b32_e32 v41, v129
	v_or_b32_e32 v40, 0x60, v96
	v_lshlrev_b64 v[42:43], 12, v[40:41]
	v_ashrrev_i32_e32 v41, 31, v40
	v_lshlrev_b64 v[44:45], 12, v[40:41]
	v_lshl_add_u64 v[46:47], s[50:51], 0, v[44:45]
	v_cmp_gt_i32_e32 vcc, s30, v40
	s_waitcnt vmcnt(0)
	v_pk_add_f32 v[32:33], v[32:33], v[36:37]
	v_cndmask_b32_e32 v47, v49, v47, vcc
	v_cndmask_b32_e32 v46, v48, v46, vcc
	v_pk_add_f32 v[34:35], v[34:35], v[38:39]
	v_lshl_add_u64 v[46:47], v[46:47], 0, v[98:99]
	global_store_dwordx4 v[52:53], v[32:35], off offset:144
	global_load_dwordx4 v[32:35], v[46:47], off
	v_cndmask_b32_e32 v41, v43, v45, vcc
	v_cndmask_b32_e32 v40, v42, v44, vcc
	v_lshl_add_u64 v[36:37], s[50:51], 0, v[40:41]
	v_lshl_add_u64 v[36:37], v[36:37], 0, v[98:99]
	s_waitcnt vmcnt(0)
	v_pk_add_f32 v[28:29], v[28:29], v[32:33]
	v_pk_add_f32 v[30:31], v[30:31], v[34:35]
	global_store_dwordx4 v[36:37], v[28:31], off
	global_load_dwordx4 v[28:31], v[46:47], off offset:16
	v_lshlrev_b64 v[32:33], 12, v[128:129]
	v_lshl_add_u64 v[32:33], s[24:25], 0, v[32:33]
	s_waitcnt vmcnt(0)
	v_pk_add_f32 v[24:25], v[24:25], v[28:29]
	v_pk_add_f32 v[26:27], v[26:27], v[30:31]
	global_store_dwordx4 v[36:37], v[24:27], off offset:16
	global_load_dwordx4 v[24:27], v[46:47], off offset:128
	s_waitcnt vmcnt(0)
	v_pk_add_f32 v[20:21], v[20:21], v[24:25]
	v_pk_add_f32 v[22:23], v[22:23], v[26:27]
	global_store_dwordx4 v[36:37], v[20:23], off offset:128
	global_load_dwordx4 v[20:23], v[46:47], off offset:144
	v_mov_b32_e32 v25, v129
	v_or_b32_e32 v24, 0x70, v96
	v_lshlrev_b64 v[26:27], 12, v[24:25]
	v_ashrrev_i32_e32 v25, 31, v24
	v_lshlrev_b64 v[28:29], 12, v[24:25]
	v_lshl_add_u64 v[30:31], s[50:51], 0, v[28:29]
	v_cmp_gt_i32_e32 vcc, s30, v24
	s_waitcnt vmcnt(0)
	v_pk_add_f32 v[16:17], v[16:17], v[20:21]
	v_cndmask_b32_e32 v31, v33, v31, vcc
	v_cndmask_b32_e32 v30, v32, v30, vcc
	v_pk_add_f32 v[18:19], v[18:19], v[22:23]
	v_lshl_add_u64 v[30:31], v[30:31], 0, v[98:99]
	global_store_dwordx4 v[36:37], v[16:19], off offset:144
	global_load_dwordx4 v[16:19], v[30:31], off
	v_cndmask_b32_e32 v25, v27, v29, vcc
	v_cndmask_b32_e32 v24, v26, v28, vcc
	v_lshl_add_u64 v[20:21], s[50:51], 0, v[24:25]
	v_lshl_add_u64 v[20:21], v[20:21], 0, v[98:99]
	s_waitcnt vmcnt(0)
	v_pk_add_f32 v[12:13], v[12:13], v[16:17]
	v_pk_add_f32 v[14:15], v[14:15], v[18:19]
	global_store_dwordx4 v[20:21], v[12:15], off
	global_load_dwordx4 v[12:15], v[30:31], off offset:16
	s_waitcnt vmcnt(0)
	v_pk_add_f32 v[8:9], v[8:9], v[12:13]
	v_pk_add_f32 v[10:11], v[10:11], v[14:15]
	global_store_dwordx4 v[20:21], v[8:11], off offset:16
	global_load_dwordx4 v[8:11], v[30:31], off offset:128
	s_waitcnt vmcnt(0)
	v_pk_add_f32 v[4:5], v[4:5], v[8:9]
	v_pk_add_f32 v[6:7], v[6:7], v[10:11]
	global_store_dwordx4 v[20:21], v[4:7], off offset:128
	global_load_dwordx4 v[4:7], v[30:31], off offset:144
	s_waitcnt vmcnt(0)
	v_pk_add_f32 v[0:1], v[0:1], v[4:5]
	v_pk_add_f32 v[2:3], v[2:3], v[6:7]
	global_store_dwordx4 v[20:21], v[0:3], off offset:144
	s_cbranch_scc0 .LBB0_2562
